# fastdiv: rcp hoisted above independent neighbours instead of padding with s_nop
# speedup vs baseline: 1.0782x; 1.0014x over previous
; DI unsigned pk2(float lo, float hi) { f32x2 v = {lo, hi}; bf16x2_t b = __builtin_convertvector(v, bf16x2_t); return __builtin_bit_cast(unsigned, b); }
; DI float siluf_(float x) { return x / (1.f + __expf(-x)); }
; #define EPI_ROWS(...) _Pragma("unroll") for (int ai = 0; ai < 2; ++ai) _Pragma("unroll") for (int m = 0; m < 4; ++m) { const int row = u.pm * 256 + ai * 128 + wr * 64 + m * 16 + fr; __VA_ARGS__ }
; DI void st16_wt(void* p, u32x4 v) { asm volatile("global_store_dwordx4 %0, %1, off sc0 sc1\n\ts_nop 1" :: "v"(p), "v"(v) : "memory"); }
; DI u32x4 pack8(f32x4 a, f32x4 b) { u32x4 w; w.x = pk2(a[0], a[1]); w.y = pk2(a[2], a[3]); w.z = pk2(b[0], b[1]); w.w = pk2(b[2], b[3]); return w; }
;     DI void operator()(const Acc& acc, const Unit& u, int wr, int wc, int fr, int fq) const {
;         const int c0 = u.pn * 128 + wc * 32 + 8 * fq;
;         EPI_ROWS( f32x4 a, b;
;             _Pragma("unroll") for (int e = 0; e < 4; ++e) { a[e] = siluf_(acc[ai][0][m][0][e]) * acc[ai][1][m][0][e]; b[e] = siluf_(acc[ai][0][m][1][e]) * acc[ai][1][m][1][e]; }
;             st16_wt(H + (size_t)row * DFF + c0, pack8(a, b)); )
;     }
.LBB0_380:
	v_mov_b32_e32 v150, v144
	v_mov_b32_e32 v151, v145
	s_lshl_b32 s15, s51, 7
	s_or_b32 s15, s15, s41
	v_lshl_add_u32 v152, v151, 3, s15
	v_mul_f32_e32 v151, 0xbfb8aa3b, v124
	v_exp_f32_e32 v154, v151
	v_mul_f32_e32 v151, 0xbfb8aa3b, v125
	v_exp_f32_e32 v155, v151
	v_mul_f32_e32 v156, 0xbfb8aa3b, v116
	v_exp_f32_e32 v156, v156
	s_lshl_b32 s15, s22, 8
	v_pk_add_f32 v[154:155], v[154:155], 1.0 op_sel_hi:[1,0]
	s_add_i32 s15, s15, s40
	v_rcp_f32_e32 v151, v155
	v_add_u32_e32 v150, s15, v150
	v_ashrrev_i32_e32 v153, 31, v152
	v_mul_f32_e32 v157, 0xbfb8aa3b, v117
	v_mul_f32_e32 v125, v125, v151
	v_rcp_f32_e32 v151, v154
	v_exp_f32_e32 v157, v157
	s_nop 0
	v_pk_add_f32 v[156:157], v[156:157], 1.0 op_sel_hi:[1,0]
	v_mul_f32_e32 v124, v124, v151
	v_pk_mul_f32 v[120:121], v[124:125], v[120:121]
	v_rcp_f32_e32 v124, v157
	s_nop 0
	v_mul_f32_e32 v117, v117, v124
	v_mul_f32_e32 v124, 0xbfb8aa3b, v126
	v_rcp_f32_e32 v151, v156
	v_mul_f32_e32 v125, 0xbfb8aa3b, v127
	v_exp_f32_e32 v124, v124
	v_exp_f32_e32 v125, v125
	v_mul_f32_e32 v116, v116, v151
	v_pk_mul_f32 v[154:155], v[116:117], v[112:113]
	v_pk_add_f32 v[124:125], v[124:125], 1.0 op_sel_hi:[1,0]
	s_nop 0
	v_rcp_f32_e32 v113, v125
	v_mul_f32_e32 v112, 0xbfb8aa3b, v118
	v_exp_f32_e32 v112, v112
	v_mul_f32_e32 v117, v127, v113
	v_rcp_f32_e32 v116, v124
	v_mul_f32_e32 v113, 0xbfb8aa3b, v119
	v_exp_f32_e32 v113, v113
	s_nop 0
	v_pk_add_f32 v[112:113], v[112:113], 1.0 op_sel_hi:[1,0]
	v_mul_f32_e32 v116, v126, v116
	v_pk_mul_f32 v[122:123], v[116:117], v[122:123]
	v_rcp_f32_e32 v116, v113
	s_nop 0
	v_mul_f32_e32 v113, v119, v116
	v_rcp_f32_e32 v116, v112
	s_nop 0
	v_mul_f32_e32 v112, v118, v116
	v_pk_mul_f32 v[124:125], v[112:113], v[114:115]
	v_mov_b64_e32 v[112:113], s[8:9]
	v_mad_i64_i32 v[116:117], s[24:25], v150, s50, v[112:113]
	v_lshlrev_b64 v[114:115], 1, v[152:153]
	v_lshl_add_u64 v[126:127], v[116:117], 0, v[114:115]
	v_mul_f32_e32 v117, 0xbfb8aa3b, v108
	v_cvt_pk_bf16_f32 v116, v120, v121
	v_exp_f32_e32 v120, v117
	v_mul_f32_e32 v117, 0xbfb8aa3b, v109
	v_exp_f32_e32 v121, v117
	v_cvt_pk_bf16_f32 v117, v122, v123
	v_cvt_pk_bf16_f32 v118, v154, v155
	v_cvt_pk_bf16_f32 v119, v124, v125
	v_pk_add_f32 v[120:121], v[120:121], 1.0 op_sel_hi:[1,0]
	global_store_dwordx4 v[126:127], v[116:119], off sc0 sc1
	s_nop 1
	v_rcp_f32_e32 v117, v121
	v_mul_f32_e32 v116, 0xbfb8aa3b, v100
	v_exp_f32_e32 v116, v116
	v_mul_f32_e32 v109, v109, v117
	v_rcp_f32_e32 v118, v120
	v_mul_f32_e32 v117, 0xbfb8aa3b, v101
	v_exp_f32_e32 v117, v117
	s_nop 0
	v_pk_add_f32 v[116:117], v[116:117], 1.0 op_sel_hi:[1,0]
	v_mul_f32_e32 v108, v108, v118
	v_pk_mul_f32 v[104:105], v[108:109], v[104:105]
	v_rcp_f32_e32 v108, v117
	s_nop 0
	v_mul_f32_e32 v101, v101, v108
	v_mul_f32_e32 v108, 0xbfb8aa3b, v110
	v_rcp_f32_e32 v117, v116
	v_mul_f32_e32 v109, 0xbfb8aa3b, v111
	v_exp_f32_e32 v108, v108
	v_exp_f32_e32 v109, v109
	v_mul_f32_e32 v100, v100, v117
	v_pk_mul_f32 v[100:101], v[100:101], v[96:97]
	v_pk_add_f32 v[108:109], v[108:109], 1.0 op_sel_hi:[1,0]
	s_nop 0
	v_rcp_f32_e32 v97, v109
	v_mul_f32_e32 v96, 0xbfb8aa3b, v102
	v_exp_f32_e32 v96, v96
	v_mul_f32_e32 v109, v111, v97
	v_rcp_f32_e32 v111, v108
	v_mul_f32_e32 v97, 0xbfb8aa3b, v103
	v_exp_f32_e32 v97, v97
	s_nop 0
	v_pk_add_f32 v[96:97], v[96:97], 1.0 op_sel_hi:[1,0]
	v_mul_f32_e32 v108, v110, v111
	v_pk_mul_f32 v[106:107], v[108:109], v[106:107]
	v_rcp_f32_e32 v108, v97
	s_nop 0
	v_mul_f32_e32 v97, v103, v108
	v_rcp_f32_e32 v103, v96
	s_nop 0
	v_mul_f32_e32 v96, v102, v103
	v_pk_mul_f32 v[102:103], v[96:97], v[98:99]
	v_add_u32_e32 v96, 16, v150
	v_mad_i64_i32 v[96:97], s[24:25], v96, s50, v[112:113]
	v_lshl_add_u64 v[108:109], v[96:97], 0, v[114:115]
	v_mul_f32_e32 v97, 0xbfb8aa3b, v92
	v_cvt_pk_bf16_f32 v96, v104, v105
	v_exp_f32_e32 v104, v97
	v_mul_f32_e32 v97, 0xbfb8aa3b, v93
	v_exp_f32_e32 v105, v97
	v_cvt_pk_bf16_f32 v98, v100, v101
	v_cvt_pk_bf16_f32 v99, v102, v103
	v_cvt_pk_bf16_f32 v97, v106, v107
	v_pk_add_f32 v[100:101], v[104:105], 1.0 op_sel_hi:[1,0]
	global_store_dwordx4 v[108:109], v[96:99], off sc0 sc1
	s_nop 1
	v_rcp_f32_e32 v97, v101
	v_mul_f32_e32 v96, 0xbfb8aa3b, v84
	v_exp_f32_e32 v96, v96
	v_mul_f32_e32 v93, v93, v97
	v_rcp_f32_e32 v98, v100
	v_mul_f32_e32 v97, 0xbfb8aa3b, v85
	v_exp_f32_e32 v97, v97
	s_nop 0
	v_pk_add_f32 v[96:97], v[96:97], 1.0 op_sel_hi:[1,0]
	v_mul_f32_e32 v92, v92, v98
	v_pk_mul_f32 v[88:89], v[92:93], v[88:89]
	v_rcp_f32_e32 v92, v97
	s_nop 0
	v_mul_f32_e32 v85, v85, v92
	v_mul_f32_e32 v92, 0xbfb8aa3b, v94
	v_rcp_f32_e32 v97, v96
	v_mul_f32_e32 v93, 0xbfb8aa3b, v95
	v_exp_f32_e32 v92, v92
	v_exp_f32_e32 v93, v93
	v_mul_f32_e32 v84, v84, v97
	v_pk_mul_f32 v[84:85], v[84:85], v[80:81]
	v_pk_add_f32 v[92:93], v[92:93], 1.0 op_sel_hi:[1,0]
	s_nop 0
	v_rcp_f32_e32 v81, v93
	v_mul_f32_e32 v80, 0xbfb8aa3b, v86
	v_exp_f32_e32 v80, v80
	v_mul_f32_e32 v93, v95, v81
	v_rcp_f32_e32 v95, v92
	v_mul_f32_e32 v81, 0xbfb8aa3b, v87
	v_exp_f32_e32 v81, v81
	s_nop 0
	v_pk_add_f32 v[80:81], v[80:81], 1.0 op_sel_hi:[1,0]
	v_mul_f32_e32 v92, v94, v95
	v_pk_mul_f32 v[90:91], v[92:93], v[90:91]
	v_rcp_f32_e32 v92, v81
	s_nop 0
	v_mul_f32_e32 v81, v87, v92
	v_rcp_f32_e32 v87, v80
	s_nop 0
	v_mul_f32_e32 v80, v86, v87
	v_pk_mul_f32 v[86:87], v[80:81], v[82:83]
	v_add_u32_e32 v80, 32, v150
	v_mad_i64_i32 v[80:81], s[24:25], v80, s50, v[112:113]
	v_lshl_add_u64 v[92:93], v[80:81], 0, v[114:115]
	v_mul_f32_e32 v81, 0xbfb8aa3b, v76
	v_cvt_pk_bf16_f32 v80, v88, v89
	v_exp_f32_e32 v88, v81
	v_mul_f32_e32 v81, 0xbfb8aa3b, v77
	v_exp_f32_e32 v89, v81
	v_cvt_pk_bf16_f32 v82, v84, v85
	v_cvt_pk_bf16_f32 v83, v86, v87
	v_cvt_pk_bf16_f32 v81, v90, v91
; DI unsigned pk2(float lo, float hi) { f32x2 v = {lo, hi}; bf16x2_t b = __builtin_convertvector(v, bf16x2_t); return __builtin_bit_cast(unsigned, b); }
; DI float siluf_(float x) { return x / (1.f + __expf(-x)); }
; #define EPI_ROWS(...) _Pragma("unroll") for (int ai = 0; ai < 2; ++ai) _Pragma("unroll") for (int m = 0; m < 4; ++m) { const int row = u.pm * 256 + ai * 128 + wr * 64 + m * 16 + fr; __VA_ARGS__ }
; DI void st16_wt(void* p, u32x4 v) { asm volatile("global_store_dwordx4 %0, %1, off sc0 sc1\n\ts_nop 1" :: "v"(p), "v"(v) : "memory"); }
; DI u32x4 pack8(f32x4 a, f32x4 b) { u32x4 w; w.x = pk2(a[0], a[1]); w.y = pk2(a[2], a[3]); w.z = pk2(b[0], b[1]); w.w = pk2(b[2], b[3]); return w; }
;     DI void operator()(const Acc& acc, const Unit& u, int wr, int wc, int fr, int fq) const {
;         const int c0 = u.pn * 128 + wc * 32 + 8 * fq;
;         EPI_ROWS( f32x4 a, b;
;             _Pragma("unroll") for (int e = 0; e < 4; ++e) { a[e] = siluf_(acc[ai][0][m][0][e]) * acc[ai][1][m][0][e]; b[e] = siluf_(acc[ai][0][m][1][e]) * acc[ai][1][m][1][e]; }
;             st16_wt(H + (size_t)row * DFF + c0, pack8(a, b)); )
;     }
	v_pk_add_f32 v[84:85], v[88:89], 1.0 op_sel_hi:[1,0]
	global_store_dwordx4 v[92:93], v[80:83], off sc0 sc1
	s_nop 1
	v_rcp_f32_e32 v81, v85
	v_mul_f32_e32 v80, 0xbfb8aa3b, v68
	v_exp_f32_e32 v80, v80
	v_mul_f32_e32 v77, v77, v81
	v_rcp_f32_e32 v82, v84
	v_mul_f32_e32 v81, 0xbfb8aa3b, v69
	v_exp_f32_e32 v81, v81
	s_nop 0
	v_pk_add_f32 v[80:81], v[80:81], 1.0 op_sel_hi:[1,0]
	v_mul_f32_e32 v76, v76, v82
	v_pk_mul_f32 v[72:73], v[76:77], v[72:73]
	v_rcp_f32_e32 v76, v81
	s_nop 0
	v_mul_f32_e32 v69, v69, v76
	v_mul_f32_e32 v76, 0xbfb8aa3b, v78
	v_rcp_f32_e32 v81, v80
	v_mul_f32_e32 v77, 0xbfb8aa3b, v79
	v_exp_f32_e32 v76, v76
	v_exp_f32_e32 v77, v77
	v_mul_f32_e32 v68, v68, v81
	v_pk_mul_f32 v[68:69], v[68:69], v[64:65]
	v_pk_add_f32 v[76:77], v[76:77], 1.0 op_sel_hi:[1,0]
	s_nop 0
	v_rcp_f32_e32 v65, v77
	v_mul_f32_e32 v64, 0xbfb8aa3b, v70
	v_exp_f32_e32 v64, v64
	v_mul_f32_e32 v77, v79, v65
	v_rcp_f32_e32 v79, v76
	v_mul_f32_e32 v65, 0xbfb8aa3b, v71
	v_exp_f32_e32 v65, v65
	s_nop 0
	v_pk_add_f32 v[64:65], v[64:65], 1.0 op_sel_hi:[1,0]
	v_mul_f32_e32 v76, v78, v79
	v_pk_mul_f32 v[74:75], v[76:77], v[74:75]
	v_rcp_f32_e32 v76, v65
	s_nop 0
	v_mul_f32_e32 v65, v71, v76
	v_rcp_f32_e32 v71, v64
	s_nop 0
	v_mul_f32_e32 v64, v70, v71
	v_pk_mul_f32 v[70:71], v[64:65], v[66:67]
	v_add_u32_e32 v64, 48, v150
	v_mad_i64_i32 v[64:65], s[24:25], v64, s50, v[112:113]
	v_mul_f32_e32 v66, 0xbfb8aa3b, v60
	v_lshl_add_u64 v[76:77], v[64:65], 0, v[114:115]
	v_cvt_pk_bf16_f32 v64, v72, v73
	v_exp_f32_e32 v72, v66
	v_mul_f32_e32 v66, 0xbfb8aa3b, v61
	v_exp_f32_e32 v73, v66
	v_cvt_pk_bf16_f32 v65, v74, v75
	v_cvt_pk_bf16_f32 v66, v68, v69
	v_cvt_pk_bf16_f32 v67, v70, v71
	global_store_dwordx4 v[76:77], v[64:67], off sc0 sc1
	s_nop 1
	v_pk_add_f32 v[64:65], v[72:73], 1.0 op_sel_hi:[1,0]
	s_nop 0
	v_rcp_f32_e32 v67, v65
	v_mul_f32_e32 v66, 0xbfb8aa3b, v52
	v_exp_f32_e32 v66, v66
	v_add_u32_e32 v69, 0x80, v150
	v_mul_f32_e32 v61, v61, v67
	v_rcp_f32_e32 v65, v64
	v_mul_f32_e32 v67, 0xbfb8aa3b, v53
	v_exp_f32_e32 v67, v67
	s_nop 0
	v_pk_add_f32 v[66:67], v[66:67], 1.0 op_sel_hi:[1,0]
	v_mul_f32_e32 v60, v60, v65
	v_pk_mul_f32 v[56:57], v[60:61], v[56:57]
	v_rcp_f32_e32 v60, v67
	s_nop 0
	v_mul_f32_e32 v53, v53, v60
	v_mul_f32_e32 v60, 0xbfb8aa3b, v62
	v_rcp_f32_e32 v64, v66
	v_mul_f32_e32 v61, 0xbfb8aa3b, v63
	v_exp_f32_e32 v60, v60
	v_exp_f32_e32 v61, v61
	v_mul_f32_e32 v52, v52, v64
	v_pk_mul_f32 v[52:53], v[52:53], v[48:49]
	v_pk_add_f32 v[60:61], v[60:61], 1.0 op_sel_hi:[1,0]
	s_nop 0
	v_rcp_f32_e32 v49, v61
	v_mul_f32_e32 v48, 0xbfb8aa3b, v54
	v_exp_f32_e32 v48, v48
	v_mul_f32_e32 v61, v63, v49
	v_rcp_f32_e32 v63, v60
	v_mul_f32_e32 v49, 0xbfb8aa3b, v55
	v_exp_f32_e32 v49, v49
	s_nop 0
	v_pk_add_f32 v[48:49], v[48:49], 1.0 op_sel_hi:[1,0]
	v_mul_f32_e32 v60, v62, v63
	v_pk_mul_f32 v[58:59], v[60:61], v[58:59]
	v_rcp_f32_e32 v60, v49
	s_nop 0
	v_mul_f32_e32 v49, v55, v60
	v_rcp_f32_e32 v55, v48
	s_nop 0
	v_mul_f32_e32 v48, v54, v55
	v_pk_mul_f32 v[54:55], v[48:49], v[50:51]
	v_mad_i64_i32 v[48:49], s[24:25], v69, s50, v[112:113]
	v_lshl_add_u64 v[60:61], v[48:49], 0, v[114:115]
	v_mul_f32_e32 v49, 0xbfb8aa3b, v44
	v_cvt_pk_bf16_f32 v48, v56, v57
	v_exp_f32_e32 v56, v49
	v_mul_f32_e32 v49, 0xbfb8aa3b, v45
	v_exp_f32_e32 v57, v49
	v_cvt_pk_bf16_f32 v50, v52, v53
	v_cvt_pk_bf16_f32 v51, v54, v55
	v_cvt_pk_bf16_f32 v49, v58, v59
	v_pk_add_f32 v[52:53], v[56:57], 1.0 op_sel_hi:[1,0]
	global_store_dwordx4 v[60:61], v[48:51], off sc0 sc1
	s_nop 1
	v_rcp_f32_e32 v49, v53
	v_mul_f32_e32 v48, 0xbfb8aa3b, v36
	v_exp_f32_e32 v48, v48
	v_mul_f32_e32 v45, v45, v49
	v_rcp_f32_e32 v50, v52
	v_mul_f32_e32 v49, 0xbfb8aa3b, v37
	v_exp_f32_e32 v49, v49
	s_nop 0
	v_pk_add_f32 v[48:49], v[48:49], 1.0 op_sel_hi:[1,0]
	v_mul_f32_e32 v44, v44, v50
	v_pk_mul_f32 v[40:41], v[44:45], v[40:41]
	v_rcp_f32_e32 v44, v49
	s_nop 0
	v_mul_f32_e32 v37, v37, v44
	v_mul_f32_e32 v44, 0xbfb8aa3b, v46
	v_rcp_f32_e32 v49, v48
	v_mul_f32_e32 v45, 0xbfb8aa3b, v47
	v_exp_f32_e32 v44, v44
	v_exp_f32_e32 v45, v45
	v_mul_f32_e32 v36, v36, v49
	v_pk_mul_f32 v[36:37], v[36:37], v[32:33]
	v_pk_add_f32 v[44:45], v[44:45], 1.0 op_sel_hi:[1,0]
	s_nop 0
	v_rcp_f32_e32 v33, v45
	v_mul_f32_e32 v32, 0xbfb8aa3b, v38
; DI unsigned pk2(float lo, float hi) { f32x2 v = {lo, hi}; bf16x2_t b = __builtin_convertvector(v, bf16x2_t); return __builtin_bit_cast(unsigned, b); }
; DI float siluf_(float x) { return x / (1.f + __expf(-x)); }
; #define EPI_ROWS(...) _Pragma("unroll") for (int ai = 0; ai < 2; ++ai) _Pragma("unroll") for (int m = 0; m < 4; ++m) { const int row = u.pm * 256 + ai * 128 + wr * 64 + m * 16 + fr; __VA_ARGS__ }
; DI void st16_wt(void* p, u32x4 v) { asm volatile("global_store_dwordx4 %0, %1, off sc0 sc1\n\ts_nop 1" :: "v"(p), "v"(v) : "memory"); }
; DI u32x4 pack8(f32x4 a, f32x4 b) { u32x4 w; w.x = pk2(a[0], a[1]); w.y = pk2(a[2], a[3]); w.z = pk2(b[0], b[1]); w.w = pk2(b[2], b[3]); return w; }
;     DI void operator()(const Acc& acc, const Unit& u, int wr, int wc, int fr, int fq) const {
;         const int c0 = u.pn * 128 + wc * 32 + 8 * fq;
;         EPI_ROWS( f32x4 a, b;
;             _Pragma("unroll") for (int e = 0; e < 4; ++e) { a[e] = siluf_(acc[ai][0][m][0][e]) * acc[ai][1][m][0][e]; b[e] = siluf_(acc[ai][0][m][1][e]) * acc[ai][1][m][1][e]; }
;             st16_wt(H + (size_t)row * DFF + c0, pack8(a, b)); )
;     }
	v_exp_f32_e32 v32, v32
	v_mul_f32_e32 v45, v47, v33
	v_rcp_f32_e32 v47, v44
	v_mul_f32_e32 v33, 0xbfb8aa3b, v39
	v_exp_f32_e32 v33, v33
	s_nop 0
	v_pk_add_f32 v[32:33], v[32:33], 1.0 op_sel_hi:[1,0]
	v_mul_f32_e32 v44, v46, v47
	v_pk_mul_f32 v[42:43], v[44:45], v[42:43]
	v_rcp_f32_e32 v44, v33
	s_nop 0
	v_mul_f32_e32 v33, v39, v44
	v_rcp_f32_e32 v39, v32
	s_nop 0
	v_mul_f32_e32 v32, v38, v39
	v_pk_mul_f32 v[38:39], v[32:33], v[34:35]
	v_add_u32_e32 v32, 0x90, v150
	v_mad_i64_i32 v[32:33], s[24:25], v32, s50, v[112:113]
	v_lshl_add_u64 v[44:45], v[32:33], 0, v[114:115]
	v_mul_f32_e32 v33, 0xbfb8aa3b, v28
	v_cvt_pk_bf16_f32 v32, v40, v41
	v_exp_f32_e32 v40, v33
	v_mul_f32_e32 v33, 0xbfb8aa3b, v29
	v_exp_f32_e32 v41, v33
	v_cvt_pk_bf16_f32 v34, v36, v37
	v_cvt_pk_bf16_f32 v35, v38, v39
	v_cvt_pk_bf16_f32 v33, v42, v43
	v_pk_add_f32 v[36:37], v[40:41], 1.0 op_sel_hi:[1,0]
	global_store_dwordx4 v[44:45], v[32:35], off sc0 sc1
	s_nop 1
	v_rcp_f32_e32 v33, v37
	v_mul_f32_e32 v32, 0xbfb8aa3b, v20
	v_exp_f32_e32 v32, v32
	v_mul_f32_e32 v29, v29, v33
	v_rcp_f32_e32 v34, v36
	v_mul_f32_e32 v33, 0xbfb8aa3b, v21
	v_exp_f32_e32 v33, v33
	s_nop 0
	v_pk_add_f32 v[32:33], v[32:33], 1.0 op_sel_hi:[1,0]
	v_mul_f32_e32 v28, v28, v34
	v_pk_mul_f32 v[24:25], v[28:29], v[24:25]
	v_rcp_f32_e32 v28, v33
	s_nop 0
	v_mul_f32_e32 v21, v21, v28
	v_mul_f32_e32 v28, 0xbfb8aa3b, v30
	v_rcp_f32_e32 v33, v32
	v_mul_f32_e32 v29, 0xbfb8aa3b, v31
	v_exp_f32_e32 v28, v28
	v_exp_f32_e32 v29, v29
	v_mul_f32_e32 v20, v20, v33
	v_pk_mul_f32 v[20:21], v[20:21], v[16:17]
	v_pk_add_f32 v[28:29], v[28:29], 1.0 op_sel_hi:[1,0]
	s_nop 0
	v_rcp_f32_e32 v17, v29
	v_mul_f32_e32 v16, 0xbfb8aa3b, v22
	v_exp_f32_e32 v16, v16
	v_mul_f32_e32 v29, v31, v17
	v_rcp_f32_e32 v31, v28
	v_mul_f32_e32 v17, 0xbfb8aa3b, v23
	v_exp_f32_e32 v17, v17
	s_nop 0
	v_pk_add_f32 v[16:17], v[16:17], 1.0 op_sel_hi:[1,0]
	v_mul_f32_e32 v28, v30, v31
	v_pk_mul_f32 v[26:27], v[28:29], v[26:27]
	v_rcp_f32_e32 v28, v17
	s_nop 0
	v_mul_f32_e32 v17, v23, v28
	v_rcp_f32_e32 v23, v16
	s_nop 0
	v_mul_f32_e32 v16, v22, v23
	v_pk_mul_f32 v[22:23], v[16:17], v[18:19]
	v_add_u32_e32 v16, 0xa0, v150
	v_mad_i64_i32 v[16:17], s[24:25], v16, s50, v[112:113]
	v_lshl_add_u64 v[28:29], v[16:17], 0, v[114:115]
	v_mul_f32_e32 v17, 0xbfb8aa3b, v12
	v_cvt_pk_bf16_f32 v16, v24, v25
	v_exp_f32_e32 v24, v17
	v_mul_f32_e32 v17, 0xbfb8aa3b, v13
	v_exp_f32_e32 v25, v17
	v_cvt_pk_bf16_f32 v18, v20, v21
	v_cvt_pk_bf16_f32 v19, v22, v23
	v_cvt_pk_bf16_f32 v17, v26, v27
	v_pk_add_f32 v[20:21], v[24:25], 1.0 op_sel_hi:[1,0]
	global_store_dwordx4 v[28:29], v[16:19], off sc0 sc1
	s_nop 1
	v_rcp_f32_e32 v17, v21
	v_mul_f32_e32 v16, 0xbfb8aa3b, v4
	v_exp_f32_e32 v16, v16
	v_mul_f32_e32 v13, v13, v17
	v_rcp_f32_e32 v18, v20
	v_mul_f32_e32 v17, 0xbfb8aa3b, v5
	v_exp_f32_e32 v17, v17
	s_nop 0
	v_pk_add_f32 v[16:17], v[16:17], 1.0 op_sel_hi:[1,0]
	v_mul_f32_e32 v12, v12, v18
	v_pk_mul_f32 v[8:9], v[12:13], v[8:9]
	v_rcp_f32_e32 v12, v17
	s_nop 0
	v_mul_f32_e32 v5, v5, v12
	v_mul_f32_e32 v12, 0xbfb8aa3b, v14
	v_rcp_f32_e32 v17, v16
	v_mul_f32_e32 v13, 0xbfb8aa3b, v15
	v_exp_f32_e32 v12, v12
	v_exp_f32_e32 v13, v13
	v_mul_f32_e32 v4, v4, v17
	v_pk_mul_f32 v[4:5], v[4:5], v[0:1]
	v_pk_add_f32 v[12:13], v[12:13], 1.0 op_sel_hi:[1,0]
	s_nop 0
	v_rcp_f32_e32 v1, v13
	v_mul_f32_e32 v0, 0xbfb8aa3b, v6
	v_exp_f32_e32 v0, v0
	v_mul_f32_e32 v13, v15, v1
	v_rcp_f32_e32 v15, v12
	v_mul_f32_e32 v1, 0xbfb8aa3b, v7
	v_exp_f32_e32 v1, v1
	s_nop 0
	v_pk_add_f32 v[0:1], v[0:1], 1.0 op_sel_hi:[1,0]
	v_mul_f32_e32 v12, v14, v15
	v_pk_mul_f32 v[10:11], v[12:13], v[10:11]
	v_rcp_f32_e32 v12, v1
	s_nop 0
	v_mul_f32_e32 v1, v7, v12
	v_rcp_f32_e32 v7, v0
	s_nop 0
	v_mul_f32_e32 v0, v6, v7
	v_pk_mul_f32 v[6:7], v[0:1], v[2:3]
	v_add_u32_e32 v0, 0xb0, v150
	v_mad_i64_i32 v[0:1], s[24:25], v0, s50, v[112:113]
	v_lshl_add_u64 v[12:13], v[0:1], 0, v[114:115]
	v_cvt_pk_bf16_f32 v0, v8, v9
	v_cvt_pk_bf16_f32 v1, v10, v11
	v_cvt_pk_bf16_f32 v2, v4, v5
	v_cvt_pk_bf16_f32 v3, v6, v7
	global_store_dwordx4 v[12:13], v[0:3], off sc0 sc1
	s_nop 1
	s_andn2_b64 vcc, exec, s[2:3]
	s_mov_b64 s[2:3], -1
	s_cbranch_vccnz .LBB0_373
	s_andn2_b64 vcc, exec, s[6:7]
	s_cbranch_vccnz .LBB0_372
	s_barrier
	s_branch .LBB0_372

; DI unsigned pk2(float lo, float hi) { f32x2 v = {lo, hi}; bf16x2_t b = __builtin_convertvector(v, bf16x2_t); return __builtin_bit_cast(unsigned, b); }
; DI float bflo(unsigned u) { return __uint_as_float(u << 16); }
; DI float bfhi(unsigned u) { return __uint_as_float(u & 0xffff0000u); }
; DI float siluf_(float x) { return x / (1.f + __expf(-x)); }
; DI void conv_phase(int wv, const Params& P) {
;     ...
;         float x[11][8];
; #pragma unroll
;         for (int i = 0; i < 11; ++i) { u32x4 q = (u32x4){0u, 0u, 0u, 0u}; if (i >= 3 || t0 != 0) q = *(const u32x4*)(XBC + (size_t)(r0 + i - 3) * 1536 + c0);
; #pragma unroll
;             for (int e = 0; e < 4; ++e) { x[i][2 * e] = bflo(q[e]); x[i][2 * e + 1] = bfhi(q[e]); } }
;         unsigned o[8][4];
; #pragma unroll
;         for (int i = 0; i < 8; ++i) { float y[8];
; #pragma unroll
;             for (int e = 0; e < 8; ++e) { float s = bias[e];
; #pragma unroll
;                 for (int k = 0; k < 4; ++k) s += w[k][e] * x[i + k][e];
;                 y[e] = siluf_(s); }
; #pragma unroll
;             for (int e = 0; e < 4; ++e) o[i][e] = pk2(y[2 * e], y[2 * e + 1]); }
.LBB0_1310:
	s_or_b64 exec, exec, s[26:27]
	v_mad_i64_i32 v[4:5], s[26:27], v94, s40, v[8:9]
	flat_load_dwordx4 v[4:7], v[4:5]
	v_or_b32_e32 v102, 4, v94
	v_mad_i64_i32 v[12:13], s[26:27], v102, s40, v[8:9]
	v_or_b32_e32 v98, 5, v94
	v_or_b32_e32 v100, 6, v94
	v_or_b32_e32 v106, 2, v94
	v_or_b32_e32 v104, 3, v94
	v_mad_i64_i32 v[14:15], s[26:27], v98, s40, v[8:9]
	flat_load_dwordx4 v[50:53], v[12:13]
	flat_load_dwordx4 v[16:19], v[14:15]
	v_mad_i64_i32 v[12:13], s[26:27], v100, s40, v[8:9]
	v_or_b32_e32 v96, 7, v94
	v_or_b32_e32 v108, 1, v94
	v_mad_i64_i32 v[10:11], s[26:27], v106, s40, v[8:9]
	v_mad_i64_i32 v[20:21], s[26:27], v104, s40, v[8:9]
	flat_load_dwordx4 v[46:49], v[12:13]
	v_mad_i64_i32 v[12:13], s[26:27], v96, s40, v[8:9]
	v_mad_i64_i32 v[8:9], s[26:27], v108, s40, v[8:9]
	flat_load_dwordx4 v[54:57], v[12:13]
	s_nop 0
	flat_load_dwordx4 v[12:15], v[10:11]
	s_nop 0
	flat_load_dwordx4 v[20:23], v[20:21]
	s_waitcnt vmcnt(0) lgkmcnt(0)
	v_lshlrev_b32_e32 v36, 16, v78
	flat_load_dwordx4 v[8:11], v[8:9]
	v_and_b32_e32 v37, 0xffff0000, v78
	v_lshlrev_b32_e32 v126, 16, v82
	v_and_b32_e32 v127, 0xffff0000, v82
	v_pk_fma_f32 v[36:37], v[58:59], v[36:37], v[74:75]
	v_lshlrev_b32_e32 v128, 16, v0
	v_and_b32_e32 v129, 0xffff0000, v0
	v_pk_fma_f32 v[36:37], v[62:63], v[126:127], v[36:37]
	v_pk_fma_f32 v[126:127], v[58:59], v[126:127], v[74:75]
	v_pk_fma_f32 v[122:123], v[66:67], v[128:129], v[36:37]
	v_pk_fma_f32 v[126:127], v[62:63], v[128:129], v[126:127]
	v_pk_fma_f32 v[148:149], v[58:59], v[128:129], v[74:75]
	v_lshlrev_b32_e32 v114, 16, v79
	v_and_b32_e32 v115, 0xffff0000, v79
	v_mad_u64_u32 v[78:79], s[26:27], v89, s42, v[86:87]
	v_lshlrev_b32_e32 v112, 16, v83
	v_and_b32_e32 v113, 0xffff0000, v83
	v_pk_fma_f32 v[114:115], v[60:61], v[114:115], v[76:77]
	v_lshlrev_b32_e32 v110, 16, v84
	v_pk_fma_f32 v[114:115], v[64:65], v[112:113], v[114:115]
	v_pk_fma_f32 v[112:113], v[60:61], v[112:113], v[76:77]
	v_and_b32_e32 v111, 0xffff0000, v84
	v_lshlrev_b32_e32 v82, 16, v85
	v_and_b32_e32 v83, 0xffff0000, v85
	v_lshlrev_b32_e32 v84, 16, v80
	v_and_b32_e32 v85, 0xffff0000, v80
	v_pk_fma_f32 v[84:85], v[24:25], v[84:85], v[42:43]
	v_lshlrev_b32_e32 v80, 16, v81
	v_pk_fma_f32 v[84:85], v[28:29], v[110:111], v[84:85]
	v_pk_fma_f32 v[110:111], v[24:25], v[110:111], v[42:43]
	v_and_b32_e32 v81, 0xffff0000, v81
	v_ashrrev_i32_e32 v95, 31, v94
	v_ashrrev_i32_e32 v109, 31, v108
	v_ashrrev_i32_e32 v107, 31, v106
	v_ashrrev_i32_e32 v105, 31, v104
	v_ashrrev_i32_e32 v103, 31, v102
	v_ashrrev_i32_e32 v99, 31, v98
	v_ashrrev_i32_e32 v101, 31, v100
	v_ashrrev_i32_e32 v97, 31, v96
	v_lshlrev_b32_e32 v130, 16, v4
	v_and_b32_e32 v131, 0xffff0000, v4
	v_pk_fma_f32 v[138:139], v[70:71], v[130:131], v[122:123]
	v_pk_fma_f32 v[126:127], v[66:67], v[130:131], v[126:127]
	v_mul_f32_e32 v0, 0xbfb8aa3b, v138
	v_mul_f32_e32 v4, 0xbfb8aa3b, v139
	v_exp_f32_e32 v142, v0
	v_exp_f32_e32 v143, v4
	v_pk_fma_f32 v[146:147], v[58:59], v[130:131], v[74:75]
	v_pk_fma_f32 v[130:131], v[62:63], v[130:131], v[148:149]
	v_lshlrev_b32_e32 v116, 16, v16
	v_pk_add_f32 v[142:143], v[142:143], 1.0 op_sel_hi:[1,0]
	v_and_b32_e32 v117, 0xffff0000, v16
	v_lshlrev_b32_e32 v36, 16, v50
	v_and_b32_e32 v37, 0xffff0000, v50
	v_lshlrev_b32_e32 v118, 16, v46
	v_and_b32_e32 v119, 0xffff0000, v46
	v_lshlrev_b32_e32 v120, 16, v54
	v_lshlrev_b32_e32 v134, 16, v12
	v_and_b32_e32 v135, 0xffff0000, v12
	v_lshlrev_b32_e32 v132, 16, v20
	s_waitcnt vmcnt(0) lgkmcnt(0)
	v_lshlrev_b32_e32 v136, 16, v8
	v_and_b32_e32 v137, 0xffff0000, v8
	v_and_b32_e32 v133, 0xffff0000, v20
	v_pk_fma_f32 v[126:127], v[70:71], v[136:137], v[126:127]
	s_nop 0
	v_mul_f32_e32 v20, 0xbfb8aa3b, v126
	v_rcp_f32_e32 v0, v143
	v_exp_f32_e32 v128, v20
	v_mul_f32_e32 v20, 0xbfb8aa3b, v127
	v_rcp_f32_e32 v4, v142
	v_exp_f32_e32 v129, v20
	v_mul_f32_e32 v0, v139, v0
	v_pk_add_f32 v[128:129], v[128:129], 1.0 op_sel_hi:[1,0]
	v_mul_f32_e32 v4, v138, v4
	v_cvt_pk_bf16_f32 v0, v4, v0
	v_pk_fma_f32 v[130:131], v[66:67], v[136:137], v[130:131]
	v_pk_fma_f32 v[144:145], v[58:59], v[136:137], v[74:75]
	v_pk_fma_f32 v[130:131], v[70:71], v[134:135], v[130:131]
	v_pk_fma_f32 v[146:147], v[62:63], v[136:137], v[146:147]
	v_mul_f32_e32 v46, 0xbfb8aa3b, v130
	v_exp_f32_e32 v136, v46
	v_rcp_f32_e32 v4, v129
	v_mul_f32_e32 v46, 0xbfb8aa3b, v131
	v_rcp_f32_e32 v8, v128
	v_exp_f32_e32 v137, v46
	s_nop 0
	v_pk_add_f32 v[136:137], v[136:137], 1.0 op_sel_hi:[1,0]
	v_mul_f32_e32 v4, v127, v4
	v_mul_f32_e32 v8, v126, v8
	v_cvt_pk_bf16_f32 v4, v8, v4
	v_pk_fma_f32 v[126:127], v[66:67], v[134:135], v[146:147]
	s_nop 0
	v_pk_fma_f32 v[126:127], v[70:71], v[132:133], v[126:127]
	s_nop 0
	v_mul_f32_e32 v50, 0xbfb8aa3b, v126
	v_exp_f32_e32 v128, v50
	v_rcp_f32_e32 v8, v137
	v_mul_f32_e32 v50, 0xbfb8aa3b, v127
	v_rcp_f32_e32 v12, v136
	v_exp_f32_e32 v129, v50
	s_nop 0
	v_pk_add_f32 v[128:129], v[128:129], 1.0 op_sel_hi:[1,0]
	v_mul_f32_e32 v8, v131, v8
	v_mul_f32_e32 v12, v130, v12
	v_cvt_pk_bf16_f32 v8, v12, v8
	v_pk_fma_f32 v[144:145], v[62:63], v[134:135], v[144:145]
	s_nop 0
	v_pk_fma_f32 v[130:131], v[66:67], v[132:133], v[144:145]
	v_and_b32_e32 v121, 0xffff0000, v54
	v_pk_fma_f32 v[130:131], v[70:71], v[36:37], v[130:131]
	v_pk_fma_f32 v[140:141], v[58:59], v[134:135], v[74:75]
	v_mul_f32_e32 v54, 0xbfb8aa3b, v130
	v_pk_fma_f32 v[122:123], v[58:59], v[132:133], v[74:75]
	v_pk_fma_f32 v[140:141], v[62:63], v[132:133], v[140:141]
	v_exp_f32_e32 v132, v54
	v_rcp_f32_e32 v12, v129
	v_mul_f32_e32 v54, 0xbfb8aa3b, v131
	v_rcp_f32_e32 v16, v128
	v_exp_f32_e32 v133, v54
	s_nop 0
	v_pk_add_f32 v[132:133], v[132:133], 1.0 op_sel_hi:[1,0]
	v_mul_f32_e32 v12, v127, v12
; DI unsigned pk2(float lo, float hi) { f32x2 v = {lo, hi}; bf16x2_t b = __builtin_convertvector(v, bf16x2_t); return __builtin_bit_cast(unsigned, b); }
; DI float bflo(unsigned u) { return __uint_as_float(u << 16); }
; DI float bfhi(unsigned u) { return __uint_as_float(u & 0xffff0000u); }
; DI float siluf_(float x) { return x / (1.f + __expf(-x)); }
; DI void conv_phase(int wv, const Params& P) {
;     ...
;         for (int i = 0; i < 11; ++i) { u32x4 q = (u32x4){0u, 0u, 0u, 0u}; if (i >= 3 || t0 != 0) q = *(const u32x4*)(XBC + (size_t)(r0 + i - 3) * 1536 + c0);
; #pragma unroll
;             for (int e = 0; e < 4; ++e) { x[i][2 * e] = bflo(q[e]); x[i][2 * e + 1] = bfhi(q[e]); } }
;         unsigned o[8][4];
; #pragma unroll
;         for (int i = 0; i < 8; ++i) { float y[8];
; #pragma unroll
;             for (int e = 0; e < 8; ++e) { float s = bias[e];
; #pragma unroll
;                 for (int k = 0; k < 4; ++k) s += w[k][e] * x[i + k][e];
;                 y[e] = siluf_(s); }
; #pragma unroll
;             for (int e = 0; e < 4; ++e) o[i][e] = pk2(y[2 * e], y[2 * e + 1]); }
	v_mul_f32_e32 v16, v126, v16
	v_cvt_pk_bf16_f32 v12, v16, v12
	v_pk_fma_f32 v[126:127], v[66:67], v[36:37], v[140:141]
	s_nop 0
	v_pk_fma_f32 v[126:127], v[70:71], v[116:117], v[126:127]
	s_nop 0
	v_mul_f32_e32 v79, 0xbfb8aa3b, v126
	v_exp_f32_e32 v128, v79
	v_rcp_f32_e32 v16, v133
	v_mul_f32_e32 v79, 0xbfb8aa3b, v127
	v_rcp_f32_e32 v20, v132
	v_exp_f32_e32 v129, v79
	s_nop 0
	v_pk_add_f32 v[128:129], v[128:129], 1.0 op_sel_hi:[1,0]
	v_mul_f32_e32 v16, v131, v16
	v_mul_f32_e32 v20, v130, v20
	v_cvt_pk_bf16_f32 v16, v20, v16
	v_pk_fma_f32 v[122:123], v[62:63], v[36:37], v[122:123]
	s_nop 0
	v_pk_fma_f32 v[122:123], v[66:67], v[116:117], v[122:123]
	s_nop 0
	v_pk_fma_f32 v[122:123], v[70:71], v[118:119], v[122:123]
	s_nop 0
	v_mul_f32_e32 v90, 0xbfb8aa3b, v122
	v_exp_f32_e32 v130, v90
	v_rcp_f32_e32 v20, v129
	v_mul_f32_e32 v90, 0xbfb8aa3b, v123
	v_rcp_f32_e32 v46, v128
	v_exp_f32_e32 v131, v90
	s_nop 0
	v_pk_add_f32 v[130:131], v[130:131], 1.0 op_sel_hi:[1,0]
	v_mul_f32_e32 v20, v127, v20
	v_mul_f32_e32 v46, v126, v46
	v_cvt_pk_bf16_f32 v20, v46, v20
	v_pk_fma_f32 v[36:37], v[58:59], v[36:37], v[74:75]
	s_nop 0
	v_pk_fma_f32 v[36:37], v[62:63], v[116:117], v[36:37]
	s_nop 0
	v_pk_fma_f32 v[36:37], v[66:67], v[118:119], v[36:37]
	s_nop 0
	v_pk_fma_f32 v[58:59], v[70:71], v[120:121], v[36:37]
	s_nop 0
	v_mul_f32_e32 v36, 0xbfb8aa3b, v58
	v_mul_f32_e32 v37, 0xbfb8aa3b, v59
	v_rcp_f32_e32 v46, v131
	v_exp_f32_e32 v36, v36
	v_exp_f32_e32 v37, v37
	s_nop 0
	v_pk_add_f32 v[62:63], v[36:37], 1.0 op_sel_hi:[1,0]
	v_rcp_f32_e32 v36, v130
	v_mul_f32_e32 v46, v123, v46
	v_mul_f32_e32 v36, v122, v36
	v_cvt_pk_bf16_f32 v36, v36, v46
	v_lshlrev_b32_e32 v122, 16, v1
	v_and_b32_e32 v123, 0xffff0000, v1
	v_lshlrev_b32_e32 v120, 16, v5
	v_and_b32_e32 v121, 0xffff0000, v5
	v_pk_fma_f32 v[114:115], v[68:69], v[122:123], v[114:115]
	s_nop 0
	v_pk_fma_f32 v[114:115], v[72:73], v[120:121], v[114:115]
	s_nop 0
	v_mul_f32_e32 v1, 0xbfb8aa3b, v114
	v_rcp_f32_e32 v37, v63
	v_exp_f32_e32 v126, v1
	v_mul_f32_e32 v1, 0xbfb8aa3b, v115
	v_exp_f32_e32 v127, v1
	v_mul_f32_e32 v70, v59, v37
	v_pk_add_f32 v[126:127], v[126:127], 1.0 op_sel_hi:[1,0]
	v_lshlrev_b32_e32 v118, 16, v9
	v_rcp_f32_e32 v37, v62
	v_and_b32_e32 v119, 0xffff0000, v9
	v_lshlrev_b32_e32 v116, 16, v13
	v_and_b32_e32 v117, 0xffff0000, v13
	v_mul_f32_e32 v71, v58, v37
	v_lshlrev_b32_e32 v58, 16, v17
	v_and_b32_e32 v59, 0xffff0000, v17
	v_pk_fma_f32 v[112:113], v[64:65], v[122:123], v[112:113]
	v_lshlrev_b32_e32 v74, 16, v21
	v_pk_fma_f32 v[112:113], v[68:69], v[120:121], v[112:113]
	v_and_b32_e32 v75, 0xffff0000, v21
	v_pk_fma_f32 v[112:113], v[72:73], v[118:119], v[112:113]
	s_nop 0
	v_mul_f32_e32 v21, 0xbfb8aa3b, v112
	v_pk_fma_f32 v[132:133], v[60:61], v[122:123], v[76:77]
	v_rcp_f32_e32 v1, v127
	v_exp_f32_e32 v122, v21
	v_mul_f32_e32 v21, 0xbfb8aa3b, v113
	v_rcp_f32_e32 v5, v126
	v_exp_f32_e32 v123, v21
	v_mul_f32_e32 v1, v115, v1
	v_pk_add_f32 v[122:123], v[122:123], 1.0 op_sel_hi:[1,0]
	v_mul_f32_e32 v5, v114, v5
	v_cvt_pk_bf16_f32 v1, v5, v1
	v_pk_fma_f32 v[114:115], v[64:65], v[120:121], v[132:133]
	v_pk_fma_f32 v[130:131], v[60:61], v[120:121], v[76:77]
	v_pk_fma_f32 v[114:115], v[68:69], v[118:119], v[114:115]
	v_pk_fma_f32 v[128:129], v[60:61], v[118:119], v[76:77]
	v_pk_fma_f32 v[114:115], v[72:73], v[116:117], v[114:115]
	v_pk_fma_f32 v[130:131], v[64:65], v[118:119], v[130:131]
	v_mul_f32_e32 v37, 0xbfb8aa3b, v114
	v_exp_f32_e32 v118, v37
	v_rcp_f32_e32 v5, v123
	v_mul_f32_e32 v37, 0xbfb8aa3b, v115
	v_rcp_f32_e32 v9, v122
	v_exp_f32_e32 v119, v37
	s_nop 0
	v_pk_add_f32 v[118:119], v[118:119], 1.0 op_sel_hi:[1,0]
	v_mul_f32_e32 v5, v113, v5
	v_mul_f32_e32 v9, v112, v9
	v_cvt_pk_bf16_f32 v5, v9, v5
	v_pk_fma_f32 v[112:113], v[68:69], v[116:117], v[130:131]
	v_pk_fma_f32 v[66:67], v[60:61], v[116:117], v[76:77]
	v_pk_fma_f32 v[112:113], v[72:73], v[74:75], v[112:113]
	v_pk_fma_f32 v[128:129], v[64:65], v[116:117], v[128:129]
	v_mul_f32_e32 v79, 0xbfb8aa3b, v112
	v_exp_f32_e32 v116, v79
	v_rcp_f32_e32 v9, v119
	v_mul_f32_e32 v79, 0xbfb8aa3b, v113
	v_rcp_f32_e32 v13, v118
	v_exp_f32_e32 v117, v79
	s_nop 0
	v_pk_add_f32 v[116:117], v[116:117], 1.0 op_sel_hi:[1,0]
	v_mul_f32_e32 v9, v115, v9
	v_mul_f32_e32 v13, v114, v13
	v_cvt_pk_bf16_f32 v9, v13, v9
	v_lshlrev_b32_e32 v50, 16, v51
	v_and_b32_e32 v51, 0xffff0000, v51
	v_pk_fma_f32 v[62:63], v[60:61], v[74:75], v[76:77]
	v_pk_fma_f32 v[66:67], v[64:65], v[74:75], v[66:67]
	v_pk_fma_f32 v[74:75], v[68:69], v[74:75], v[128:129]
	s_nop 0
	v_pk_fma_f32 v[74:75], v[72:73], v[50:51], v[74:75]
	s_nop 0
	v_mul_f32_e32 v90, 0xbfb8aa3b, v74
	v_exp_f32_e32 v114, v90
	v_rcp_f32_e32 v13, v117
	v_mul_f32_e32 v90, 0xbfb8aa3b, v75
	v_rcp_f32_e32 v17, v116
	v_exp_f32_e32 v115, v90
	s_nop 0
	v_pk_add_f32 v[114:115], v[114:115], 1.0 op_sel_hi:[1,0]
	v_mul_f32_e32 v13, v113, v13
	v_mul_f32_e32 v17, v112, v17
	v_cvt_pk_bf16_f32 v13, v17, v13
	v_pk_fma_f32 v[66:67], v[68:69], v[50:51], v[66:67]
	s_nop 0
	v_pk_fma_f32 v[66:67], v[72:73], v[58:59], v[66:67]
	s_nop 0
	v_mul_f32_e32 v90, 0xbfb8aa3b, v66
	v_rcp_f32_e32 v17, v115
	v_exp_f32_e32 v112, v90
	v_mul_f32_e32 v90, 0xbfb8aa3b, v67
	v_rcp_f32_e32 v21, v114
	v_exp_f32_e32 v113, v90
	v_mul_f32_e32 v17, v75, v17
	v_pk_add_f32 v[112:113], v[112:113], 1.0 op_sel_hi:[1,0]
	v_mul_f32_e32 v21, v74, v21
	v_cvt_pk_bf16_f32 v17, v21, v17
	v_pk_fma_f32 v[62:63], v[64:65], v[50:51], v[62:63]
	v_lshlrev_b32_e32 v46, 16, v47
	v_rcp_f32_e32 v21, v113
	v_and_b32_e32 v47, 0xffff0000, v47
	v_pk_fma_f32 v[62:63], v[68:69], v[58:59], v[62:63]
	s_nop 0
	v_pk_fma_f32 v[62:63], v[72:73], v[46:47], v[62:63]
	v_mul_f32_e32 v21, v67, v21
; DI unsigned pk2(float lo, float hi) { f32x2 v = {lo, hi}; bf16x2_t b = __builtin_convertvector(v, bf16x2_t); return __builtin_bit_cast(unsigned, b); }
; DI float bflo(unsigned u) { return __uint_as_float(u << 16); }
; DI float bfhi(unsigned u) { return __uint_as_float(u & 0xffff0000u); }
; DI float siluf_(float x) { return x / (1.f + __expf(-x)); }
; DI void conv_phase(int wv, const Params& P) {
;     ...
;         for (int i = 0; i < 11; ++i) { u32x4 q = (u32x4){0u, 0u, 0u, 0u}; if (i >= 3 || t0 != 0) q = *(const u32x4*)(XBC + (size_t)(r0 + i - 3) * 1536 + c0);
; #pragma unroll
;             for (int e = 0; e < 4; ++e) { x[i][2 * e] = bflo(q[e]); x[i][2 * e + 1] = bfhi(q[e]); } }
;         unsigned o[8][4];
; #pragma unroll
;         for (int i = 0; i < 8; ++i) { float y[8];
; #pragma unroll
;             for (int e = 0; e < 8; ++e) { float s = bias[e];
; #pragma unroll
;                 for (int k = 0; k < 4; ++k) s += w[k][e] * x[i + k][e];
;                 y[e] = siluf_(s); }
; #pragma unroll
;             for (int e = 0; e < 4; ++e) o[i][e] = pk2(y[2 * e], y[2 * e + 1]); }
	v_mul_f32_e32 v74, 0xbfb8aa3b, v62
	v_mul_f32_e32 v75, 0xbfb8aa3b, v63
	v_rcp_f32_e32 v37, v112
	v_exp_f32_e32 v74, v74
	v_exp_f32_e32 v75, v75
	s_nop 0
	v_pk_add_f32 v[74:75], v[74:75], 1.0 op_sel_hi:[1,0]
	v_mul_f32_e32 v37, v66, v37
	v_cvt_pk_bf16_f32 v21, v37, v21
	v_pk_fma_f32 v[50:51], v[60:61], v[50:51], v[76:77]
	s_nop 0
	v_pk_fma_f32 v[50:51], v[64:65], v[58:59], v[50:51]
	v_lshlrev_b32_e32 v54, 16, v55
	v_and_b32_e32 v55, 0xffff0000, v55
	v_pk_fma_f32 v[46:47], v[68:69], v[46:47], v[50:51]
	s_nop 0
	v_pk_fma_f32 v[46:47], v[72:73], v[54:55], v[46:47]
	s_nop 0
	v_mul_f32_e32 v50, 0xbfb8aa3b, v46
	v_rcp_f32_e32 v37, v75
	v_mul_f32_e32 v51, 0xbfb8aa3b, v47
	v_exp_f32_e32 v50, v50
	v_rcp_f32_e32 v54, v74
	v_exp_f32_e32 v51, v51
	v_mul_f32_e32 v37, v63, v37
	v_pk_add_f32 v[50:51], v[50:51], 1.0 op_sel_hi:[1,0]
	v_mul_f32_e32 v54, v62, v54
	v_cvt_pk_bf16_f32 v37, v54, v37
	v_lshlrev_b32_e32 v76, 16, v2
	v_and_b32_e32 v77, 0xffff0000, v2
	v_lshlrev_b32_e32 v74, 16, v6
	v_and_b32_e32 v75, 0xffff0000, v6
	v_pk_fma_f32 v[84:85], v[32:33], v[76:77], v[84:85]
	s_nop 0
	v_pk_fma_f32 v[84:85], v[38:39], v[74:75], v[84:85]
	s_nop 0
	v_mul_f32_e32 v2, 0xbfb8aa3b, v84
	v_rcp_f32_e32 v54, v51
	v_exp_f32_e32 v112, v2
	v_mul_f32_e32 v2, 0xbfb8aa3b, v85
	v_exp_f32_e32 v113, v2
	v_mul_f32_e32 v64, v47, v54
	v_pk_add_f32 v[112:113], v[112:113], 1.0 op_sel_hi:[1,0]
	v_lshlrev_b32_e32 v72, 16, v10
	v_rcp_f32_e32 v47, v50
	v_and_b32_e32 v73, 0xffff0000, v10
	v_lshlrev_b32_e32 v68, 16, v14
	v_and_b32_e32 v69, 0xffff0000, v14
	v_mul_f32_e32 v65, v46, v47
	v_lshlrev_b32_e32 v50, 16, v18
	v_and_b32_e32 v51, 0xffff0000, v18
	v_pk_fma_f32 v[118:119], v[24:25], v[76:77], v[42:43]
	v_pk_fma_f32 v[76:77], v[28:29], v[76:77], v[110:111]
	s_nop 0
	v_pk_fma_f32 v[76:77], v[32:33], v[74:75], v[76:77]
	v_lshlrev_b32_e32 v66, 16, v22
	v_and_b32_e32 v67, 0xffff0000, v22
	v_pk_fma_f32 v[76:77], v[38:39], v[72:73], v[76:77]
	s_nop 0
	v_mul_f32_e32 v22, 0xbfb8aa3b, v76
	v_rcp_f32_e32 v2, v113
	v_exp_f32_e32 v110, v22
	v_mul_f32_e32 v22, 0xbfb8aa3b, v77
	v_rcp_f32_e32 v6, v112
	v_exp_f32_e32 v111, v22
	v_mul_f32_e32 v2, v85, v2
	v_pk_add_f32 v[110:111], v[110:111], 1.0 op_sel_hi:[1,0]
	v_mul_f32_e32 v6, v84, v6
	v_cvt_pk_bf16_f32 v2, v6, v2
	v_pk_fma_f32 v[116:117], v[24:25], v[74:75], v[42:43]
	v_pk_fma_f32 v[74:75], v[28:29], v[74:75], v[118:119]
	v_pk_fma_f32 v[114:115], v[24:25], v[72:73], v[42:43]
	v_pk_fma_f32 v[116:117], v[28:29], v[72:73], v[116:117]
	v_pk_fma_f32 v[72:73], v[32:33], v[72:73], v[74:75]
	v_lshlrev_b32_e32 v54, 16, v48
	v_pk_fma_f32 v[72:73], v[38:39], v[68:69], v[72:73]
	v_and_b32_e32 v55, 0xffff0000, v48
	v_mul_f32_e32 v48, 0xbfb8aa3b, v72
	v_exp_f32_e32 v74, v48
	v_rcp_f32_e32 v6, v111
	v_mul_f32_e32 v48, 0xbfb8aa3b, v73
	v_rcp_f32_e32 v10, v110
	v_exp_f32_e32 v75, v48
	s_nop 0
	v_pk_add_f32 v[74:75], v[74:75], 1.0 op_sel_hi:[1,0]
	v_mul_f32_e32 v6, v77, v6
	v_mul_f32_e32 v10, v76, v10
	v_cvt_pk_bf16_f32 v6, v10, v6
	v_pk_fma_f32 v[62:63], v[24:25], v[68:69], v[42:43]
	v_pk_fma_f32 v[114:115], v[28:29], v[68:69], v[114:115]
	v_pk_fma_f32 v[68:69], v[32:33], v[68:69], v[116:117]
	v_lshlrev_b32_e32 v46, 16, v52
	v_pk_fma_f32 v[68:69], v[38:39], v[66:67], v[68:69]
	v_and_b32_e32 v47, 0xffff0000, v52
	v_mul_f32_e32 v52, 0xbfb8aa3b, v68
	v_exp_f32_e32 v76, v52
	v_rcp_f32_e32 v10, v75
	v_mul_f32_e32 v52, 0xbfb8aa3b, v69
	v_rcp_f32_e32 v14, v74
	v_exp_f32_e32 v77, v52
	s_nop 0
	v_pk_add_f32 v[76:77], v[76:77], 1.0 op_sel_hi:[1,0]
	v_mul_f32_e32 v10, v73, v10
	v_mul_f32_e32 v14, v72, v14
	v_cvt_pk_bf16_f32 v10, v14, v10
	v_pk_fma_f32 v[60:61], v[24:25], v[66:67], v[42:43]
	v_pk_fma_f32 v[62:63], v[28:29], v[66:67], v[62:63]
	v_pk_fma_f32 v[66:67], v[32:33], v[66:67], v[114:115]
	v_lshlrev_b32_e32 v58, 16, v56
	v_pk_fma_f32 v[66:67], v[38:39], v[46:47], v[66:67]
	v_and_b32_e32 v59, 0xffff0000, v56
	v_mul_f32_e32 v56, 0xbfb8aa3b, v66
	v_exp_f32_e32 v72, v56
	v_rcp_f32_e32 v14, v77
	v_mul_f32_e32 v56, 0xbfb8aa3b, v67
	v_rcp_f32_e32 v18, v76
	v_exp_f32_e32 v73, v56
	s_nop 0
	v_pk_add_f32 v[72:73], v[72:73], 1.0 op_sel_hi:[1,0]
	v_mul_f32_e32 v14, v69, v14
	v_mul_f32_e32 v18, v68, v18
	v_cvt_pk_bf16_f32 v14, v18, v14
	v_rcp_f32_e32 v18, v73
	v_pk_fma_f32 v[62:63], v[32:33], v[46:47], v[62:63]
	s_nop 0
	v_pk_fma_f32 v[62:63], v[38:39], v[50:51], v[62:63]
	v_mul_f32_e32 v18, v67, v18
	v_mul_f32_e32 v67, 0xbfb8aa3b, v62
	v_exp_f32_e32 v68, v67
	v_rcp_f32_e32 v22, v72
	v_mul_f32_e32 v67, 0xbfb8aa3b, v63
	v_exp_f32_e32 v69, v67
	s_nop 0
	v_pk_add_f32 v[68:69], v[68:69], 1.0 op_sel_hi:[1,0]
	v_mul_f32_e32 v22, v66, v22
	v_cvt_pk_bf16_f32 v18, v22, v18
	v_pk_fma_f32 v[60:61], v[28:29], v[46:47], v[60:61]
	s_nop 0
	v_pk_fma_f32 v[60:61], v[32:33], v[50:51], v[60:61]
	s_nop 0
	v_pk_fma_f32 v[60:61], v[38:39], v[54:55], v[60:61]
	s_nop 0
	v_mul_f32_e32 v66, 0xbfb8aa3b, v60
	v_rcp_f32_e32 v22, v69
	v_mul_f32_e32 v67, 0xbfb8aa3b, v61
	v_exp_f32_e32 v66, v66
	v_rcp_f32_e32 v48, v68
	v_exp_f32_e32 v67, v67
	v_mul_f32_e32 v22, v63, v22
	v_pk_add_f32 v[66:67], v[66:67], 1.0 op_sel_hi:[1,0]
	v_mul_f32_e32 v48, v62, v48
	v_cvt_pk_bf16_f32 v22, v48, v22
	v_pk_fma_f32 v[24:25], v[24:25], v[46:47], v[42:43]
	s_nop 0
	v_pk_fma_f32 v[24:25], v[28:29], v[50:51], v[24:25]
	s_nop 0
	v_pk_fma_f32 v[24:25], v[32:33], v[54:55], v[24:25]
	s_nop 0
	v_pk_fma_f32 v[24:25], v[38:39], v[58:59], v[24:25]
	s_nop 0
	v_mul_f32_e32 v28, 0xbfb8aa3b, v24
	v_rcp_f32_e32 v48, v67
	v_mul_f32_e32 v29, 0xbfb8aa3b, v25
	v_exp_f32_e32 v28, v28
	v_rcp_f32_e32 v32, v66
	v_exp_f32_e32 v29, v29
	v_mul_f32_e32 v48, v61, v48
	v_pk_add_f32 v[28:29], v[28:29], 1.0 op_sel_hi:[1,0]
	v_mul_f32_e32 v32, v60, v32
; DI unsigned pk2(float lo, float hi) { f32x2 v = {lo, hi}; bf16x2_t b = __builtin_convertvector(v, bf16x2_t); return __builtin_bit_cast(unsigned, b); }
; DI float bflo(unsigned u) { return __uint_as_float(u << 16); }
; DI float bfhi(unsigned u) { return __uint_as_float(u & 0xffff0000u); }
; DI float siluf_(float x) { return x / (1.f + __expf(-x)); }
; DI void conv_phase(int wv, const Params& P) {
;     ...
;         for (int i = 0; i < 11; ++i) { u32x4 q = (u32x4){0u, 0u, 0u, 0u}; if (i >= 3 || t0 != 0) q = *(const u32x4*)(XBC + (size_t)(r0 + i - 3) * 1536 + c0);
; #pragma unroll
;             for (int e = 0; e < 4; ++e) { x[i][2 * e] = bflo(q[e]); x[i][2 * e + 1] = bfhi(q[e]); } }
;         unsigned o[8][4];
; #pragma unroll
;         for (int i = 0; i < 8; ++i) { float y[8];
; #pragma unroll
;             for (int e = 0; e < 8; ++e) { float s = bias[e];
; #pragma unroll
;                 for (int k = 0; k < 4; ++k) s += w[k][e] * x[i + k][e];
;                 y[e] = siluf_(s); }
; #pragma unroll
;             for (int e = 0; e < 4; ++e) o[i][e] = pk2(y[2 * e], y[2 * e + 1]); }
;         if (c0 < 1024) {
	v_cvt_pk_bf16_f32 v38, v32, v48
	v_rcp_f32_e32 v32, v29
	s_nop 0
	v_mul_f32_e32 v76, v25, v32
	v_pk_fma_f32 v[60:61], v[26:27], v[80:81], v[44:45]
	v_lshlrev_b32_e32 v58, 16, v3
	v_and_b32_e32 v59, 0xffff0000, v3
	v_pk_fma_f32 v[60:61], v[30:31], v[82:83], v[60:61]
	v_lshlrev_b32_e32 v42, 16, v57
	v_and_b32_e32 v43, 0xffff0000, v57
	v_lshlrev_b32_e32 v56, 16, v7
	v_and_b32_e32 v57, 0xffff0000, v7
	v_pk_fma_f32 v[60:61], v[34:35], v[58:59], v[60:61]
	v_lshlrev_b32_e32 v54, 16, v11
	v_pk_fma_f32 v[60:61], v[40:41], v[56:57], v[60:61]
	v_and_b32_e32 v55, 0xffff0000, v11
	v_mul_f32_e32 v3, 0xbfb8aa3b, v60
	v_rcp_f32_e32 v25, v28
	v_exp_f32_e32 v62, v3
	v_mul_f32_e32 v3, 0xbfb8aa3b, v61
	v_exp_f32_e32 v63, v3
	v_mul_f32_e32 v77, v24, v25
	v_lshlrev_b32_e32 v24, 16, v53
	v_and_b32_e32 v25, 0xffff0000, v53
	v_pk_add_f32 v[62:63], v[62:63], 1.0 op_sel_hi:[1,0]
	v_lshlrev_b32_e32 v52, 16, v15
	v_and_b32_e32 v53, 0xffff0000, v15
	v_lshlrev_b32_e32 v28, 16, v19
	v_and_b32_e32 v29, 0xffff0000, v19
	v_pk_fma_f32 v[74:75], v[26:27], v[82:83], v[44:45]
	v_pk_fma_f32 v[72:73], v[26:27], v[58:59], v[44:45]
	v_pk_fma_f32 v[58:59], v[30:31], v[58:59], v[74:75]
	s_nop 0
	v_pk_fma_f32 v[58:59], v[34:35], v[56:57], v[58:59]
	v_lshlrev_b32_e32 v50, 16, v23
	v_and_b32_e32 v51, 0xffff0000, v23
	v_pk_fma_f32 v[58:59], v[40:41], v[54:55], v[58:59]
	s_nop 0
	v_mul_f32_e32 v23, 0xbfb8aa3b, v58
	v_rcp_f32_e32 v3, v63
	v_exp_f32_e32 v74, v23
	v_mul_f32_e32 v23, 0xbfb8aa3b, v59
	v_rcp_f32_e32 v7, v62
	v_exp_f32_e32 v75, v23
	v_mul_f32_e32 v3, v61, v3
	v_pk_add_f32 v[74:75], v[74:75], 1.0 op_sel_hi:[1,0]
	v_mul_f32_e32 v7, v60, v7
	v_cvt_pk_bf16_f32 v3, v7, v3
	v_pk_fma_f32 v[68:69], v[26:27], v[56:57], v[44:45]
	v_pk_fma_f32 v[56:57], v[30:31], v[56:57], v[72:73]
	v_pk_fma_f32 v[66:67], v[26:27], v[54:55], v[44:45]
	v_pk_fma_f32 v[68:69], v[30:31], v[54:55], v[68:69]
	v_pk_fma_f32 v[54:55], v[34:35], v[54:55], v[56:57]
	s_nop 0
	v_pk_fma_f32 v[54:55], v[40:41], v[52:53], v[54:55]
	s_nop 0
	v_mul_f32_e32 v39, 0xbfb8aa3b, v54
	v_exp_f32_e32 v56, v39
	v_rcp_f32_e32 v7, v75
	v_mul_f32_e32 v39, 0xbfb8aa3b, v55
	v_rcp_f32_e32 v11, v74
	v_exp_f32_e32 v57, v39
	s_nop 0
	v_pk_add_f32 v[56:57], v[56:57], 1.0 op_sel_hi:[1,0]
	v_mul_f32_e32 v7, v59, v7
	v_mul_f32_e32 v11, v58, v11
	v_cvt_pk_bf16_f32 v7, v11, v7
	v_lshlrev_b32_e32 v32, 16, v49
	v_and_b32_e32 v33, 0xffff0000, v49
	v_pk_fma_f32 v[48:49], v[26:27], v[52:53], v[44:45]
	v_rcp_f32_e32 v11, v57
	v_pk_fma_f32 v[66:67], v[30:31], v[52:53], v[66:67]
	v_pk_fma_f32 v[52:53], v[34:35], v[52:53], v[68:69]
	s_nop 0
	v_pk_fma_f32 v[52:53], v[40:41], v[50:51], v[52:53]
	v_mul_f32_e32 v11, v55, v11
	v_mul_f32_e32 v55, 0xbfb8aa3b, v52
	v_exp_f32_e32 v58, v55
	v_rcp_f32_e32 v15, v56
	v_mul_f32_e32 v55, 0xbfb8aa3b, v53
	v_exp_f32_e32 v59, v55
	s_nop 0
	v_pk_add_f32 v[58:59], v[58:59], 1.0 op_sel_hi:[1,0]
	v_mul_f32_e32 v15, v54, v15
	v_cvt_pk_bf16_f32 v11, v15, v11
	v_pk_fma_f32 v[46:47], v[26:27], v[50:51], v[44:45]
	v_pk_fma_f32 v[48:49], v[30:31], v[50:51], v[48:49]
	v_pk_fma_f32 v[50:51], v[34:35], v[50:51], v[66:67]
	s_nop 0
	v_pk_fma_f32 v[50:51], v[40:41], v[24:25], v[50:51]
	s_nop 0
	v_mul_f32_e32 v54, 0xbfb8aa3b, v50
	v_rcp_f32_e32 v15, v59
	v_mul_f32_e32 v55, 0xbfb8aa3b, v51
	v_exp_f32_e32 v54, v54
	v_rcp_f32_e32 v19, v58
	v_exp_f32_e32 v55, v55
	v_mul_f32_e32 v15, v53, v15
	v_pk_add_f32 v[54:55], v[54:55], 1.0 op_sel_hi:[1,0]
	v_mul_f32_e32 v19, v52, v19
	v_cvt_pk_bf16_f32 v15, v19, v15
	v_pk_fma_f32 v[48:49], v[34:35], v[24:25], v[48:49]
	s_nop 0
	v_pk_fma_f32 v[48:49], v[40:41], v[28:29], v[48:49]
	s_nop 0
	v_mul_f32_e32 v52, 0xbfb8aa3b, v48
	v_rcp_f32_e32 v19, v55
	v_mul_f32_e32 v53, 0xbfb8aa3b, v49
	v_exp_f32_e32 v52, v52
	v_rcp_f32_e32 v23, v54
	v_exp_f32_e32 v53, v53
	v_mul_f32_e32 v19, v51, v19
	v_pk_add_f32 v[52:53], v[52:53], 1.0 op_sel_hi:[1,0]
	v_mul_f32_e32 v23, v50, v23
	v_cvt_pk_bf16_f32 v19, v23, v19
	v_rcp_f32_e32 v23, v53
	v_pk_fma_f32 v[46:47], v[30:31], v[24:25], v[46:47]
	s_nop 0
	v_pk_fma_f32 v[46:47], v[34:35], v[28:29], v[46:47]
	v_mul_f32_e32 v23, v49, v23
	v_pk_fma_f32 v[46:47], v[40:41], v[32:33], v[46:47]
	s_nop 0
	v_mul_f32_e32 v50, 0xbfb8aa3b, v46
	v_mul_f32_e32 v51, 0xbfb8aa3b, v47
	v_rcp_f32_e32 v39, v52
	v_exp_f32_e32 v50, v50
	v_exp_f32_e32 v51, v51
	s_nop 0
	v_pk_add_f32 v[50:51], v[50:51], 1.0 op_sel_hi:[1,0]
	v_mul_f32_e32 v39, v48, v39
	v_cvt_pk_bf16_f32 v23, v39, v23
	v_pk_fma_f32 v[24:25], v[26:27], v[24:25], v[44:45]
	s_nop 0
	v_pk_fma_f32 v[24:25], v[30:31], v[28:29], v[24:25]
	s_nop 0
	v_pk_fma_f32 v[24:25], v[34:35], v[32:33], v[24:25]
	s_nop 0
	v_pk_fma_f32 v[24:25], v[40:41], v[42:43], v[24:25]
	s_nop 0
	v_mul_f32_e32 v26, 0xbfb8aa3b, v24
	v_rcp_f32_e32 v39, v51
	v_mul_f32_e32 v27, 0xbfb8aa3b, v25
	v_exp_f32_e32 v26, v26
	v_rcp_f32_e32 v28, v50
	v_exp_f32_e32 v27, v27
	v_mul_f32_e32 v39, v47, v39
	v_pk_add_f32 v[26:27], v[26:27], 1.0 op_sel_hi:[1,0]
	v_mul_f32_e32 v28, v46, v28
	v_cvt_pk_bf16_f32 v39, v28, v39
	v_rcp_f32_e32 v28, v27
	s_nop 0
	v_mul_f32_e32 v27, v25, v28
	v_rcp_f32_e32 v25, v26
	s_nop 0
	v_mul_f32_e32 v28, v24, v25
	v_cvt_pk_bf16_f32 v24, v71, v70
	v_cvt_pk_bf16_f32 v25, v65, v64
	v_cvt_pk_bf16_f32 v26, v77, v76
	v_cvt_pk_bf16_f32 v27, v28, v27
	v_cmp_lt_i32_e32 vcc, s43, v78
	s_and_saveexec_b64 s[26:27], vcc
	s_xor_b64 s[26:27], exec, s[26:27]
	s_cbranch_execz .LBB0_1316
; DI void conv_phase(int wv, const Params& P) {
;     ...
;         if (c0 < 1024) {
; #pragma unroll
;             for (int i = 0; i < 8; ++i) *(u32x4*)(XS + (size_t)(r0 + i) * 1024 + c0) = (u32x4){o[i][0], o[i][1], o[i][2], o[i][3]};
;         } else if (c0 < 1280) { const int cc = c0 - 1024, g = cc >> 7, n0 = cc & 127;
; #pragma unroll
;             for (int i = 0; i < 8; ++i) *(u32x4*)(BM + (size_t)(r0 + i) * 256 + cc) = (u32x4){o[i][0], o[i][1], o[i][2], o[i][3]};
; #pragma unroll
;             for (int e = 0; e < 8; ++e) { u32x4 q;
; #pragma unroll
;                 for (int i2 = 0; i2 < 4; ++i2) { const unsigned lo = (o[2 * i2][e >> 1] >> ((e & 1) * 16)) & 0xffffu, hi = (o[2 * i2 + 1][e >> 1] >> ((e & 1) * 16)) & 0xffffu; q[i2] = lo | (hi << 16); }
;                 *(u32x4*)(BMT + ((size_t)(b * 2 + g) * 128 + n0 + e) * SEQ + t0) = q; }
;         } else { const int cc = c0 - 1280;
; #pragma unroll
;             for (int i = 0; i < 8; ++i) *(u32x4*)(CM + (size_t)(r0 + i) * 256 + cc) = (u32x4){o[i][0], o[i][1], o[i][2], o[i][3]};
;         }
	v_cmp_lt_u32_e32 vcc, s44, v78
	v_lshlrev_b64 v[42:43], 9, v[106:107]
	v_lshlrev_b64 v[46:47], 9, v[94:95]
	v_lshlrev_b64 v[44:45], 9, v[108:109]
	v_lshlrev_b64 v[40:41], 9, v[104:105]
	v_lshlrev_b64 v[34:35], 9, v[102:103]
	v_lshlrev_b64 v[32:33], 9, v[98:99]
	v_lshlrev_b64 v[30:31], 9, v[100:101]
	v_lshlrev_b64 v[28:29], 9, v[96:97]
	s_and_saveexec_b64 s[28:29], vcc
	s_xor_b64 s[28:29], exec, s[28:29]
	s_cbranch_execz .LBB0_1313
	v_lshl_add_u64 v[48:49], v[92:93], 1, s[2:3]
	v_lshl_add_u64 v[46:47], v[48:49], 0, v[46:47]
	v_add_co_u32_e32 v46, vcc, 0xd7ff000, v46
	s_nop 1
	v_addc_co_u32_e32 v47, vcc, 0, v47, vcc
	flat_store_dwordx4 v[46:47], v[0:3] offset:1536
	s_nop 1
	v_lshl_add_u64 v[0:1], v[48:49], 0, v[44:45]
	v_add_co_u32_e32 v0, vcc, 0xd7ff000, v0
	s_nop 1
	v_addc_co_u32_e32 v1, vcc, 0, v1, vcc
	flat_store_dwordx4 v[0:1], v[4:7] offset:1536
	v_lshl_add_u64 v[0:1], v[48:49], 0, v[42:43]
	v_add_co_u32_e32 v0, vcc, 0xd7ff000, v0
	s_nop 1
	v_addc_co_u32_e32 v1, vcc, 0, v1, vcc
	flat_store_dwordx4 v[0:1], v[8:11] offset:1536
	v_lshl_add_u64 v[0:1], v[48:49], 0, v[40:41]
	v_add_co_u32_e32 v0, vcc, 0xd7ff000, v0
	s_nop 1
	v_addc_co_u32_e32 v1, vcc, 0, v1, vcc
	flat_store_dwordx4 v[0:1], v[12:15] offset:1536
	v_lshl_add_u64 v[0:1], v[48:49], 0, v[34:35]
	v_add_co_u32_e32 v0, vcc, 0xd7ff000, v0
	s_nop 1
	v_addc_co_u32_e32 v1, vcc, 0, v1, vcc
	flat_store_dwordx4 v[0:1], v[16:19] offset:1536
	v_lshl_add_u64 v[0:1], v[48:49], 0, v[32:33]
	v_add_co_u32_e32 v0, vcc, 0xd7ff000, v0
	s_nop 1
	v_addc_co_u32_e32 v1, vcc, 0, v1, vcc
	flat_store_dwordx4 v[0:1], v[20:23] offset:1536
	v_lshl_add_u64 v[0:1], v[48:49], 0, v[30:31]
	v_add_co_u32_e32 v0, vcc, 0xd7ff000, v0
	s_nop 1
	v_addc_co_u32_e32 v1, vcc, 0, v1, vcc
	flat_store_dwordx4 v[0:1], v[36:39] offset:1536
	v_lshl_add_u64 v[0:1], v[48:49], 0, v[28:29]
	v_add_co_u32_e32 v0, vcc, 0xd7ff000, v0
	s_nop 1
	v_addc_co_u32_e32 v1, vcc, 0, v1, vcc
	flat_store_dwordx4 v[0:1], v[24:27] offset:1536

; DI float xsum32(float v) { auto r = __builtin_amdgcn_permlane32_swap(__float_as_uint(v), __float_as_uint(v), false, false); return __uint_as_float(r[0]) + __uint_as_float(r[1]); }
; DI void nsa_phase(int wv, const Params& P, LAS unsigned char* lds) {
;     ...
;             const float lt = xsum32(st.l), gg = br ? g2 : g1, sc = lt > 0.f ? gg / lt : 0.f;
.LBB0_1610:
	v_mov_b32_e32 v0, v219
	s_nop 1
	v_permlane32_swap_b32_e32 v219, v0
	v_add_f32_e32 v34, v219, v0
	v_mov_b32_e32 v0, 0
	v_cmp_lt_f32_e32 vcc, 0, v34
	s_and_saveexec_b64 s[10:11], vcc
	s_cbranch_execz .LBB0_1564
	v_rcp_f32_e32 v35, v34
	v_cndmask_b32_e64 v0, v120, v119, s[16:17]
	v_mul_f32_e32 v0, v0, v35
	s_branch .LBB0_1564

; DI float bflo(unsigned u) { return __uint_as_float(u << 16); }
; DI float bfhi(unsigned u) { return __uint_as_float(u & 0xffff0000u); }
; DI float siluf_(float x) { return x / (1.f + __expf(-x)); }
; DI float xhalf(float v) { return __shfl_xor(v, 32); }
; DI void ssd_out_phase(int wv, const Params& P, LAS unsigned char* lds) {
;     ...
;         for (int lt = 0; lt < 4; ++lt) { const size_t rr = (size_t)(row0 + lt * 32 + q); float ss = 0.f;
; #pragma unroll
;             for (int pt = 0; pt < 2; ++pt)
; #pragma unroll
;                 for (int i4 = 0; i4 < 4; ++i4) { const int p0 = h * 64 + pt * 32 + 8 * i4 + 4 * hh; const u32x2 xv = *(const u32x2*)(XS + rr * 1024 + p0), zv = *(const u32x2*)(Z + rr * 1024 + p0);
;                     const float xs4[4] = {bflo(xv.x), bfhi(xv.x), bflo(xv.y), bfhi(xv.y)}, zs4[4] = {bflo(zv.x), bfhi(zv.x), bflo(zv.y), bfhi(zv.y)};
; #pragma unroll
;                     for (int e = 0; e < 4; ++e) { const float y = (acc[pt][lt][4 * i4 + e] + xs4[e] * dsk) * siluf_(zs4[e]); acc[pt][lt][4 * i4 + e] = y; ss += y * y; } }
;             ss += xhalf(ss); if (hh == 0) ssq[wave * 128 + lt * 32 + q] = ss; }
.LBB0_1687:
	v_ashrrev_i32_e32 v197, 31, v196
	v_or_b32_e32 v130, v204, v228
	v_lshlrev_b64 v[128:129], 11, v[196:197]
	v_ashrrev_i32_e32 v131, 31, v130
	v_lshl_add_u64 v[132:133], s[28:29], 0, v[128:129]
	v_lshl_add_u64 v[136:137], s[34:35], 0, v[128:129]
	v_lshlrev_b64 v[128:129], 1, v[130:131]
	v_lshl_add_u64 v[134:135], v[132:133], 0, v[128:129]
	v_lshl_add_u64 v[136:137], v[136:137], 0, v[128:129]
	flat_load_dwordx2 v[138:139], v[134:135]
	flat_load_dwordx2 v[140:141], v[136:137]
	flat_load_dwordx2 v[142:143], v[136:137] offset:16
	v_lshl_add_u64 v[132:133], v[198:199], 2, s[22:23]
	global_load_dword v132, v[132:133], off
	s_nop 0
	flat_load_dwordx2 v[144:145], v[134:135] offset:16
	flat_load_dwordx2 v[148:149], v[134:135] offset:32
	flat_load_dwordx2 v[156:157], v[134:135] offset:48
	flat_load_dwordx2 v[146:147], v[136:137] offset:32
	flat_load_dwordx2 v[150:151], v[136:137] offset:48
	s_waitcnt vmcnt(0) lgkmcnt(0)
	v_lshlrev_b32_e32 v133, 16, v140
	v_and_b32_e32 v158, 0xffff0000, v140
	v_lshlrev_b32_e32 v152, 16, v138
	v_and_b32_e32 v153, 0xffff0000, v138
	v_lshlrev_b32_e32 v159, 16, v141
	v_and_b32_e32 v160, 0xffff0000, v141
	v_lshlrev_b32_e32 v161, 16, v142
	v_and_b32_e32 v142, 0xffff0000, v142
	v_mul_f32_e32 v140, 0xbfb8aa3b, v133
	v_mul_f32_e32 v141, 0xbfb8aa3b, v158
	v_pk_fma_f32 v[112:113], v[132:133], v[152:153], v[112:113] op_sel_hi:[0,1,1]
	v_mul_f32_e32 v152, 0xbfb8aa3b, v159
	v_mul_f32_e32 v153, 0xbfb8aa3b, v160
	v_mul_f32_e32 v154, 0xbfb8aa3b, v161
	v_mul_f32_e32 v155, 0xbfb8aa3b, v142
	v_exp_f32_e32 v140, v140
	v_exp_f32_e32 v141, v141
	v_exp_f32_e32 v152, v152
	v_exp_f32_e32 v153, v153
	v_exp_f32_e32 v154, v154
	v_exp_f32_e32 v155, v155
	v_lshlrev_b32_e32 v138, 16, v139
	v_and_b32_e32 v139, 0xffff0000, v139
	v_pk_fma_f32 v[114:115], v[132:133], v[138:139], v[114:115] op_sel_hi:[0,1,1]
	v_pk_add_f32 v[138:139], v[140:141], 1.0 op_sel_hi:[1,0]
	v_pk_add_f32 v[140:141], v[152:153], 1.0 op_sel_hi:[1,0]
	v_pk_add_f32 v[152:153], v[154:155], 1.0 op_sel_hi:[1,0]
	v_rcp_f32_e32 v154, v139
	s_mov_b64 vcc, s[14:15]
	v_mul_f32_e32 v139, v158, v154
	v_rcp_f32_e32 v154, v138
	s_mov_b64 vcc, s[16:17]
	v_mul_f32_e32 v138, v133, v154
	v_rcp_f32_e32 v133, v141
	s_mov_b64 vcc, s[18:19]
	v_mul_f32_e32 v141, v160, v133
	v_rcp_f32_e32 v133, v140
	v_lshlrev_b32_e32 v154, 16, v144
	v_and_b32_e32 v155, 0xffff0000, v144
	v_mul_f32_e32 v140, v159, v133
	v_pk_fma_f32 v[116:117], v[132:133], v[154:155], v[116:117] op_sel_hi:[0,1,1]
	v_rcp_f32_e32 v133, v153
	s_nop 0
	v_mul_f32_e32 v153, v142, v133
	v_lshlrev_b32_e32 v158, 16, v143
	v_and_b32_e32 v159, 0xffff0000, v143
	v_mul_f32_e32 v142, 0xbfb8aa3b, v158
	v_rcp_f32_e32 v133, v152
	v_exp_f32_e32 v154, v142
	v_mul_f32_e32 v142, 0xbfb8aa3b, v159
	v_exp_f32_e32 v155, v142
	v_mul_f32_e32 v152, v161, v133
	v_pk_mul_f32 v[116:117], v[116:117], v[152:153]
	v_lshlrev_b32_e32 v144, 16, v145
	v_pk_add_f32 v[152:153], v[154:155], 1.0 op_sel_hi:[1,0]
	v_and_b32_e32 v145, 0xffff0000, v145
	v_div_scale_f32 v133, s[14:15], v153, v153, v159
	v_rcp_f32_e32 v154, v133
	v_pk_fma_f32 v[118:119], v[132:133], v[144:145], v[118:119] op_sel_hi:[0,1,1]
	v_lshlrev_b32_e32 v160, 16, v147
	v_lshlrev_b32_e32 v162, 16, v150
	v_fma_f32 v144, -v133, v154, 1.0
	v_fmac_f32_e32 v154, v144, v154
	v_div_scale_f32 v144, vcc, v159, v153, v159
	v_mul_f32_e32 v145, v144, v154
	v_fma_f32 v155, -v133, v145, v144
	v_fmac_f32_e32 v145, v155, v154
	v_fma_f32 v133, -v133, v145, v144
	v_div_fmas_f32 v133, v133, v154, v145
	v_div_fixup_f32 v145, v133, v153, v159
	v_lshlrev_b32_e32 v159, 16, v146
	v_and_b32_e32 v146, 0xffff0000, v146
	v_mul_f32_e32 v144, 0xbfb8aa3b, v159
	v_rcp_f32_e32 v133, v152
	v_exp_f32_e32 v154, v144
	v_mul_f32_e32 v144, 0xbfb8aa3b, v146
	v_exp_f32_e32 v155, v144
	v_mul_f32_e32 v144, v158, v133
	v_and_b32_e32 v150, 0xffff0000, v150
	v_lshlrev_b32_e32 v166, 16, v151
	v_pk_add_f32 v[152:153], v[154:155], 1.0 op_sel_hi:[1,0]
	v_lshlrev_b32_e32 v154, 16, v148
	v_div_scale_f32 v133, s[14:15], v153, v153, v146
	v_rcp_f32_e32 v158, v133
	v_and_b32_e32 v155, 0xffff0000, v148
	v_pk_fma_f32 v[120:121], v[132:133], v[154:155], v[120:121] op_sel_hi:[0,1,1]
	v_pk_mul_f32 v[112:113], v[112:113], v[138:139]
	v_fma_f32 v148, -v133, v158, 1.0
	v_fmac_f32_e32 v158, v148, v158
	v_div_scale_f32 v148, vcc, v146, v153, v146
	v_mul_f32_e32 v154, v148, v158
	v_fma_f32 v155, -v133, v154, v148
	v_fmac_f32_e32 v154, v155, v158
	v_fma_f32 v133, -v133, v154, v148
	v_div_fmas_f32 v133, v133, v158, v154
	v_div_fixup_f32 v153, v133, v153, v146
	v_and_b32_e32 v158, 0xffff0000, v147
	v_mul_f32_e32 v146, 0xbfb8aa3b, v160
	v_rcp_f32_e32 v133, v152
	v_exp_f32_e32 v154, v146
	v_mul_f32_e32 v146, 0xbfb8aa3b, v158
	v_exp_f32_e32 v155, v146
	v_mul_f32_e32 v152, v159, v133
	v_pk_mul_f32 v[120:121], v[120:121], v[152:153]
	v_lshlrev_b32_e32 v148, 16, v149
	v_pk_add_f32 v[154:155], v[154:155], 1.0 op_sel_hi:[1,0]
	v_and_b32_e32 v149, 0xffff0000, v149
	v_div_scale_f32 v133, s[14:15], v155, v155, v158
	v_rcp_f32_e32 v152, v133
	v_pk_fma_f32 v[122:123], v[132:133], v[148:149], v[122:123] op_sel_hi:[0,1,1]
	v_pk_mul_f32 v[138:139], v[112:113], v[112:113]
	v_pk_mul_f32 v[114:115], v[114:115], v[140:141]
	v_fma_f32 v148, -v133, v152, 1.0
	v_fmac_f32_e32 v152, v148, v152
	v_div_scale_f32 v148, vcc, v158, v155, v158
	v_mul_f32_e32 v149, v148, v152
	v_fma_f32 v153, -v133, v149, v148
	v_fmac_f32_e32 v149, v153, v152
	v_fma_f32 v133, -v133, v149, v148
	v_div_fmas_f32 v133, v133, v152, v149
	v_div_fixup_f32 v149, v133, v155, v158
	v_pk_mul_f32 v[140:141], v[114:115], v[114:115]
	flat_load_dwordx2 v[152:153], v[136:137] offset:64
	v_mul_f32_e32 v148, 0xbfb8aa3b, v162
; DI float bflo(unsigned u) { return __uint_as_float(u << 16); }
; DI float bfhi(unsigned u) { return __uint_as_float(u & 0xffff0000u); }
; DI float siluf_(float x) { return x / (1.f + __expf(-x)); }
; DI float xhalf(float v) { return __shfl_xor(v, 32); }
; DI void ssd_out_phase(int wv, const Params& P, LAS unsigned char* lds) {
;     ...
;         for (int lt = 0; lt < 4; ++lt) { const size_t rr = (size_t)(row0 + lt * 32 + q); float ss = 0.f;
; #pragma unroll
;             for (int pt = 0; pt < 2; ++pt)
; #pragma unroll
;                 for (int i4 = 0; i4 < 4; ++i4) { const int p0 = h * 64 + pt * 32 + 8 * i4 + 4 * hh; const u32x2 xv = *(const u32x2*)(XS + rr * 1024 + p0), zv = *(const u32x2*)(Z + rr * 1024 + p0);
;                     const float xs4[4] = {bflo(xv.x), bfhi(xv.x), bflo(xv.y), bfhi(xv.y)}, zs4[4] = {bflo(zv.x), bfhi(zv.x), bflo(zv.y), bfhi(zv.y)};
; #pragma unroll
;                     for (int e = 0; e < 4; ++e) { const float y = (acc[pt][lt][4 * i4 + e] + xs4[e] * dsk) * siluf_(zs4[e]); acc[pt][lt][4 * i4 + e] = y; ss += y * y; } }
;             ss += xhalf(ss); if (hh == 0) ssq[wave * 128 + lt * 32 + q] = ss; }
	v_rcp_f32_e32 v133, v154
	v_exp_f32_e32 v158, v148
	v_mul_f32_e32 v148, 0xbfb8aa3b, v150
	v_exp_f32_e32 v159, v148
	v_mul_f32_e32 v148, v160, v133
	v_lshlrev_b32_e32 v154, 16, v156
	v_and_b32_e32 v155, 0xffff0000, v156
	v_pk_add_f32 v[158:159], v[158:159], 1.0 op_sel_hi:[1,0]
	v_pk_mul_f32 v[142:143], v[116:117], v[116:117]
	v_div_scale_f32 v133, s[14:15], v159, v159, v150
	v_rcp_f32_e32 v160, v133
	v_pk_fma_f32 v[124:125], v[132:133], v[154:155], v[124:125] op_sel_hi:[0,1,1]
	v_div_scale_f32 v156, vcc, v150, v159, v150
	v_fma_f32 v154, -v133, v160, 1.0
	v_fmac_f32_e32 v160, v154, v160
	flat_load_dwordx2 v[154:155], v[134:135] offset:64
	v_mul_f32_e32 v161, v156, v160
	v_fma_f32 v163, -v133, v161, v156
	v_fmac_f32_e32 v161, v163, v160
	v_fma_f32 v133, -v133, v161, v156
	v_div_fmas_f32 v133, v133, v160, v161
	v_div_fixup_f32 v159, v133, v159, v150
	v_pk_mul_f32 v[118:119], v[118:119], v[144:145]
	v_and_b32_e32 v163, 0xffff0000, v151
	v_mul_f32_e32 v150, 0xbfb8aa3b, v166
	v_rcp_f32_e32 v133, v158
	v_exp_f32_e32 v160, v150
	v_mul_f32_e32 v150, 0xbfb8aa3b, v163
	v_exp_f32_e32 v161, v150
	v_mul_f32_e32 v158, v162, v133
	v_pk_mul_f32 v[124:125], v[124:125], v[158:159]
	v_lshlrev_b32_e32 v156, 16, v157
	v_pk_add_f32 v[158:159], v[160:161], 1.0 op_sel_hi:[1,0]
	v_and_b32_e32 v157, 0xffff0000, v157
	v_div_scale_f32 v133, s[14:15], v159, v159, v163
	v_rcp_f32_e32 v160, v133
	v_pk_fma_f32 v[126:127], v[132:133], v[156:157], v[126:127] op_sel_hi:[0,1,1]
	v_pk_mul_f32 v[144:145], v[118:119], v[118:119]
	v_pk_mul_f32 v[146:147], v[120:121], v[120:121]
	v_fma_f32 v156, -v133, v160, 1.0
	v_fmac_f32_e32 v160, v156, v160
	v_div_scale_f32 v156, vcc, v163, v159, v163
	v_mul_f32_e32 v157, v156, v160
	v_fma_f32 v161, -v133, v157, v156
	v_fmac_f32_e32 v157, v161, v160
	v_fma_f32 v133, -v133, v157, v156
	v_div_fmas_f32 v133, v133, v160, v157
	v_div_fixup_f32 v159, v133, v159, v163
	v_pk_mul_f32 v[122:123], v[122:123], v[148:149]
	flat_load_dwordx2 v[156:157], v[136:137] offset:80
	flat_load_dwordx2 v[160:161], v[136:137] offset:96
	flat_load_dwordx2 v[162:163], v[136:137] offset:112
	v_rcp_f32_e32 v133, v158
	s_nop 0
	v_mul_f32_e32 v158, v166, v133
	v_pk_mul_f32 v[126:127], v[126:127], v[158:159]
	s_waitcnt vmcnt(0) lgkmcnt(0)
	v_lshlrev_b32_e32 v170, 16, v152
	v_and_b32_e32 v152, 0xffff0000, v152
	v_mul_f32_e32 v136, 0xbfb8aa3b, v170
	v_exp_f32_e32 v164, v136
	v_mul_f32_e32 v136, 0xbfb8aa3b, v152
	v_exp_f32_e32 v165, v136
	v_and_b32_e32 v172, 0xffff0000, v153
	v_pk_mul_f32 v[148:149], v[122:123], v[122:123]
	v_pk_mul_f32 v[150:151], v[124:125], v[124:125]
	v_pk_add_f32 v[158:159], v[164:165], 1.0 op_sel_hi:[1,0]
	flat_load_dwordx2 v[164:165], v[134:135] offset:80
	flat_load_dwordx2 v[166:167], v[134:135] offset:96
	s_nop 0
	flat_load_dwordx2 v[134:135], v[134:135] offset:112
	v_div_scale_f32 v133, s[14:15], v159, v159, v152
	v_rcp_f32_e32 v171, v133
	v_pk_mul_f32 v[136:137], v[126:127], v[126:127]
	v_lshlrev_b32_e32 v168, 16, v154
	v_and_b32_e32 v169, 0xffff0000, v154
	v_fma_f32 v154, -v133, v171, 1.0
	v_fmac_f32_e32 v171, v154, v171
	v_div_scale_f32 v154, vcc, v152, v159, v152
	v_pk_fma_f32 v[96:97], v[132:133], v[168:169], v[96:97] op_sel_hi:[0,1,1]
	v_mul_f32_e32 v168, v154, v171
	v_fma_f32 v169, -v133, v168, v154
	v_fmac_f32_e32 v168, v169, v171
	v_fma_f32 v133, -v133, v168, v154
	v_div_fmas_f32 v133, v133, v171, v168
	v_div_fixup_f32 v159, v133, v159, v152
	v_lshlrev_b32_e32 v171, 16, v153
	v_mul_f32_e32 v152, 0xbfb8aa3b, v171
	v_rcp_f32_e32 v133, v158
	v_exp_f32_e32 v168, v152
	v_mul_f32_e32 v152, 0xbfb8aa3b, v172
	v_exp_f32_e32 v169, v152
	v_mul_f32_e32 v158, v170, v133
	v_pk_mul_f32 v[96:97], v[96:97], v[158:159]
	v_lshlrev_b32_e32 v154, 16, v155
	v_pk_add_f32 v[158:159], v[168:169], 1.0 op_sel_hi:[1,0]
	v_and_b32_e32 v155, 0xffff0000, v155
	v_div_scale_f32 v133, s[14:15], v159, v159, v172
	v_rcp_f32_e32 v168, v133
	v_pk_fma_f32 v[98:99], v[132:133], v[154:155], v[98:99] op_sel_hi:[0,1,1]
	v_pk_mul_f32 v[152:153], v[96:97], v[96:97]
	v_fma_f32 v154, -v133, v168, 1.0
	v_fmac_f32_e32 v168, v154, v168
	v_div_scale_f32 v154, vcc, v172, v159, v172
	v_mul_f32_e32 v155, v154, v168
	v_fma_f32 v169, -v133, v155, v154
	v_fmac_f32_e32 v155, v169, v168
	v_fma_f32 v133, -v133, v155, v154
	v_div_fmas_f32 v133, v133, v168, v155
	v_div_fixup_f32 v155, v133, v159, v172
	v_lshlrev_b32_e32 v170, 16, v156
	v_and_b32_e32 v156, 0xffff0000, v156
	v_mul_f32_e32 v154, 0xbfb8aa3b, v170
	v_rcp_f32_e32 v133, v158
	v_exp_f32_e32 v168, v154
	v_mul_f32_e32 v154, 0xbfb8aa3b, v156
	v_exp_f32_e32 v169, v154
	v_mul_f32_e32 v154, v171, v133
	v_pk_mul_f32 v[98:99], v[98:99], v[154:155]
	v_pk_add_f32 v[158:159], v[168:169], 1.0 op_sel_hi:[1,0]
	s_nop 0
	v_div_scale_f32 v133, s[14:15], v159, v159, v156
	v_rcp_f32_e32 v171, v133
	s_waitcnt vmcnt(0) lgkmcnt(0)
; DI float bflo(unsigned u) { return __uint_as_float(u << 16); }
; DI float bfhi(unsigned u) { return __uint_as_float(u & 0xffff0000u); }
; DI float siluf_(float x) { return x / (1.f + __expf(-x)); }
; DI float xhalf(float v) { return __shfl_xor(v, 32); }
; DI void ssd_out_phase(int wv, const Params& P, LAS unsigned char* lds) {
;     ...
;         for (int lt = 0; lt < 4; ++lt) { const size_t rr = (size_t)(row0 + lt * 32 + q); float ss = 0.f;
; #pragma unroll
;             for (int pt = 0; pt < 2; ++pt)
; #pragma unroll
;                 for (int i4 = 0; i4 < 4; ++i4) { const int p0 = h * 64 + pt * 32 + 8 * i4 + 4 * hh; const u32x2 xv = *(const u32x2*)(XS + rr * 1024 + p0), zv = *(const u32x2*)(Z + rr * 1024 + p0);
;                     const float xs4[4] = {bflo(xv.x), bfhi(xv.x), bflo(xv.y), bfhi(xv.y)}, zs4[4] = {bflo(zv.x), bfhi(zv.x), bflo(zv.y), bfhi(zv.y)};
; #pragma unroll
;                     for (int e = 0; e < 4; ++e) { const float y = (acc[pt][lt][4 * i4 + e] + xs4[e] * dsk) * siluf_(zs4[e]); acc[pt][lt][4 * i4 + e] = y; ss += y * y; } }
;             ss += xhalf(ss); if (hh == 0) ssq[wave * 128 + lt * 32 + q] = ss; }
	v_lshlrev_b32_e32 v168, 16, v164
	v_and_b32_e32 v169, 0xffff0000, v164
	v_pk_fma_f32 v[100:101], v[132:133], v[168:169], v[100:101] op_sel_hi:[0,1,1]
	v_fma_f32 v164, -v133, v171, 1.0
	v_fmac_f32_e32 v171, v164, v171
	v_div_scale_f32 v164, vcc, v156, v159, v156
	v_mul_f32_e32 v168, v164, v171
	v_fma_f32 v169, -v133, v168, v164
	v_fmac_f32_e32 v168, v169, v171
	v_fma_f32 v133, -v133, v168, v164
	v_div_fmas_f32 v133, v133, v171, v168
	v_div_fixup_f32 v159, v133, v159, v156
	v_pk_mul_f32 v[154:155], v[98:99], v[98:99]
	v_lshlrev_b32_e32 v168, 16, v157
	v_and_b32_e32 v169, 0xffff0000, v157
	v_mul_f32_e32 v156, 0xbfb8aa3b, v168
	v_rcp_f32_e32 v133, v158
	v_mul_f32_e32 v157, 0xbfb8aa3b, v169
	v_exp_f32_e32 v156, v156
	v_exp_f32_e32 v157, v157
	v_mul_f32_e32 v158, v170, v133
	v_lshlrev_b32_e32 v164, 16, v165
	v_and_b32_e32 v165, 0xffff0000, v165
	v_pk_add_f32 v[156:157], v[156:157], 1.0 op_sel_hi:[1,0]
	v_pk_mul_f32 v[100:101], v[100:101], v[158:159]
	v_div_scale_f32 v133, s[14:15], v157, v157, v169
	v_rcp_f32_e32 v170, v133
	v_pk_fma_f32 v[102:103], v[132:133], v[164:165], v[102:103] op_sel_hi:[0,1,1]
	v_pk_mul_f32 v[158:159], v[100:101], v[100:101]
	v_fma_f32 v164, -v133, v170, 1.0
	v_fmac_f32_e32 v170, v164, v170
	v_div_scale_f32 v164, vcc, v169, v157, v169
	v_mul_f32_e32 v165, v164, v170
	v_fma_f32 v171, -v133, v165, v164
	v_fmac_f32_e32 v165, v171, v170
	v_fma_f32 v133, -v133, v165, v164
	v_div_fmas_f32 v133, v133, v170, v165
	v_div_fixup_f32 v157, v133, v157, v169
	v_lshlrev_b32_e32 v170, 16, v160
	v_and_b32_e32 v160, 0xffff0000, v160
	v_mul_f32_e32 v164, 0xbfb8aa3b, v170
	v_rcp_f32_e32 v133, v156
	v_mul_f32_e32 v165, 0xbfb8aa3b, v160
	v_exp_f32_e32 v164, v164
	v_exp_f32_e32 v165, v165
	v_mul_f32_e32 v156, v168, v133
	v_lshlrev_b32_e32 v168, 16, v166
	v_and_b32_e32 v169, 0xffff0000, v166
	v_pk_add_f32 v[164:165], v[164:165], 1.0 op_sel_hi:[1,0]
	v_pk_mul_f32 v[102:103], v[102:103], v[156:157]
	v_div_scale_f32 v133, s[14:15], v165, v165, v160
	v_rcp_f32_e32 v171, v133
	v_pk_fma_f32 v[104:105], v[132:133], v[168:169], v[104:105] op_sel_hi:[0,1,1]
	v_pk_mul_f32 v[156:157], v[102:103], v[102:103]
	v_fma_f32 v166, -v133, v171, 1.0
	v_fmac_f32_e32 v171, v166, v171
	v_div_scale_f32 v166, vcc, v160, v165, v160
	v_mul_f32_e32 v168, v166, v171
	v_fma_f32 v169, -v133, v168, v166
	v_fmac_f32_e32 v168, v169, v171
	v_fma_f32 v133, -v133, v168, v166
	v_div_fmas_f32 v133, v133, v171, v168
	v_div_fixup_f32 v165, v133, v165, v160
	v_lshlrev_b32_e32 v168, 16, v161
	v_and_b32_e32 v169, 0xffff0000, v161
	v_mul_f32_e32 v160, 0xbfb8aa3b, v168
	v_rcp_f32_e32 v133, v164
	v_mul_f32_e32 v161, 0xbfb8aa3b, v169
	v_exp_f32_e32 v160, v160
	v_exp_f32_e32 v161, v161
	v_mul_f32_e32 v164, v170, v133
	v_lshlrev_b32_e32 v166, 16, v167
	v_and_b32_e32 v167, 0xffff0000, v167
	v_pk_add_f32 v[160:161], v[160:161], 1.0 op_sel_hi:[1,0]
	v_pk_mul_f32 v[104:105], v[104:105], v[164:165]
	v_div_scale_f32 v133, s[14:15], v161, v161, v169
	v_rcp_f32_e32 v170, v133
	v_pk_fma_f32 v[106:107], v[132:133], v[166:167], v[106:107] op_sel_hi:[0,1,1]
	v_pk_mul_f32 v[164:165], v[104:105], v[104:105]
	v_fma_f32 v166, -v133, v170, 1.0
	v_fmac_f32_e32 v170, v166, v170
	v_div_scale_f32 v166, vcc, v169, v161, v169
	v_mul_f32_e32 v167, v166, v170
	v_fma_f32 v171, -v133, v167, v166
	v_fmac_f32_e32 v167, v171, v170
	v_fma_f32 v133, -v133, v167, v166
	v_div_fmas_f32 v133, v133, v170, v167
	v_div_fixup_f32 v161, v133, v161, v169
	v_lshlrev_b32_e32 v170, 16, v162
	v_and_b32_e32 v162, 0xffff0000, v162
	v_mul_f32_e32 v166, 0xbfb8aa3b, v170
	v_rcp_f32_e32 v133, v160
	v_mul_f32_e32 v167, 0xbfb8aa3b, v162
	v_exp_f32_e32 v166, v166
	v_exp_f32_e32 v167, v167
	v_mul_f32_e32 v160, v168, v133
	v_lshlrev_b32_e32 v168, 16, v134
	v_and_b32_e32 v169, 0xffff0000, v134
	v_pk_add_f32 v[166:167], v[166:167], 1.0 op_sel_hi:[1,0]
	v_pk_mul_f32 v[106:107], v[106:107], v[160:161]
	v_div_scale_f32 v133, s[14:15], v167, v167, v162
	v_rcp_f32_e32 v171, v133
	v_pk_fma_f32 v[108:109], v[132:133], v[168:169], v[108:109] op_sel_hi:[0,1,1]
	v_pk_mul_f32 v[160:161], v[106:107], v[106:107]
	v_fma_f32 v134, -v133, v171, 1.0
	v_fmac_f32_e32 v171, v134, v171
	v_div_scale_f32 v134, vcc, v162, v167, v162
	v_mul_f32_e32 v168, v134, v171
	v_fma_f32 v169, -v133, v168, v134
	v_fmac_f32_e32 v168, v169, v171
	v_fma_f32 v133, -v133, v168, v134
	v_div_fmas_f32 v133, v133, v171, v168
	v_div_fixup_f32 v167, v133, v167, v162
	v_lshlrev_b32_e32 v168, 16, v163
	v_and_b32_e32 v169, 0xffff0000, v163
	v_mul_f32_e32 v134, 0xbfb8aa3b, v168
	v_rcp_f32_e32 v133, v166
	v_exp_f32_e32 v162, v134
	v_mul_f32_e32 v134, 0xbfb8aa3b, v169
	v_exp_f32_e32 v163, v134
	v_mul_f32_e32 v166, v170, v133
	v_lshlrev_b32_e32 v134, 16, v135
	v_and_b32_e32 v135, 0xffff0000, v135
	v_pk_add_f32 v[162:163], v[162:163], 1.0 op_sel_hi:[1,0]
	v_pk_mul_f32 v[108:109], v[108:109], v[166:167]
	v_div_scale_f32 v133, s[14:15], v163, v163, v169
	v_rcp_f32_e32 v170, v133
	v_pk_fma_f32 v[110:111], v[132:133], v[134:135], v[110:111] op_sel_hi:[0,1,1]
	v_pk_mul_f32 v[166:167], v[108:109], v[108:109]
	v_fma_f32 v134, -v133, v170, 1.0
	v_fmac_f32_e32 v170, v134, v170
	v_div_scale_f32 v134, vcc, v169, v163, v169
	v_mul_f32_e32 v135, v134, v170
	v_fma_f32 v171, -v133, v135, v134
	v_fmac_f32_e32 v135, v171, v170
	v_fma_f32 v133, -v133, v135, v134
	v_div_fmas_f32 v133, v133, v170, v135
	v_div_fixup_f32 v135, v133, v163, v169
	v_rcp_f32_e32 v133, v162
	s_nop 0
	v_mul_f32_e32 v134, v168, v133
	v_add_f32_e32 v133, v138, v139
	v_add_f32_e32 v133, v140, v133
	v_add_f32_e32 v133, v141, v133
	v_add_f32_e32 v133, v142, v133
	v_add_f32_e32 v133, v143, v133
	v_add_f32_e32 v133, v144, v133
	v_add_f32_e32 v133, v145, v133
	v_add_f32_e32 v133, v146, v133
	v_add_f32_e32 v133, v147, v133
	v_add_f32_e32 v133, v148, v133
	v_add_f32_e32 v133, v149, v133
	v_add_f32_e32 v133, v150, v133
	v_add_f32_e32 v133, v151, v133
	v_add_f32_e32 v133, v136, v133
	v_add_f32_e32 v133, v137, v133
	v_add_f32_e32 v133, v152, v133
	v_add_f32_e32 v133, v153, v133
	v_add_f32_e32 v133, v154, v133
	v_add_f32_e32 v133, v155, v133
	v_add_f32_e32 v133, v158, v133
	v_add_f32_e32 v133, v159, v133
	v_add_f32_e32 v133, v156, v133
	v_add_f32_e32 v133, v157, v133
	v_add_f32_e32 v133, v164, v133
	v_add_f32_e32 v133, v165, v133
	v_add_f32_e32 v133, v160, v133
	v_add_f32_e32 v133, v161, v133
	v_pk_mul_f32 v[134:135], v[110:111], v[134:135]
	v_add_f32_e32 v133, v166, v133
	v_pk_mul_f32 v[110:111], v[134:135], v[134:135]
	v_add_f32_e32 v133, v167, v133
	v_add_f32_e32 v110, v110, v133
	v_add_f32_e32 v110, v111, v110
	ds_bpermute_b32 v111, v229, v110
	s_and_saveexec_b64 s[14:15], s[12:13]
	s_cbranch_execz .LBB0_1689
	s_waitcnt lgkmcnt(0)
	v_add_f32_e32 v110, v110, v111
	ds_write_b32 v231, v110
; DI float bflo(unsigned u) { return __uint_as_float(u << 16); }
; DI float bfhi(unsigned u) { return __uint_as_float(u & 0xffff0000u); }
; DI float siluf_(float x) { return x / (1.f + __expf(-x)); }
; DI float xhalf(float v) { return __shfl_xor(v, 32); }
; DI void ssd_out_phase(int wv, const Params& P, LAS unsigned char* lds) {
;     ...
;         for (int lt = 0; lt < 4; ++lt) { const size_t rr = (size_t)(row0 + lt * 32 + q); float ss = 0.f;
; #pragma unroll
;             for (int pt = 0; pt < 2; ++pt)
; #pragma unroll
;                 for (int i4 = 0; i4 < 4; ++i4) { const int p0 = h * 64 + pt * 32 + 8 * i4 + 4 * hh; const u32x2 xv = *(const u32x2*)(XS + rr * 1024 + p0), zv = *(const u32x2*)(Z + rr * 1024 + p0);
;                     const float xs4[4] = {bflo(xv.x), bfhi(xv.x), bflo(xv.y), bfhi(xv.y)}, zs4[4] = {bflo(zv.x), bfhi(zv.x), bflo(zv.y), bfhi(zv.y)};
; #pragma unroll
;                     for (int e = 0; e < 4; ++e) { const float y = (acc[pt][lt][4 * i4 + e] + xs4[e] * dsk) * siluf_(zs4[e]); acc[pt][lt][4 * i4 + e] = y; ss += y * y; } }
;             ss += xhalf(ss); if (hh == 0) ssq[wave * 128 + lt * 32 + q] = ss; }
.LBB0_1689:
	s_or_b64 exec, exec, s[14:15]
	v_or_b32_e32 v110, 32, v196
	s_waitcnt lgkmcnt(0)
	v_ashrrev_i32_e32 v111, 31, v110
	v_lshlrev_b64 v[136:137], 11, v[110:111]
	v_lshl_add_u64 v[138:139], s[28:29], 0, v[136:137]
	v_lshl_add_u64 v[142:143], s[34:35], 0, v[136:137]
	v_lshl_add_u64 v[136:137], v[138:139], 0, v[128:129]
	flat_load_dwordx2 v[140:141], v[136:137]
	v_lshl_add_u64 v[138:139], v[142:143], 0, v[128:129]
	flat_load_dwordx2 v[142:143], v[138:139]
	flat_load_dwordx2 v[146:147], v[136:137] offset:16
	flat_load_dwordx2 v[144:145], v[138:139] offset:16
	flat_load_dwordx2 v[150:151], v[136:137] offset:32
	flat_load_dwordx2 v[158:159], v[136:137] offset:48
	flat_load_dwordx2 v[148:149], v[138:139] offset:32
	flat_load_dwordx2 v[152:153], v[138:139] offset:48
	v_mov_b32_e32 v133, v132
	s_waitcnt vmcnt(0) lgkmcnt(0)
	v_lshlrev_b32_e32 v111, 16, v142
	v_lshlrev_b32_e32 v154, 16, v140
	v_and_b32_e32 v155, 0xffff0000, v140
	v_and_b32_e32 v160, 0xffff0000, v142
	v_lshlrev_b32_e32 v140, 16, v141
	v_and_b32_e32 v141, 0xffff0000, v141
	v_lshlrev_b32_e32 v161, 16, v143
	v_and_b32_e32 v162, 0xffff0000, v143
	v_lshlrev_b32_e32 v142, 16, v146
	v_and_b32_e32 v143, 0xffff0000, v146
	v_lshlrev_b32_e32 v146, 16, v144
	v_and_b32_e32 v144, 0xffff0000, v144
	v_mul_f32_e32 v156, 0xbfb8aa3b, v111
	v_pk_fma_f32 v[80:81], v[132:133], v[154:155], v[80:81]
	v_mul_f32_e32 v154, 0xbfb8aa3b, v160
	v_mul_f32_e32 v155, 0xbfb8aa3b, v161
	v_pk_fma_f32 v[82:83], v[132:133], v[140:141], v[82:83]
	v_mul_f32_e32 v157, 0xbfb8aa3b, v162
	v_mul_f32_e32 v163, 0xbfb8aa3b, v146
	v_mul_f32_e32 v164, 0xbfb8aa3b, v144
	v_exp_f32_e32 v140, v156
	v_exp_f32_e32 v141, v154
	v_exp_f32_e32 v154, v155
	v_exp_f32_e32 v155, v157
	v_exp_f32_e32 v156, v163
	v_exp_f32_e32 v157, v164
	v_pk_add_f32 v[140:141], v[140:141], 1.0 op_sel_hi:[1,0]
	v_pk_fma_f32 v[84:85], v[132:133], v[142:143], v[84:85]
	v_pk_add_f32 v[142:143], v[154:155], 1.0 op_sel_hi:[1,0]
	v_pk_add_f32 v[154:155], v[156:157], 1.0 op_sel_hi:[1,0]
	v_rcp_f32_e32 v156, v141
	s_mov_b64 vcc, s[14:15]
	v_mul_f32_e32 v141, v160, v156
	v_rcp_f32_e32 v156, v140
	s_mov_b64 vcc, s[16:17]
	v_mul_f32_e32 v140, v111, v156
	v_rcp_f32_e32 v111, v143
	s_mov_b64 vcc, s[18:19]
	v_mul_f32_e32 v143, v162, v111
	v_rcp_f32_e32 v111, v142
	s_nop 0
	v_mul_f32_e32 v142, v161, v111
	v_rcp_f32_e32 v111, v155
	s_nop 0
	v_mul_f32_e32 v155, v144, v111
	v_lshlrev_b32_e32 v160, 16, v145
	v_and_b32_e32 v161, 0xffff0000, v145
	v_mul_f32_e32 v144, 0xbfb8aa3b, v160
	v_rcp_f32_e32 v111, v154
	v_exp_f32_e32 v156, v144
	v_mul_f32_e32 v144, 0xbfb8aa3b, v161
	v_exp_f32_e32 v157, v144
	v_mul_f32_e32 v154, v146, v111
	v_pk_mul_f32 v[84:85], v[84:85], v[154:155]
	v_lshlrev_b32_e32 v146, 16, v147
	v_pk_add_f32 v[154:155], v[156:157], 1.0 op_sel_hi:[1,0]
	v_and_b32_e32 v147, 0xffff0000, v147
	v_rcp_f32_e32 v111, v155
	v_pk_fma_f32 v[86:87], v[132:133], v[146:147], v[86:87]
	v_lshlrev_b32_e32 v162, 16, v149
	v_lshlrev_b32_e32 v164, 16, v152
	v_mul_f32_e32 v147, v161, v111
	v_lshlrev_b32_e32 v161, 16, v148
	v_and_b32_e32 v148, 0xffff0000, v148
	v_mul_f32_e32 v146, 0xbfb8aa3b, v161
	v_rcp_f32_e32 v111, v154
	v_exp_f32_e32 v156, v146
	v_mul_f32_e32 v146, 0xbfb8aa3b, v148
	v_exp_f32_e32 v157, v146
	v_mul_f32_e32 v146, v160, v111
	v_and_b32_e32 v152, 0xffff0000, v152
	v_lshlrev_b32_e32 v168, 16, v153
	v_pk_add_f32 v[154:155], v[156:157], 1.0 op_sel_hi:[1,0]
	v_lshlrev_b32_e32 v156, 16, v150
	v_rcp_f32_e32 v111, v155
	v_and_b32_e32 v157, 0xffff0000, v150
	v_pk_fma_f32 v[88:89], v[132:133], v[156:157], v[88:89]
	v_pk_mul_f32 v[80:81], v[80:81], v[140:141]
	v_mul_f32_e32 v155, v148, v111
	v_and_b32_e32 v160, 0xffff0000, v149
	v_mul_f32_e32 v148, 0xbfb8aa3b, v162
	v_rcp_f32_e32 v111, v154
	v_exp_f32_e32 v156, v148
	v_mul_f32_e32 v148, 0xbfb8aa3b, v160
	v_exp_f32_e32 v157, v148
	v_mul_f32_e32 v154, v161, v111
	v_pk_mul_f32 v[88:89], v[88:89], v[154:155]
	v_lshlrev_b32_e32 v150, 16, v151
	v_pk_add_f32 v[156:157], v[156:157], 1.0 op_sel_hi:[1,0]
	v_and_b32_e32 v151, 0xffff0000, v151
	v_rcp_f32_e32 v111, v157
	v_pk_fma_f32 v[90:91], v[132:133], v[150:151], v[90:91]
	v_pk_mul_f32 v[140:141], v[80:81], v[80:81]
	v_pk_mul_f32 v[82:83], v[82:83], v[142:143]
	v_mul_f32_e32 v151, v160, v111
	v_pk_mul_f32 v[142:143], v[82:83], v[82:83]
	flat_load_dwordx2 v[154:155], v[138:139] offset:64
	v_mul_f32_e32 v150, 0xbfb8aa3b, v164
	v_rcp_f32_e32 v111, v156
	v_exp_f32_e32 v160, v150
	v_mul_f32_e32 v150, 0xbfb8aa3b, v152
	v_exp_f32_e32 v161, v150
	v_mul_f32_e32 v150, v162, v111
	v_lshlrev_b32_e32 v156, 16, v158
	v_and_b32_e32 v157, 0xffff0000, v158
	v_pk_add_f32 v[160:161], v[160:161], 1.0 op_sel_hi:[1,0]
	v_pk_fma_f32 v[92:93], v[132:133], v[156:157], v[92:93]
	v_pk_mul_f32 v[144:145], v[84:85], v[84:85]
	flat_load_dwordx2 v[156:157], v[136:137] offset:64
	v_rcp_f32_e32 v111, v161
	s_nop 0
	v_mul_f32_e32 v161, v152, v111
	v_pk_mul_f32 v[86:87], v[86:87], v[146:147]
	v_and_b32_e32 v165, 0xffff0000, v153
	v_mul_f32_e32 v152, 0xbfb8aa3b, v168
	v_rcp_f32_e32 v111, v160
	v_exp_f32_e32 v162, v152
	v_mul_f32_e32 v152, 0xbfb8aa3b, v165
	v_exp_f32_e32 v163, v152
	v_mul_f32_e32 v160, v164, v111
	v_pk_mul_f32 v[92:93], v[92:93], v[160:161]
	v_lshlrev_b32_e32 v158, 16, v159
	v_pk_add_f32 v[160:161], v[162:163], 1.0 op_sel_hi:[1,0]
	v_and_b32_e32 v159, 0xffff0000, v159
	v_rcp_f32_e32 v111, v161
	v_pk_fma_f32 v[94:95], v[132:133], v[158:159], v[94:95]
	v_pk_mul_f32 v[146:147], v[86:87], v[86:87]
	v_pk_mul_f32 v[148:149], v[88:89], v[88:89]
	v_mul_f32_e32 v161, v165, v111
	v_pk_mul_f32 v[90:91], v[90:91], v[150:151]
	flat_load_dwordx2 v[158:159], v[138:139] offset:80
	flat_load_dwordx2 v[162:163], v[138:139] offset:96
	flat_load_dwordx2 v[164:165], v[138:139] offset:112
	v_rcp_f32_e32 v111, v160
	s_nop 0
	v_mul_f32_e32 v160, v168, v111
	v_pk_mul_f32 v[94:95], v[94:95], v[160:161]
	s_waitcnt vmcnt(0) lgkmcnt(0)
; DI float bflo(unsigned u) { return __uint_as_float(u << 16); }
; DI float bfhi(unsigned u) { return __uint_as_float(u & 0xffff0000u); }
; DI float siluf_(float x) { return x / (1.f + __expf(-x)); }
; DI float xhalf(float v) { return __shfl_xor(v, 32); }
; DI void ssd_out_phase(int wv, const Params& P, LAS unsigned char* lds) {
;     ...
;         for (int lt = 0; lt < 4; ++lt) { const size_t rr = (size_t)(row0 + lt * 32 + q); float ss = 0.f;
; #pragma unroll
;             for (int pt = 0; pt < 2; ++pt)
; #pragma unroll
;                 for (int i4 = 0; i4 < 4; ++i4) { const int p0 = h * 64 + pt * 32 + 8 * i4 + 4 * hh; const u32x2 xv = *(const u32x2*)(XS + rr * 1024 + p0), zv = *(const u32x2*)(Z + rr * 1024 + p0);
;                     const float xs4[4] = {bflo(xv.x), bfhi(xv.x), bflo(xv.y), bfhi(xv.y)}, zs4[4] = {bflo(zv.x), bfhi(zv.x), bflo(zv.y), bfhi(zv.y)};
; #pragma unroll
;                     for (int e = 0; e < 4; ++e) { const float y = (acc[pt][lt][4 * i4 + e] + xs4[e] * dsk) * siluf_(zs4[e]); acc[pt][lt][4 * i4 + e] = y; ss += y * y; } }
;             ss += xhalf(ss); if (hh == 0) ssq[wave * 128 + lt * 32 + q] = ss; }
	v_lshlrev_b32_e32 v172, 16, v154
	v_and_b32_e32 v154, 0xffff0000, v154
	v_mul_f32_e32 v138, 0xbfb8aa3b, v172
	v_exp_f32_e32 v166, v138
	v_mul_f32_e32 v138, 0xbfb8aa3b, v154
	v_exp_f32_e32 v167, v138
	v_and_b32_e32 v174, 0xffff0000, v155
	v_pk_mul_f32 v[150:151], v[90:91], v[90:91]
	v_pk_mul_f32 v[152:153], v[92:93], v[92:93]
	v_pk_add_f32 v[160:161], v[166:167], 1.0 op_sel_hi:[1,0]
	flat_load_dwordx2 v[166:167], v[136:137] offset:80
	flat_load_dwordx2 v[168:169], v[136:137] offset:96
	s_nop 0
	flat_load_dwordx2 v[136:137], v[136:137] offset:112
	v_pk_mul_f32 v[138:139], v[94:95], v[94:95]
	v_rcp_f32_e32 v111, v161
	v_lshlrev_b32_e32 v170, 16, v156
	v_and_b32_e32 v171, 0xffff0000, v156
	v_pk_fma_f32 v[48:49], v[132:133], v[170:171], v[48:49]
	v_mul_f32_e32 v161, v154, v111
	v_lshlrev_b32_e32 v173, 16, v155
	v_mul_f32_e32 v154, 0xbfb8aa3b, v173
	v_rcp_f32_e32 v111, v160
	v_exp_f32_e32 v170, v154
	v_mul_f32_e32 v154, 0xbfb8aa3b, v174
	v_exp_f32_e32 v171, v154
	v_mul_f32_e32 v160, v172, v111
	v_pk_mul_f32 v[48:49], v[48:49], v[160:161]
	v_lshlrev_b32_e32 v156, 16, v157
	v_pk_add_f32 v[160:161], v[170:171], 1.0 op_sel_hi:[1,0]
	s_nop 0
	v_rcp_f32_e32 v111, v161
	v_and_b32_e32 v157, 0xffff0000, v157
	v_pk_fma_f32 v[50:51], v[132:133], v[156:157], v[50:51]
	v_pk_mul_f32 v[154:155], v[48:49], v[48:49]
	v_mul_f32_e32 v157, v174, v111
	v_lshlrev_b32_e32 v172, 16, v158
	v_and_b32_e32 v158, 0xffff0000, v158
	v_mul_f32_e32 v156, 0xbfb8aa3b, v172
	v_rcp_f32_e32 v111, v160
	v_exp_f32_e32 v170, v156
	v_mul_f32_e32 v156, 0xbfb8aa3b, v158
	v_exp_f32_e32 v171, v156
	v_mul_f32_e32 v156, v173, v111
	v_pk_mul_f32 v[50:51], v[50:51], v[156:157]
	v_pk_add_f32 v[160:161], v[170:171], 1.0 op_sel_hi:[1,0]
	s_nop 0
	s_waitcnt vmcnt(0) lgkmcnt(0)
	v_rcp_f32_e32 v111, v161
	v_lshlrev_b32_e32 v170, 16, v166
	v_and_b32_e32 v171, 0xffff0000, v166
	v_pk_fma_f32 v[52:53], v[132:133], v[170:171], v[52:53]
	v_mul_f32_e32 v161, v158, v111
	v_pk_mul_f32 v[156:157], v[50:51], v[50:51]
	v_lshlrev_b32_e32 v170, 16, v159
	v_and_b32_e32 v171, 0xffff0000, v159
	v_mul_f32_e32 v158, 0xbfb8aa3b, v170
	v_rcp_f32_e32 v111, v160
	v_mul_f32_e32 v159, 0xbfb8aa3b, v171
	v_exp_f32_e32 v158, v158
	v_exp_f32_e32 v159, v159
	v_mul_f32_e32 v160, v172, v111
	v_lshlrev_b32_e32 v166, 16, v167
	v_and_b32_e32 v167, 0xffff0000, v167
	v_pk_add_f32 v[158:159], v[158:159], 1.0 op_sel_hi:[1,0]
	s_nop 0
	v_rcp_f32_e32 v111, v159
	v_pk_fma_f32 v[54:55], v[132:133], v[166:167], v[54:55]
	v_pk_mul_f32 v[52:53], v[52:53], v[160:161]
	v_mul_f32_e32 v159, v171, v111
	v_lshlrev_b32_e32 v172, 16, v162
	v_and_b32_e32 v162, 0xffff0000, v162
	v_mul_f32_e32 v166, 0xbfb8aa3b, v172
	v_rcp_f32_e32 v111, v158
	v_mul_f32_e32 v167, 0xbfb8aa3b, v162
	v_exp_f32_e32 v166, v166
	v_exp_f32_e32 v167, v167
	v_mul_f32_e32 v158, v170, v111
	v_lshlrev_b32_e32 v170, 16, v168
	v_and_b32_e32 v171, 0xffff0000, v168
	v_pk_add_f32 v[166:167], v[166:167], 1.0 op_sel_hi:[1,0]
	s_nop 0
	v_rcp_f32_e32 v111, v167
	v_pk_fma_f32 v[56:57], v[132:133], v[170:171], v[56:57]
	v_pk_mul_f32 v[160:161], v[52:53], v[52:53]
	v_pk_mul_f32 v[54:55], v[54:55], v[158:159]
	v_mul_f32_e32 v167, v162, v111
	v_pk_mul_f32 v[158:159], v[54:55], v[54:55]
	v_lshlrev_b32_e32 v170, 16, v163
	v_and_b32_e32 v171, 0xffff0000, v163
	v_mul_f32_e32 v162, 0xbfb8aa3b, v170
	v_rcp_f32_e32 v111, v166
	v_mul_f32_e32 v163, 0xbfb8aa3b, v171
	v_exp_f32_e32 v162, v162
	v_exp_f32_e32 v163, v163
	v_mul_f32_e32 v166, v172, v111
	v_lshlrev_b32_e32 v168, 16, v169
	v_and_b32_e32 v169, 0xffff0000, v169
	v_pk_add_f32 v[162:163], v[162:163], 1.0 op_sel_hi:[1,0]
	s_nop 0
	v_rcp_f32_e32 v111, v163
	v_pk_fma_f32 v[58:59], v[132:133], v[168:169], v[58:59]
	v_pk_mul_f32 v[56:57], v[56:57], v[166:167]
	v_mul_f32_e32 v163, v171, v111
	v_lshlrev_b32_e32 v172, 16, v164
	v_and_b32_e32 v164, 0xffff0000, v164
	v_mul_f32_e32 v168, 0xbfb8aa3b, v172
	v_rcp_f32_e32 v111, v162
	v_mul_f32_e32 v169, 0xbfb8aa3b, v164
	v_exp_f32_e32 v168, v168
	v_exp_f32_e32 v169, v169
	v_mul_f32_e32 v162, v170, v111
	v_lshlrev_b32_e32 v170, 16, v136
	v_and_b32_e32 v171, 0xffff0000, v136
	v_pk_add_f32 v[168:169], v[168:169], 1.0 op_sel_hi:[1,0]
	s_nop 0
	v_rcp_f32_e32 v111, v169
	v_pk_fma_f32 v[60:61], v[132:133], v[170:171], v[60:61]
	v_pk_mul_f32 v[166:167], v[56:57], v[56:57]
	v_pk_mul_f32 v[58:59], v[58:59], v[162:163]
	v_mul_f32_e32 v169, v164, v111
	v_pk_mul_f32 v[162:163], v[58:59], v[58:59]
	v_lshlrev_b32_e32 v170, 16, v165
	v_and_b32_e32 v171, 0xffff0000, v165
	v_mul_f32_e32 v136, 0xbfb8aa3b, v170
	v_rcp_f32_e32 v111, v168
	v_exp_f32_e32 v164, v136
	v_mul_f32_e32 v136, 0xbfb8aa3b, v171
	v_exp_f32_e32 v165, v136
	v_mul_f32_e32 v168, v172, v111
	v_lshlrev_b32_e32 v136, 16, v137
	v_and_b32_e32 v137, 0xffff0000, v137
	v_pk_add_f32 v[164:165], v[164:165], 1.0 op_sel_hi:[1,0]
	s_nop 0
	v_rcp_f32_e32 v111, v165
	v_pk_fma_f32 v[62:63], v[132:133], v[136:137], v[62:63]
	v_pk_mul_f32 v[60:61], v[60:61], v[168:169]
	v_mul_f32_e32 v137, v171, v111
	v_rcp_f32_e32 v111, v164
	v_pk_mul_f32 v[168:169], v[60:61], v[60:61]
	v_mul_f32_e32 v136, v170, v111
	v_add_f32_e32 v111, v140, v141
	v_add_f32_e32 v111, v142, v111
	v_add_f32_e32 v111, v143, v111
	v_add_f32_e32 v111, v144, v111
	v_add_f32_e32 v111, v145, v111
	v_add_f32_e32 v111, v146, v111
	v_add_f32_e32 v111, v147, v111
	v_add_f32_e32 v111, v148, v111
	v_add_f32_e32 v111, v149, v111
	v_add_f32_e32 v111, v150, v111
	v_add_f32_e32 v111, v151, v111
	v_add_f32_e32 v111, v152, v111
	v_add_f32_e32 v111, v153, v111
	v_add_f32_e32 v111, v138, v111
	v_add_f32_e32 v111, v139, v111
	v_add_f32_e32 v111, v154, v111
	v_add_f32_e32 v111, v155, v111
	v_add_f32_e32 v111, v156, v111
	v_add_f32_e32 v111, v157, v111
	v_add_f32_e32 v111, v160, v111
	v_add_f32_e32 v111, v161, v111
	v_add_f32_e32 v111, v158, v111
	v_add_f32_e32 v111, v159, v111
	v_add_f32_e32 v111, v166, v111
	v_add_f32_e32 v111, v167, v111
	v_add_f32_e32 v111, v162, v111
	v_add_f32_e32 v111, v163, v111
	v_pk_mul_f32 v[136:137], v[62:63], v[136:137]
	v_add_f32_e32 v111, v168, v111
	v_pk_mul_f32 v[62:63], v[136:137], v[136:137]
	v_add_f32_e32 v111, v169, v111
	v_add_f32_e32 v62, v62, v111
	v_add_f32_e32 v62, v63, v62
	ds_bpermute_b32 v63, v229, v62
	s_and_saveexec_b64 s[14:15], s[12:13]
	s_cbranch_execz .LBB0_1691
	s_waitcnt lgkmcnt(0)
	v_add_f32_e32 v62, v62, v63
	ds_write_b32 v231, v62 offset:128
; DI float bflo(unsigned u) { return __uint_as_float(u << 16); }
; DI float bfhi(unsigned u) { return __uint_as_float(u & 0xffff0000u); }
; DI float siluf_(float x) { return x / (1.f + __expf(-x)); }
; DI float xhalf(float v) { return __shfl_xor(v, 32); }
; DI void ssd_out_phase(int wv, const Params& P, LAS unsigned char* lds) {
;     ...
;         for (int lt = 0; lt < 4; ++lt) { const size_t rr = (size_t)(row0 + lt * 32 + q); float ss = 0.f;
; #pragma unroll
;             for (int pt = 0; pt < 2; ++pt)
; #pragma unroll
;                 for (int i4 = 0; i4 < 4; ++i4) { const int p0 = h * 64 + pt * 32 + 8 * i4 + 4 * hh; const u32x2 xv = *(const u32x2*)(XS + rr * 1024 + p0), zv = *(const u32x2*)(Z + rr * 1024 + p0);
;                     const float xs4[4] = {bflo(xv.x), bfhi(xv.x), bflo(xv.y), bfhi(xv.y)}, zs4[4] = {bflo(zv.x), bfhi(zv.x), bflo(zv.y), bfhi(zv.y)};
; #pragma unroll
;                     for (int e = 0; e < 4; ++e) { const float y = (acc[pt][lt][4 * i4 + e] + xs4[e] * dsk) * siluf_(zs4[e]); acc[pt][lt][4 * i4 + e] = y; ss += y * y; } }
;             ss += xhalf(ss); if (hh == 0) ssq[wave * 128 + lt * 32 + q] = ss; }
.LBB0_1691:
	s_or_b64 exec, exec, s[14:15]
	v_or_b32_e32 v62, 64, v196
	s_waitcnt lgkmcnt(0)
	v_ashrrev_i32_e32 v63, 31, v62
	v_lshlrev_b64 v[138:139], 11, v[62:63]
	v_lshl_add_u64 v[140:141], s[28:29], 0, v[138:139]
	v_lshl_add_u64 v[144:145], s[34:35], 0, v[138:139]
	v_lshl_add_u64 v[138:139], v[140:141], 0, v[128:129]
	flat_load_dwordx2 v[142:143], v[138:139]
	v_lshl_add_u64 v[140:141], v[144:145], 0, v[128:129]
	flat_load_dwordx2 v[144:145], v[140:141]
	flat_load_dwordx2 v[148:149], v[138:139] offset:16
	flat_load_dwordx2 v[146:147], v[140:141] offset:16
	flat_load_dwordx2 v[152:153], v[138:139] offset:32
	flat_load_dwordx2 v[160:161], v[138:139] offset:48
	flat_load_dwordx2 v[150:151], v[140:141] offset:32
	flat_load_dwordx2 v[154:155], v[140:141] offset:48
	s_waitcnt vmcnt(0) lgkmcnt(0)
	v_lshlrev_b32_e32 v63, 16, v144
	v_and_b32_e32 v111, 0xffff0000, v144
	v_lshlrev_b32_e32 v162, 16, v145
	v_and_b32_e32 v163, 0xffff0000, v145
	v_lshlrev_b32_e32 v156, 16, v142
	v_and_b32_e32 v157, 0xffff0000, v142
	v_lshlrev_b32_e32 v142, 16, v143
	v_and_b32_e32 v143, 0xffff0000, v143
	v_lshlrev_b32_e32 v144, 16, v148
	v_and_b32_e32 v145, 0xffff0000, v148
	v_lshlrev_b32_e32 v148, 16, v146
	v_and_b32_e32 v146, 0xffff0000, v146
	v_mul_f32_e32 v158, 0xbfb8aa3b, v63
	v_pk_fma_f32 v[64:65], v[132:133], v[156:157], v[64:65]
	v_mul_f32_e32 v156, 0xbfb8aa3b, v111
	v_mul_f32_e32 v157, 0xbfb8aa3b, v162
	v_pk_fma_f32 v[66:67], v[132:133], v[142:143], v[66:67]
	v_mul_f32_e32 v159, 0xbfb8aa3b, v163
	v_mul_f32_e32 v164, 0xbfb8aa3b, v148
	v_mul_f32_e32 v165, 0xbfb8aa3b, v146
	v_exp_f32_e32 v142, v158
	v_exp_f32_e32 v143, v156
	v_exp_f32_e32 v156, v157
	v_exp_f32_e32 v157, v159
	v_exp_f32_e32 v158, v164
	v_exp_f32_e32 v159, v165
	v_pk_add_f32 v[142:143], v[142:143], 1.0 op_sel_hi:[1,0]
	v_pk_fma_f32 v[68:69], v[132:133], v[144:145], v[68:69]
	v_pk_add_f32 v[144:145], v[156:157], 1.0 op_sel_hi:[1,0]
	v_pk_add_f32 v[156:157], v[158:159], 1.0 op_sel_hi:[1,0]
	v_rcp_f32_e32 v158, v143
	s_mov_b64 vcc, s[14:15]
	v_mul_f32_e32 v143, v111, v158
	v_rcp_f32_e32 v111, v142
	s_mov_b64 vcc, s[16:17]
	v_mul_f32_e32 v142, v63, v111
	v_rcp_f32_e32 v63, v145
	s_mov_b64 vcc, s[18:19]
	v_mul_f32_e32 v145, v163, v63
	v_rcp_f32_e32 v63, v144
	s_nop 0
	v_mul_f32_e32 v144, v162, v63
	v_rcp_f32_e32 v63, v157
	s_nop 0
	v_mul_f32_e32 v157, v146, v63
	v_lshlrev_b32_e32 v111, 16, v147
	v_and_b32_e32 v162, 0xffff0000, v147
	v_mul_f32_e32 v146, 0xbfb8aa3b, v111
	v_rcp_f32_e32 v63, v156
	v_exp_f32_e32 v158, v146
	v_mul_f32_e32 v146, 0xbfb8aa3b, v162
	v_exp_f32_e32 v159, v146
	v_mul_f32_e32 v156, v148, v63
	v_pk_mul_f32 v[68:69], v[68:69], v[156:157]
	v_lshlrev_b32_e32 v148, 16, v149
	v_pk_add_f32 v[156:157], v[158:159], 1.0 op_sel_hi:[1,0]
	v_and_b32_e32 v149, 0xffff0000, v149
	v_rcp_f32_e32 v63, v157
	v_pk_fma_f32 v[70:71], v[132:133], v[148:149], v[70:71]
	v_and_b32_e32 v163, 0xffff0000, v151
	v_lshlrev_b32_e32 v166, 16, v154
	v_mul_f32_e32 v149, v162, v63
	v_lshlrev_b32_e32 v162, 16, v150
	v_and_b32_e32 v150, 0xffff0000, v150
	v_mul_f32_e32 v148, 0xbfb8aa3b, v162
	v_rcp_f32_e32 v63, v156
	v_exp_f32_e32 v158, v148
	v_mul_f32_e32 v148, 0xbfb8aa3b, v150
	v_exp_f32_e32 v159, v148
	v_mul_f32_e32 v148, v111, v63
	v_and_b32_e32 v154, 0xffff0000, v154
	v_and_b32_e32 v167, 0xffff0000, v155
	v_pk_add_f32 v[156:157], v[158:159], 1.0 op_sel_hi:[1,0]
	v_lshlrev_b32_e32 v158, 16, v152
	v_rcp_f32_e32 v63, v157
	v_and_b32_e32 v159, 0xffff0000, v152
	v_pk_fma_f32 v[72:73], v[132:133], v[158:159], v[72:73]
	v_pk_mul_f32 v[64:65], v[64:65], v[142:143]
	v_mul_f32_e32 v157, v150, v63
	v_pk_mul_f32 v[142:143], v[64:65], v[64:65]
	v_lshlrev_b32_e32 v111, 16, v151
	v_mul_f32_e32 v150, 0xbfb8aa3b, v111
	v_rcp_f32_e32 v63, v156
	v_exp_f32_e32 v158, v150
	v_mul_f32_e32 v150, 0xbfb8aa3b, v163
	v_exp_f32_e32 v159, v150
	v_mul_f32_e32 v156, v162, v63
	v_pk_mul_f32 v[72:73], v[72:73], v[156:157]
	v_lshlrev_b32_e32 v152, 16, v153
	v_pk_add_f32 v[158:159], v[158:159], 1.0 op_sel_hi:[1,0]
	v_and_b32_e32 v153, 0xffff0000, v153
	v_rcp_f32_e32 v63, v159
	v_pk_fma_f32 v[74:75], v[132:133], v[152:153], v[74:75]
	v_pk_mul_f32 v[66:67], v[66:67], v[144:145]
	v_pk_mul_f32 v[146:147], v[68:69], v[68:69]
	v_mul_f32_e32 v153, v163, v63
	v_pk_mul_f32 v[144:145], v[66:67], v[66:67]
	flat_load_dwordx2 v[156:157], v[140:141] offset:64
	v_mul_f32_e32 v152, 0xbfb8aa3b, v166
	v_rcp_f32_e32 v63, v158
	v_exp_f32_e32 v162, v152
	v_mul_f32_e32 v152, 0xbfb8aa3b, v154
	v_exp_f32_e32 v163, v152
	v_mul_f32_e32 v152, v111, v63
	v_lshlrev_b32_e32 v158, 16, v160
	v_and_b32_e32 v159, 0xffff0000, v160
	v_pk_add_f32 v[162:163], v[162:163], 1.0 op_sel_hi:[1,0]
	v_pk_fma_f32 v[76:77], v[132:133], v[158:159], v[76:77]
	v_pk_mul_f32 v[70:71], v[70:71], v[148:149]
	flat_load_dwordx2 v[158:159], v[138:139] offset:64
	v_rcp_f32_e32 v63, v163
	s_nop 0
	v_mul_f32_e32 v163, v154, v63
	v_pk_mul_f32 v[148:149], v[70:71], v[70:71]
	v_lshlrev_b32_e32 v111, 16, v155
	v_mul_f32_e32 v154, 0xbfb8aa3b, v111
	v_rcp_f32_e32 v63, v162
	v_exp_f32_e32 v164, v154
	v_mul_f32_e32 v154, 0xbfb8aa3b, v167
	v_exp_f32_e32 v165, v154
	v_mul_f32_e32 v162, v166, v63
	v_pk_mul_f32 v[76:77], v[76:77], v[162:163]
	v_lshlrev_b32_e32 v160, 16, v161
	v_pk_add_f32 v[162:163], v[164:165], 1.0 op_sel_hi:[1,0]
	v_and_b32_e32 v161, 0xffff0000, v161
	v_rcp_f32_e32 v63, v163
	v_pk_fma_f32 v[78:79], v[132:133], v[160:161], v[78:79]
	v_pk_mul_f32 v[150:151], v[72:73], v[72:73]
	v_pk_mul_f32 v[74:75], v[74:75], v[152:153]
	v_mul_f32_e32 v163, v167, v63
	v_pk_mul_f32 v[152:153], v[74:75], v[74:75]
	flat_load_dwordx2 v[160:161], v[140:141] offset:80
	flat_load_dwordx2 v[164:165], v[140:141] offset:96
	flat_load_dwordx2 v[166:167], v[140:141] offset:112
	v_rcp_f32_e32 v63, v162
	s_nop 0
	v_mul_f32_e32 v162, v111, v63
	v_pk_mul_f32 v[78:79], v[78:79], v[162:163]
	s_waitcnt vmcnt(0) lgkmcnt(0)
; DI float bflo(unsigned u) { return __uint_as_float(u << 16); }
; DI float bfhi(unsigned u) { return __uint_as_float(u & 0xffff0000u); }
; DI float siluf_(float x) { return x / (1.f + __expf(-x)); }
; DI float xhalf(float v) { return __shfl_xor(v, 32); }
; DI void ssd_out_phase(int wv, const Params& P, LAS unsigned char* lds) {
;     ...
;         for (int lt = 0; lt < 4; ++lt) { const size_t rr = (size_t)(row0 + lt * 32 + q); float ss = 0.f;
; #pragma unroll
;             for (int pt = 0; pt < 2; ++pt)
; #pragma unroll
;                 for (int i4 = 0; i4 < 4; ++i4) { const int p0 = h * 64 + pt * 32 + 8 * i4 + 4 * hh; const u32x2 xv = *(const u32x2*)(XS + rr * 1024 + p0), zv = *(const u32x2*)(Z + rr * 1024 + p0);
;                     const float xs4[4] = {bflo(xv.x), bfhi(xv.x), bflo(xv.y), bfhi(xv.y)}, zs4[4] = {bflo(zv.x), bfhi(zv.x), bflo(zv.y), bfhi(zv.y)};
; #pragma unroll
;                     for (int e = 0; e < 4; ++e) { const float y = (acc[pt][lt][4 * i4 + e] + xs4[e] * dsk) * siluf_(zs4[e]); acc[pt][lt][4 * i4 + e] = y; ss += y * y; } }
;             ss += xhalf(ss); if (hh == 0) ssq[wave * 128 + lt * 32 + q] = ss; }
	v_lshlrev_b32_e32 v174, 16, v156
	v_and_b32_e32 v156, 0xffff0000, v156
	v_mul_f32_e32 v140, 0xbfb8aa3b, v174
	v_exp_f32_e32 v168, v140
	v_mul_f32_e32 v140, 0xbfb8aa3b, v156
	v_exp_f32_e32 v169, v140
	v_and_b32_e32 v175, 0xffff0000, v157
	v_pk_mul_f32 v[154:155], v[76:77], v[76:77]
	v_pk_mul_f32 v[140:141], v[78:79], v[78:79]
	v_pk_add_f32 v[162:163], v[168:169], 1.0 op_sel_hi:[1,0]
	flat_load_dwordx2 v[168:169], v[138:139] offset:80
	flat_load_dwordx2 v[170:171], v[138:139] offset:96
	s_nop 0
	flat_load_dwordx2 v[138:139], v[138:139] offset:112
	v_rcp_f32_e32 v63, v163
	v_lshlrev_b32_e32 v172, 16, v158
	v_and_b32_e32 v173, 0xffff0000, v158
	v_pk_fma_f32 v[32:33], v[132:133], v[172:173], v[32:33]
	v_mul_f32_e32 v163, v156, v63
	v_lshlrev_b32_e32 v111, 16, v157
	v_mul_f32_e32 v156, 0xbfb8aa3b, v111
	v_rcp_f32_e32 v63, v162
	v_exp_f32_e32 v172, v156
	v_mul_f32_e32 v156, 0xbfb8aa3b, v175
	v_exp_f32_e32 v173, v156
	v_mul_f32_e32 v162, v174, v63
	v_pk_mul_f32 v[32:33], v[32:33], v[162:163]
	v_lshlrev_b32_e32 v158, 16, v159
	v_pk_add_f32 v[162:163], v[172:173], 1.0 op_sel_hi:[1,0]
	s_nop 0
	v_rcp_f32_e32 v63, v163
	v_and_b32_e32 v159, 0xffff0000, v159
	v_pk_fma_f32 v[34:35], v[132:133], v[158:159], v[34:35]
	v_pk_mul_f32 v[156:157], v[32:33], v[32:33]
	v_mul_f32_e32 v159, v175, v63
	v_lshlrev_b32_e32 v174, 16, v160
	v_and_b32_e32 v160, 0xffff0000, v160
	v_mul_f32_e32 v158, 0xbfb8aa3b, v174
	v_rcp_f32_e32 v63, v162
	v_exp_f32_e32 v172, v158
	v_mul_f32_e32 v158, 0xbfb8aa3b, v160
	v_exp_f32_e32 v173, v158
	v_mul_f32_e32 v158, v111, v63
	v_pk_mul_f32 v[34:35], v[34:35], v[158:159]
	v_pk_add_f32 v[162:163], v[172:173], 1.0 op_sel_hi:[1,0]
	s_nop 0
	s_waitcnt vmcnt(0) lgkmcnt(0)
	v_rcp_f32_e32 v63, v163
	v_lshlrev_b32_e32 v172, 16, v168
	v_and_b32_e32 v173, 0xffff0000, v168
	v_pk_fma_f32 v[36:37], v[132:133], v[172:173], v[36:37]
	v_mul_f32_e32 v163, v160, v63
	v_and_b32_e32 v172, 0xffff0000, v161
	v_lshlrev_b32_e32 v111, 16, v161
	v_mul_f32_e32 v160, 0xbfb8aa3b, v111
	v_rcp_f32_e32 v63, v162
	v_mul_f32_e32 v161, 0xbfb8aa3b, v172
	v_exp_f32_e32 v160, v160
	v_exp_f32_e32 v161, v161
	v_mul_f32_e32 v162, v174, v63
	v_lshlrev_b32_e32 v168, 16, v169
	v_and_b32_e32 v169, 0xffff0000, v169
	v_pk_add_f32 v[160:161], v[160:161], 1.0 op_sel_hi:[1,0]
	s_nop 0
	v_rcp_f32_e32 v63, v161
	v_pk_fma_f32 v[38:39], v[132:133], v[168:169], v[38:39]
	v_pk_mul_f32 v[158:159], v[34:35], v[34:35]
	v_pk_mul_f32 v[36:37], v[36:37], v[162:163]
	v_mul_f32_e32 v161, v172, v63
	v_and_b32_e32 v173, 0xffff0000, v170
	v_lshlrev_b32_e32 v174, 16, v164
	v_and_b32_e32 v164, 0xffff0000, v164
	v_mul_f32_e32 v168, 0xbfb8aa3b, v174
	v_rcp_f32_e32 v63, v160
	v_mul_f32_e32 v169, 0xbfb8aa3b, v164
	v_exp_f32_e32 v168, v168
	v_exp_f32_e32 v169, v169
	v_mul_f32_e32 v160, v111, v63
	v_lshlrev_b32_e32 v172, 16, v170
	v_pk_fma_f32 v[40:41], v[132:133], v[172:173], v[40:41]
	v_pk_add_f32 v[168:169], v[168:169], 1.0 op_sel_hi:[1,0]
	s_nop 0
	v_rcp_f32_e32 v63, v169
	v_pk_mul_f32 v[162:163], v[36:37], v[36:37]
	v_pk_mul_f32 v[38:39], v[38:39], v[160:161]
	v_mul_f32_e32 v169, v164, v63
	v_and_b32_e32 v172, 0xffff0000, v165
	v_lshlrev_b32_e32 v111, 16, v165
	v_mul_f32_e32 v164, 0xbfb8aa3b, v111
	v_rcp_f32_e32 v63, v168
	v_mul_f32_e32 v165, 0xbfb8aa3b, v172
	v_exp_f32_e32 v164, v164
	v_exp_f32_e32 v165, v165
	v_mul_f32_e32 v168, v174, v63
	v_lshlrev_b32_e32 v170, 16, v171
	v_and_b32_e32 v171, 0xffff0000, v171
	v_pk_add_f32 v[164:165], v[164:165], 1.0 op_sel_hi:[1,0]
	s_nop 0
	v_rcp_f32_e32 v63, v165
	v_pk_fma_f32 v[42:43], v[132:133], v[170:171], v[42:43]
	v_pk_mul_f32 v[160:161], v[38:39], v[38:39]
	v_pk_mul_f32 v[40:41], v[40:41], v[168:169]
	v_mul_f32_e32 v165, v172, v63
	v_and_b32_e32 v173, 0xffff0000, v138
	v_lshlrev_b32_e32 v174, 16, v166
	v_and_b32_e32 v166, 0xffff0000, v166
	v_mul_f32_e32 v170, 0xbfb8aa3b, v174
	v_rcp_f32_e32 v63, v164
	v_mul_f32_e32 v171, 0xbfb8aa3b, v166
	v_exp_f32_e32 v170, v170
	v_exp_f32_e32 v171, v171
	v_mul_f32_e32 v164, v111, v63
	v_lshlrev_b32_e32 v172, 16, v138
	v_pk_fma_f32 v[44:45], v[132:133], v[172:173], v[44:45]
	v_pk_add_f32 v[170:171], v[170:171], 1.0 op_sel_hi:[1,0]
	s_nop 0
	v_rcp_f32_e32 v63, v171
	v_pk_mul_f32 v[168:169], v[40:41], v[40:41]
	v_pk_mul_f32 v[42:43], v[42:43], v[164:165]
	v_mul_f32_e32 v171, v166, v63
	v_and_b32_e32 v172, 0xffff0000, v167
	v_lshlrev_b32_e32 v111, 16, v167
	v_mul_f32_e32 v138, 0xbfb8aa3b, v111
	v_rcp_f32_e32 v63, v170
	v_exp_f32_e32 v166, v138
	v_mul_f32_e32 v138, 0xbfb8aa3b, v172
	v_exp_f32_e32 v167, v138
	v_mul_f32_e32 v170, v174, v63
	v_lshlrev_b32_e32 v138, 16, v139
	v_and_b32_e32 v139, 0xffff0000, v139
	v_pk_add_f32 v[166:167], v[166:167], 1.0 op_sel_hi:[1,0]
	s_nop 0
	v_rcp_f32_e32 v63, v167
	v_pk_fma_f32 v[46:47], v[132:133], v[138:139], v[46:47]
	v_pk_mul_f32 v[164:165], v[42:43], v[42:43]
	v_pk_mul_f32 v[44:45], v[44:45], v[170:171]
	v_mul_f32_e32 v139, v172, v63
	v_rcp_f32_e32 v63, v166
	v_pk_mul_f32 v[170:171], v[44:45], v[44:45]
	v_mul_f32_e32 v138, v111, v63
	v_add_f32_e32 v63, v142, v143
	v_add_f32_e32 v63, v144, v63
	v_add_f32_e32 v63, v145, v63
	v_add_f32_e32 v63, v146, v63
	v_add_f32_e32 v63, v147, v63
	v_add_f32_e32 v63, v148, v63
	v_add_f32_e32 v63, v149, v63
	v_add_f32_e32 v63, v150, v63
	v_add_f32_e32 v63, v151, v63
	v_add_f32_e32 v63, v152, v63
	v_add_f32_e32 v63, v153, v63
	v_add_f32_e32 v63, v154, v63
	v_add_f32_e32 v63, v155, v63
	v_add_f32_e32 v63, v140, v63
	v_add_f32_e32 v63, v141, v63
	v_add_f32_e32 v63, v156, v63
	v_add_f32_e32 v63, v157, v63
	v_add_f32_e32 v63, v158, v63
	v_add_f32_e32 v63, v159, v63
	v_add_f32_e32 v63, v162, v63
	v_add_f32_e32 v63, v163, v63
	v_add_f32_e32 v63, v160, v63
	v_add_f32_e32 v63, v161, v63
	v_add_f32_e32 v63, v168, v63
	v_add_f32_e32 v63, v169, v63
	v_add_f32_e32 v63, v164, v63
	v_add_f32_e32 v63, v165, v63
	v_pk_mul_f32 v[138:139], v[46:47], v[138:139]
	v_add_f32_e32 v63, v170, v63
	v_pk_mul_f32 v[46:47], v[138:139], v[138:139]
	v_add_f32_e32 v63, v171, v63
	v_add_f32_e32 v46, v46, v63
	v_add_f32_e32 v46, v47, v46
	ds_bpermute_b32 v47, v229, v46
	s_and_saveexec_b64 s[14:15], s[12:13]
	s_cbranch_execz .LBB0_1693
	s_waitcnt lgkmcnt(0)
	v_add_f32_e32 v46, v46, v47
	ds_write_b32 v231, v46 offset:256
; DI float bflo(unsigned u) { return __uint_as_float(u << 16); }
; DI float bfhi(unsigned u) { return __uint_as_float(u & 0xffff0000u); }
; DI float siluf_(float x) { return x / (1.f + __expf(-x)); }
; DI float xhalf(float v) { return __shfl_xor(v, 32); }
; DI void ssd_out_phase(int wv, const Params& P, LAS unsigned char* lds) {
;     ...
;         for (int lt = 0; lt < 4; ++lt) { const size_t rr = (size_t)(row0 + lt * 32 + q); float ss = 0.f;
; #pragma unroll
;             for (int pt = 0; pt < 2; ++pt)
; #pragma unroll
;                 for (int i4 = 0; i4 < 4; ++i4) { const int p0 = h * 64 + pt * 32 + 8 * i4 + 4 * hh; const u32x2 xv = *(const u32x2*)(XS + rr * 1024 + p0), zv = *(const u32x2*)(Z + rr * 1024 + p0);
;                     const float xs4[4] = {bflo(xv.x), bfhi(xv.x), bflo(xv.y), bfhi(xv.y)}, zs4[4] = {bflo(zv.x), bfhi(zv.x), bflo(zv.y), bfhi(zv.y)};
; #pragma unroll
;                     for (int e = 0; e < 4; ++e) { const float y = (acc[pt][lt][4 * i4 + e] + xs4[e] * dsk) * siluf_(zs4[e]); acc[pt][lt][4 * i4 + e] = y; ss += y * y; } }
;             ss += xhalf(ss); if (hh == 0) ssq[wave * 128 + lt * 32 + q] = ss; }
.LBB0_1693:
	s_or_b64 exec, exec, s[14:15]
	v_or_b32_e32 v46, 0x60, v196
	s_waitcnt lgkmcnt(0)
	v_ashrrev_i32_e32 v47, 31, v46
	v_lshlrev_b64 v[140:141], 11, v[46:47]
	v_lshl_add_u64 v[142:143], s[28:29], 0, v[140:141]
	v_lshl_add_u64 v[146:147], s[34:35], 0, v[140:141]
	v_lshl_add_u64 v[140:141], v[142:143], 0, v[128:129]
	flat_load_dwordx2 v[144:145], v[140:141]
	v_lshl_add_u64 v[142:143], v[146:147], 0, v[128:129]
	flat_load_dwordx2 v[146:147], v[142:143]
	flat_load_dwordx2 v[150:151], v[140:141] offset:16
	flat_load_dwordx2 v[148:149], v[142:143] offset:16
	flat_load_dwordx2 v[154:155], v[140:141] offset:32
	flat_load_dwordx2 v[162:163], v[140:141] offset:48
	flat_load_dwordx2 v[152:153], v[142:143] offset:32
	flat_load_dwordx2 v[156:157], v[142:143] offset:48
	s_waitcnt vmcnt(0) lgkmcnt(0)
	v_lshlrev_b32_e32 v47, 16, v146
	v_and_b32_e32 v63, 0xffff0000, v146
	v_lshlrev_b32_e32 v111, 16, v147
	v_and_b32_e32 v164, 0xffff0000, v147
	v_lshlrev_b32_e32 v158, 16, v144
	v_and_b32_e32 v159, 0xffff0000, v144
	v_lshlrev_b32_e32 v144, 16, v145
	v_and_b32_e32 v145, 0xffff0000, v145
	v_lshlrev_b32_e32 v146, 16, v150
	v_and_b32_e32 v147, 0xffff0000, v150
	v_lshlrev_b32_e32 v150, 16, v148
	v_and_b32_e32 v148, 0xffff0000, v148
	v_mul_f32_e32 v160, 0xbfb8aa3b, v47
	v_pk_fma_f32 v[16:17], v[132:133], v[158:159], v[16:17]
	v_mul_f32_e32 v158, 0xbfb8aa3b, v63
	v_mul_f32_e32 v159, 0xbfb8aa3b, v111
	v_pk_fma_f32 v[18:19], v[132:133], v[144:145], v[18:19]
	v_mul_f32_e32 v161, 0xbfb8aa3b, v164
	v_mul_f32_e32 v165, 0xbfb8aa3b, v150
	v_mul_f32_e32 v166, 0xbfb8aa3b, v148
	v_exp_f32_e32 v144, v160
	v_exp_f32_e32 v145, v158
	v_exp_f32_e32 v158, v159
	v_exp_f32_e32 v159, v161
	v_exp_f32_e32 v160, v165
	v_exp_f32_e32 v161, v166
	v_pk_add_f32 v[144:145], v[144:145], 1.0 op_sel_hi:[1,0]
	v_pk_fma_f32 v[20:21], v[132:133], v[146:147], v[20:21]
	v_pk_add_f32 v[146:147], v[158:159], 1.0 op_sel_hi:[1,0]
	v_pk_add_f32 v[158:159], v[160:161], 1.0 op_sel_hi:[1,0]
	v_rcp_f32_e32 v160, v145
	s_mov_b64 vcc, s[14:15]
	v_mul_f32_e32 v145, v63, v160
	v_rcp_f32_e32 v63, v144
	s_mov_b64 vcc, s[16:17]
	v_mul_f32_e32 v144, v47, v63
	v_rcp_f32_e32 v47, v147
	s_mov_b64 vcc, s[18:19]
	v_mul_f32_e32 v147, v164, v47
	v_rcp_f32_e32 v47, v146
	s_nop 0
	v_mul_f32_e32 v146, v111, v47
	v_rcp_f32_e32 v47, v159
	s_nop 0
	v_mul_f32_e32 v159, v148, v47
	v_lshlrev_b32_e32 v63, 16, v149
	v_and_b32_e32 v111, 0xffff0000, v149
	v_mul_f32_e32 v148, 0xbfb8aa3b, v63
	v_rcp_f32_e32 v47, v158
	v_exp_f32_e32 v160, v148
	v_mul_f32_e32 v148, 0xbfb8aa3b, v111
	v_exp_f32_e32 v161, v148
	v_mul_f32_e32 v158, v150, v47
	v_pk_mul_f32 v[20:21], v[20:21], v[158:159]
	v_lshlrev_b32_e32 v150, 16, v151
	v_pk_add_f32 v[158:159], v[160:161], 1.0 op_sel_hi:[1,0]
	v_and_b32_e32 v151, 0xffff0000, v151
	v_rcp_f32_e32 v47, v159
	v_pk_fma_f32 v[22:23], v[132:133], v[150:151], v[22:23]
	v_and_b32_e32 v164, 0xffff0000, v153
	v_and_b32_e32 v168, 0xffff0000, v157
	v_mul_f32_e32 v151, v111, v47
	v_pk_mul_f32 v[16:17], v[16:17], v[144:145]
	v_lshlrev_b32_e32 v111, 16, v152
	v_and_b32_e32 v152, 0xffff0000, v152
	v_mul_f32_e32 v150, 0xbfb8aa3b, v111
	v_rcp_f32_e32 v47, v158
	v_exp_f32_e32 v160, v150
	v_mul_f32_e32 v150, 0xbfb8aa3b, v152
	v_exp_f32_e32 v161, v150
	v_mul_f32_e32 v150, v63, v47
	v_pk_mul_f32 v[144:145], v[16:17], v[16:17]
	v_pk_mul_f32 v[18:19], v[18:19], v[146:147]
	v_pk_add_f32 v[158:159], v[160:161], 1.0 op_sel_hi:[1,0]
	v_lshlrev_b32_e32 v160, 16, v154
	v_rcp_f32_e32 v47, v159
	v_and_b32_e32 v161, 0xffff0000, v154
	v_pk_fma_f32 v[24:25], v[132:133], v[160:161], v[24:25]
	v_pk_mul_f32 v[146:147], v[18:19], v[18:19]
	v_mul_f32_e32 v159, v152, v47
	v_pk_mul_f32 v[148:149], v[20:21], v[20:21]
	v_lshlrev_b32_e32 v63, 16, v153
	v_mul_f32_e32 v152, 0xbfb8aa3b, v63
	v_rcp_f32_e32 v47, v158
	v_exp_f32_e32 v160, v152
	v_mul_f32_e32 v152, 0xbfb8aa3b, v164
	v_exp_f32_e32 v161, v152
	v_mul_f32_e32 v158, v111, v47
	v_lshlrev_b32_e32 v154, 16, v155
	v_and_b32_e32 v155, 0xffff0000, v155
	v_pk_add_f32 v[160:161], v[160:161], 1.0 op_sel_hi:[1,0]
	v_pk_fma_f32 v[26:27], v[132:133], v[154:155], v[26:27]
	v_rcp_f32_e32 v47, v161
	v_pk_mul_f32 v[24:25], v[24:25], v[158:159]
	v_pk_mul_f32 v[22:23], v[22:23], v[150:151]
	v_pk_mul_f32 v[152:153], v[24:25], v[24:25]
	v_mul_f32_e32 v155, v164, v47
	v_and_b32_e32 v161, 0xffff0000, v162
	v_lshlrev_b32_e32 v111, 16, v156
	v_and_b32_e32 v156, 0xffff0000, v156
	v_mul_f32_e32 v154, 0xbfb8aa3b, v111
	v_exp_f32_e32 v164, v154
	v_mul_f32_e32 v154, 0xbfb8aa3b, v156
	flat_load_dwordx2 v[158:159], v[142:143] offset:64
	v_rcp_f32_e32 v47, v160
	v_exp_f32_e32 v165, v154
	v_mul_f32_e32 v154, v63, v47
	v_lshlrev_b32_e32 v160, 16, v162
	v_pk_fma_f32 v[28:29], v[132:133], v[160:161], v[28:29]
	v_pk_add_f32 v[164:165], v[164:165], 1.0 op_sel_hi:[1,0]
	v_pk_mul_f32 v[150:151], v[22:23], v[22:23]
	v_pk_mul_f32 v[26:27], v[26:27], v[154:155]
	flat_load_dwordx2 v[160:161], v[140:141] offset:64
	v_rcp_f32_e32 v47, v165
	s_nop 0
	v_mul_f32_e32 v165, v156, v47
	v_pk_mul_f32 v[154:155], v[26:27], v[26:27]
	v_lshlrev_b32_e32 v63, 16, v157
	v_mul_f32_e32 v156, 0xbfb8aa3b, v63
	v_rcp_f32_e32 v47, v164
	v_exp_f32_e32 v166, v156
	v_mul_f32_e32 v156, 0xbfb8aa3b, v168
	v_exp_f32_e32 v167, v156
	v_mul_f32_e32 v164, v111, v47
	v_pk_mul_f32 v[28:29], v[28:29], v[164:165]
	v_lshlrev_b32_e32 v162, 16, v163
	v_pk_add_f32 v[164:165], v[166:167], 1.0 op_sel_hi:[1,0]
	s_nop 0
	v_rcp_f32_e32 v47, v165
	v_and_b32_e32 v163, 0xffff0000, v163
	v_pk_fma_f32 v[30:31], v[132:133], v[162:163], v[30:31]
	v_pk_mul_f32 v[156:157], v[28:29], v[28:29]
	v_mul_f32_e32 v165, v168, v47
	flat_load_dwordx2 v[162:163], v[142:143] offset:80
	flat_load_dwordx2 v[166:167], v[142:143] offset:96
	flat_load_dwordx2 v[168:169], v[142:143] offset:112
	v_rcp_f32_e32 v47, v164
	s_nop 0
	v_mul_f32_e32 v164, v63, v47
	v_pk_mul_f32 v[30:31], v[30:31], v[164:165]
	flat_load_dwordx2 v[172:173], v[140:141] offset:80
	flat_load_dwordx2 v[174:175], v[140:141] offset:96
	flat_load_dwordx2 v[164:165], v[140:141] offset:112
	s_waitcnt vmcnt(0) lgkmcnt(0)
; DI float bflo(unsigned u) { return __uint_as_float(u << 16); }
; DI float bfhi(unsigned u) { return __uint_as_float(u & 0xffff0000u); }
; DI float siluf_(float x) { return x / (1.f + __expf(-x)); }
; DI float xhalf(float v) { return __shfl_xor(v, 32); }
; DI void ssd_out_phase(int wv, const Params& P, LAS unsigned char* lds) {
;     ...
;         for (int lt = 0; lt < 4; ++lt) { const size_t rr = (size_t)(row0 + lt * 32 + q); float ss = 0.f;
; #pragma unroll
;             for (int pt = 0; pt < 2; ++pt)
; #pragma unroll
;                 for (int i4 = 0; i4 < 4; ++i4) { const int p0 = h * 64 + pt * 32 + 8 * i4 + 4 * hh; const u32x2 xv = *(const u32x2*)(XS + rr * 1024 + p0), zv = *(const u32x2*)(Z + rr * 1024 + p0);
;                     const float xs4[4] = {bflo(xv.x), bfhi(xv.x), bflo(xv.y), bfhi(xv.y)}, zs4[4] = {bflo(zv.x), bfhi(zv.x), bflo(zv.y), bfhi(zv.y)};
; #pragma unroll
;                     for (int e = 0; e < 4; ++e) { const float y = (acc[pt][lt][4 * i4 + e] + xs4[e] * dsk) * siluf_(zs4[e]); acc[pt][lt][4 * i4 + e] = y; ss += y * y; } }
;             ss += xhalf(ss); if (hh == 0) ssq[wave * 128 + lt * 32 + q] = ss; }
	v_lshlrev_b32_e32 v111, 16, v158
	v_and_b32_e32 v158, 0xffff0000, v158
	v_mul_f32_e32 v142, 0xbfb8aa3b, v111
	v_exp_f32_e32 v170, v142
	v_mul_f32_e32 v142, 0xbfb8aa3b, v158
	v_exp_f32_e32 v171, v142
	v_pk_mul_f32 v[142:143], v[30:31], v[30:31]
	v_pk_add_f32 v[170:171], v[170:171], 1.0 op_sel_hi:[1,0]
	s_nop 0
	v_rcp_f32_e32 v47, v171
	v_lshlrev_b32_e32 v140, 16, v160
	v_and_b32_e32 v141, 0xffff0000, v160
	v_pk_fma_f32 v[0:1], v[132:133], v[140:141], v[0:1]
	v_mul_f32_e32 v141, v158, v47
	v_and_b32_e32 v171, 0xffff0000, v159
	v_lshlrev_b32_e32 v63, 16, v159
	v_mul_f32_e32 v140, 0xbfb8aa3b, v63
	v_rcp_f32_e32 v47, v170
	v_exp_f32_e32 v158, v140
	v_mul_f32_e32 v140, 0xbfb8aa3b, v171
	v_exp_f32_e32 v159, v140
	v_mul_f32_e32 v140, v111, v47
	v_lshlrev_b32_e32 v160, 16, v161
	v_and_b32_e32 v161, 0xffff0000, v161
	v_pk_add_f32 v[158:159], v[158:159], 1.0 op_sel_hi:[1,0]
	s_nop 0
	v_rcp_f32_e32 v47, v159
	v_pk_fma_f32 v[2:3], v[132:133], v[160:161], v[2:3]
	v_pk_mul_f32 v[0:1], v[0:1], v[140:141]
	v_mul_f32_e32 v159, v171, v47
	v_pk_mul_f32 v[140:141], v[0:1], v[0:1]
	v_lshlrev_b32_e32 v111, 16, v162
	v_and_b32_e32 v162, 0xffff0000, v162
	v_mul_f32_e32 v160, 0xbfb8aa3b, v111
	v_rcp_f32_e32 v47, v158
	v_mul_f32_e32 v161, 0xbfb8aa3b, v162
	v_exp_f32_e32 v160, v160
	v_exp_f32_e32 v161, v161
	v_mul_f32_e32 v158, v63, v47
	v_lshlrev_b32_e32 v170, 16, v172
	v_and_b32_e32 v171, 0xffff0000, v172
	v_pk_add_f32 v[160:161], v[160:161], 1.0 op_sel_hi:[1,0]
	s_nop 0
	v_rcp_f32_e32 v47, v161
	v_pk_fma_f32 v[4:5], v[132:133], v[170:171], v[4:5]
	v_pk_mul_f32 v[2:3], v[2:3], v[158:159]
	v_mul_f32_e32 v161, v162, v47
	v_and_b32_e32 v171, 0xffff0000, v173
	v_lshlrev_b32_e32 v63, 16, v163
	v_and_b32_e32 v172, 0xffff0000, v163
	v_mul_f32_e32 v162, 0xbfb8aa3b, v63
	v_rcp_f32_e32 v47, v160
	v_mul_f32_e32 v163, 0xbfb8aa3b, v172
	v_exp_f32_e32 v162, v162
	v_exp_f32_e32 v163, v163
	v_mul_f32_e32 v160, v111, v47
	v_lshlrev_b32_e32 v170, 16, v173
	v_pk_fma_f32 v[6:7], v[132:133], v[170:171], v[6:7]
	v_pk_add_f32 v[162:163], v[162:163], 1.0 op_sel_hi:[1,0]
	s_nop 0
	v_rcp_f32_e32 v47, v163
	v_pk_mul_f32 v[158:159], v[2:3], v[2:3]
	v_pk_mul_f32 v[4:5], v[4:5], v[160:161]
	v_mul_f32_e32 v163, v172, v47
	v_lshlrev_b32_e32 v172, 16, v174
	v_lshlrev_b32_e32 v111, 16, v166
	v_and_b32_e32 v166, 0xffff0000, v166
	v_mul_f32_e32 v170, 0xbfb8aa3b, v111
	v_rcp_f32_e32 v47, v162
	v_mul_f32_e32 v171, 0xbfb8aa3b, v166
	v_exp_f32_e32 v170, v170
	v_exp_f32_e32 v171, v171
	v_mul_f32_e32 v162, v63, v47
	v_and_b32_e32 v173, 0xffff0000, v174
	v_pk_fma_f32 v[8:9], v[132:133], v[172:173], v[8:9]
	v_pk_add_f32 v[170:171], v[170:171], 1.0 op_sel_hi:[1,0]
	s_nop 0
	v_rcp_f32_e32 v47, v171
	v_pk_mul_f32 v[160:161], v[4:5], v[4:5]
	v_pk_mul_f32 v[6:7], v[6:7], v[162:163]
	v_mul_f32_e32 v171, v166, v47
	v_and_b32_e32 v173, 0xffff0000, v175
	v_lshlrev_b32_e32 v63, 16, v167
	v_and_b32_e32 v174, 0xffff0000, v167
	v_mul_f32_e32 v166, 0xbfb8aa3b, v63
	v_rcp_f32_e32 v47, v170
	v_mul_f32_e32 v167, 0xbfb8aa3b, v174
	v_exp_f32_e32 v166, v166
	v_exp_f32_e32 v167, v167
	v_mul_f32_e32 v170, v111, v47
	v_lshlrev_b32_e32 v172, 16, v175
	v_pk_fma_f32 v[10:11], v[132:133], v[172:173], v[10:11]
	v_pk_add_f32 v[166:167], v[166:167], 1.0 op_sel_hi:[1,0]
	s_nop 0
	v_rcp_f32_e32 v47, v167
	v_pk_mul_f32 v[162:163], v[6:7], v[6:7]
	v_pk_mul_f32 v[8:9], v[8:9], v[170:171]
	v_mul_f32_e32 v167, v174, v47
	v_lshlrev_b32_e32 v174, 16, v164
	v_lshlrev_b32_e32 v111, 16, v168
	v_and_b32_e32 v168, 0xffff0000, v168
	v_mul_f32_e32 v172, 0xbfb8aa3b, v111
	v_rcp_f32_e32 v47, v166
	v_mul_f32_e32 v173, 0xbfb8aa3b, v168
	v_exp_f32_e32 v172, v172
	v_exp_f32_e32 v173, v173
	v_mul_f32_e32 v166, v63, v47
	v_and_b32_e32 v175, 0xffff0000, v164
	v_pk_fma_f32 v[12:13], v[132:133], v[174:175], v[12:13]
	v_pk_add_f32 v[172:173], v[172:173], 1.0 op_sel_hi:[1,0]
	s_nop 0
	v_rcp_f32_e32 v47, v173
	v_pk_mul_f32 v[170:171], v[8:9], v[8:9]
	v_pk_mul_f32 v[10:11], v[10:11], v[166:167]
	v_mul_f32_e32 v173, v168, v47
	v_and_b32_e32 v174, 0xffff0000, v169
	v_lshlrev_b32_e32 v63, 16, v169
	v_mul_f32_e32 v164, 0xbfb8aa3b, v63
	v_rcp_f32_e32 v47, v172
	v_exp_f32_e32 v168, v164
	v_mul_f32_e32 v164, 0xbfb8aa3b, v174
	v_exp_f32_e32 v169, v164
	v_mul_f32_e32 v172, v111, v47
	v_lshlrev_b32_e32 v164, 16, v165
	v_and_b32_e32 v165, 0xffff0000, v165
	v_pk_add_f32 v[168:169], v[168:169], 1.0 op_sel_hi:[1,0]
	s_nop 0
	v_rcp_f32_e32 v47, v169
	v_pk_fma_f32 v[14:15], v[132:133], v[164:165], v[14:15]
	v_pk_mul_f32 v[166:167], v[10:11], v[10:11]
	v_pk_mul_f32 v[12:13], v[12:13], v[172:173]
	v_mul_f32_e32 v133, v174, v47
	v_rcp_f32_e32 v47, v168
	v_pk_mul_f32 v[172:173], v[12:13], v[12:13]
	v_mul_f32_e32 v132, v63, v47
	v_add_f32_e32 v47, v144, v145
	v_add_f32_e32 v47, v146, v47
	v_add_f32_e32 v47, v147, v47
	v_add_f32_e32 v47, v148, v47
	v_add_f32_e32 v47, v149, v47
	v_add_f32_e32 v47, v150, v47
	v_add_f32_e32 v47, v151, v47
	v_add_f32_e32 v47, v152, v47
	v_add_f32_e32 v47, v153, v47
	v_add_f32_e32 v47, v154, v47
	v_add_f32_e32 v47, v155, v47
	v_add_f32_e32 v47, v156, v47
	v_add_f32_e32 v47, v157, v47
	v_add_f32_e32 v47, v142, v47
	v_add_f32_e32 v47, v143, v47
	v_add_f32_e32 v47, v140, v47
	v_add_f32_e32 v47, v141, v47
	v_add_f32_e32 v47, v158, v47
	v_add_f32_e32 v47, v159, v47
	v_add_f32_e32 v47, v160, v47
	v_add_f32_e32 v47, v161, v47
	v_add_f32_e32 v47, v162, v47
	v_add_f32_e32 v47, v163, v47
	v_add_f32_e32 v47, v170, v47
	v_add_f32_e32 v47, v171, v47
	v_add_f32_e32 v47, v166, v47
	v_add_f32_e32 v47, v167, v47
	v_pk_mul_f32 v[14:15], v[14:15], v[132:133]
	v_add_f32_e32 v47, v172, v47
	v_pk_mul_f32 v[132:133], v[14:15], v[14:15]
	v_add_f32_e32 v47, v173, v47
	v_add_f32_e32 v47, v132, v47
	v_add_f32_e32 v47, v133, v47
	ds_bpermute_b32 v63, v229, v47
	s_and_saveexec_b64 s[14:15], s[12:13]
	s_cbranch_execz .LBB0_1668
	s_waitcnt lgkmcnt(0)
	v_add_f32_e32 v47, v47, v63
	ds_write_b32 v231, v47 offset:384
	s_branch .LBB0_1668

; DI float siluf_(float x) { return x / (1.f + __expf(-x)); }
; #define EPI_ROWS(...) _Pragma("unroll") for (int ai = 0; ai < 2; ++ai) _Pragma("unroll") for (int m = 0; m < 4; ++m) { const int row = u.pm * 256 + ai * 128 + wr * 64 + m * 16 + fr; __VA_ARGS__ }
; DI u32x4 pack8(f32x4 a, f32x4 b) { u32x4 w; w.x = pk2(a[0], a[1]); w.y = pk2(a[2], a[3]); w.z = pk2(b[0], b[1]); w.w = pk2(b[2], b[3]); return w; }
; DI void st16_wt(void* p, u32x4 v) { asm volatile("global_store_dwordx4 %0, %1, off sc0 sc1\n\ts_nop 1" :: "v"(p), "v"(v) : "memory"); }
;     DI void operator()(const Acc& acc, const Unit& u, int wr, int wc, int fr, int fq) const {
;         const int c0 = u.pn * 128 + wc * 32 + 8 * fq;
;         EPI_ROWS( f32x4 a, b;
;             _Pragma("unroll") for (int e = 0; e < 4; ++e) { a[e] = siluf_(acc[ai][0][m][0][e]) * acc[ai][1][m][0][e]; b[e] = siluf_(acc[ai][0][m][1][e]) * acc[ai][1][m][1][e]; }
;             st16_wt(H + (size_t)row * DFF + c0, pack8(a, b)); )
;     }
.LBB0_1891:
	v_mov_b32_e32 v150, v144
	v_mov_b32_e32 v151, v145
	s_lshl_b32 s15, s50, 7
	s_or_b32 s15, s15, s42
	v_lshl_add_u32 v152, v151, 3, s15
	v_mul_f32_e32 v151, 0xbfb8aa3b, v124
	v_exp_f32_e32 v154, v151
	v_mul_f32_e32 v151, 0xbfb8aa3b, v125
	v_exp_f32_e32 v155, v151
	v_mul_f32_e32 v156, 0xbfb8aa3b, v116
	v_exp_f32_e32 v156, v156
	s_lshl_b32 s15, s22, 8
	v_pk_add_f32 v[154:155], v[154:155], 1.0 op_sel_hi:[1,0]
	s_add_i32 s15, s15, s41
	v_rcp_f32_e32 v151, v155
	v_add_u32_e32 v150, s15, v150
	v_ashrrev_i32_e32 v153, 31, v152
	v_mul_f32_e32 v157, 0xbfb8aa3b, v117
	v_mul_f32_e32 v125, v125, v151
	v_rcp_f32_e32 v151, v154
	v_exp_f32_e32 v157, v157
	s_nop 0
	v_pk_add_f32 v[156:157], v[156:157], 1.0 op_sel_hi:[1,0]
	v_mul_f32_e32 v124, v124, v151
	v_pk_mul_f32 v[120:121], v[124:125], v[120:121]
	v_rcp_f32_e32 v124, v157
	s_nop 0
	v_mul_f32_e32 v117, v117, v124
	v_mul_f32_e32 v124, 0xbfb8aa3b, v126
	v_rcp_f32_e32 v151, v156
	v_mul_f32_e32 v125, 0xbfb8aa3b, v127
	v_exp_f32_e32 v124, v124
	v_exp_f32_e32 v125, v125
	v_mul_f32_e32 v116, v116, v151
	v_pk_mul_f32 v[154:155], v[116:117], v[112:113]
	v_pk_add_f32 v[124:125], v[124:125], 1.0 op_sel_hi:[1,0]
	s_nop 0
	v_rcp_f32_e32 v113, v125
	v_mul_f32_e32 v112, 0xbfb8aa3b, v118
	v_exp_f32_e32 v112, v112
	v_mul_f32_e32 v117, v127, v113
	v_rcp_f32_e32 v116, v124
	v_mul_f32_e32 v113, 0xbfb8aa3b, v119
	v_exp_f32_e32 v113, v113
	s_nop 0
	v_pk_add_f32 v[112:113], v[112:113], 1.0 op_sel_hi:[1,0]
	v_mul_f32_e32 v116, v126, v116
	v_pk_mul_f32 v[122:123], v[116:117], v[122:123]
	v_rcp_f32_e32 v116, v113
	s_nop 0
	v_mul_f32_e32 v113, v119, v116
	v_rcp_f32_e32 v116, v112
	s_nop 0
	v_mul_f32_e32 v112, v118, v116
	v_pk_mul_f32 v[124:125], v[112:113], v[114:115]
	v_mov_b64_e32 v[112:113], s[8:9]
	v_mad_i64_i32 v[116:117], s[24:25], v150, s47, v[112:113]
	v_lshlrev_b64 v[114:115], 1, v[152:153]
	v_lshl_add_u64 v[126:127], v[116:117], 0, v[114:115]
	v_mul_f32_e32 v117, 0xbfb8aa3b, v108
	v_cvt_pk_bf16_f32 v116, v120, v121
	v_exp_f32_e32 v120, v117
	v_mul_f32_e32 v117, 0xbfb8aa3b, v109
	v_exp_f32_e32 v121, v117
	v_cvt_pk_bf16_f32 v117, v122, v123
	v_cvt_pk_bf16_f32 v118, v154, v155
	v_cvt_pk_bf16_f32 v119, v124, v125
	v_pk_add_f32 v[120:121], v[120:121], 1.0 op_sel_hi:[1,0]
	global_store_dwordx4 v[126:127], v[116:119], off sc0 sc1
	s_nop 1
	v_rcp_f32_e32 v117, v121
	v_mul_f32_e32 v116, 0xbfb8aa3b, v100
	v_exp_f32_e32 v116, v116
	v_mul_f32_e32 v109, v109, v117
	v_rcp_f32_e32 v118, v120
	v_mul_f32_e32 v117, 0xbfb8aa3b, v101
	v_exp_f32_e32 v117, v117
	s_nop 0
	v_pk_add_f32 v[116:117], v[116:117], 1.0 op_sel_hi:[1,0]
	v_mul_f32_e32 v108, v108, v118
	v_pk_mul_f32 v[104:105], v[108:109], v[104:105]
	v_rcp_f32_e32 v108, v117
	s_nop 0
	v_mul_f32_e32 v101, v101, v108
	v_mul_f32_e32 v108, 0xbfb8aa3b, v110
	v_rcp_f32_e32 v117, v116
	v_mul_f32_e32 v109, 0xbfb8aa3b, v111
	v_exp_f32_e32 v108, v108
	v_exp_f32_e32 v109, v109
	v_mul_f32_e32 v100, v100, v117
	v_pk_mul_f32 v[100:101], v[100:101], v[96:97]
	v_pk_add_f32 v[108:109], v[108:109], 1.0 op_sel_hi:[1,0]
	s_nop 0
	v_rcp_f32_e32 v97, v109
	v_mul_f32_e32 v96, 0xbfb8aa3b, v102
	v_exp_f32_e32 v96, v96
	v_mul_f32_e32 v109, v111, v97
	v_rcp_f32_e32 v111, v108
	v_mul_f32_e32 v97, 0xbfb8aa3b, v103
	v_exp_f32_e32 v97, v97
	s_nop 0
	v_pk_add_f32 v[96:97], v[96:97], 1.0 op_sel_hi:[1,0]
	v_mul_f32_e32 v108, v110, v111
	v_pk_mul_f32 v[106:107], v[108:109], v[106:107]
	v_rcp_f32_e32 v108, v97
	s_nop 0
	v_mul_f32_e32 v97, v103, v108
	v_rcp_f32_e32 v103, v96
	s_nop 0
	v_mul_f32_e32 v96, v102, v103
	v_pk_mul_f32 v[102:103], v[96:97], v[98:99]
	v_add_u32_e32 v96, 16, v150
	v_mad_i64_i32 v[96:97], s[24:25], v96, s47, v[112:113]
	v_lshl_add_u64 v[108:109], v[96:97], 0, v[114:115]
	v_mul_f32_e32 v97, 0xbfb8aa3b, v92
	v_cvt_pk_bf16_f32 v96, v104, v105
	v_exp_f32_e32 v104, v97
	v_mul_f32_e32 v97, 0xbfb8aa3b, v93
	v_exp_f32_e32 v105, v97
	v_cvt_pk_bf16_f32 v98, v100, v101
	v_cvt_pk_bf16_f32 v99, v102, v103
	v_cvt_pk_bf16_f32 v97, v106, v107
	v_pk_add_f32 v[100:101], v[104:105], 1.0 op_sel_hi:[1,0]
	global_store_dwordx4 v[108:109], v[96:99], off sc0 sc1
	s_nop 1
	v_rcp_f32_e32 v97, v101
	v_mul_f32_e32 v96, 0xbfb8aa3b, v84
	v_exp_f32_e32 v96, v96
	v_mul_f32_e32 v93, v93, v97
	v_rcp_f32_e32 v98, v100
	v_mul_f32_e32 v97, 0xbfb8aa3b, v85
	v_exp_f32_e32 v97, v97
	s_nop 0
	v_pk_add_f32 v[96:97], v[96:97], 1.0 op_sel_hi:[1,0]
	v_mul_f32_e32 v92, v92, v98
	v_pk_mul_f32 v[88:89], v[92:93], v[88:89]
	v_rcp_f32_e32 v92, v97
	s_nop 0
	v_mul_f32_e32 v85, v85, v92
	v_mul_f32_e32 v92, 0xbfb8aa3b, v94
	v_rcp_f32_e32 v97, v96
	v_mul_f32_e32 v93, 0xbfb8aa3b, v95
	v_exp_f32_e32 v92, v92
	v_exp_f32_e32 v93, v93
	v_mul_f32_e32 v84, v84, v97
	v_pk_mul_f32 v[84:85], v[84:85], v[80:81]
	v_pk_add_f32 v[92:93], v[92:93], 1.0 op_sel_hi:[1,0]
	s_nop 0
	v_rcp_f32_e32 v81, v93
	v_mul_f32_e32 v80, 0xbfb8aa3b, v86
	v_exp_f32_e32 v80, v80
	v_mul_f32_e32 v93, v95, v81
	v_rcp_f32_e32 v95, v92
	v_mul_f32_e32 v81, 0xbfb8aa3b, v87
	v_exp_f32_e32 v81, v81
	s_nop 0
	v_pk_add_f32 v[80:81], v[80:81], 1.0 op_sel_hi:[1,0]
	v_mul_f32_e32 v92, v94, v95
	v_pk_mul_f32 v[90:91], v[92:93], v[90:91]
	v_rcp_f32_e32 v92, v81
	s_nop 0
	v_mul_f32_e32 v81, v87, v92
	v_rcp_f32_e32 v87, v80
	s_nop 0
	v_mul_f32_e32 v80, v86, v87
	v_pk_mul_f32 v[86:87], v[80:81], v[82:83]
	v_add_u32_e32 v80, 32, v150
	v_mad_i64_i32 v[80:81], s[24:25], v80, s47, v[112:113]
	v_lshl_add_u64 v[92:93], v[80:81], 0, v[114:115]
	v_mul_f32_e32 v81, 0xbfb8aa3b, v76
	v_cvt_pk_bf16_f32 v80, v88, v89
	v_exp_f32_e32 v88, v81
	v_mul_f32_e32 v81, 0xbfb8aa3b, v77
	v_exp_f32_e32 v89, v81
	v_cvt_pk_bf16_f32 v82, v84, v85
	v_cvt_pk_bf16_f32 v83, v86, v87
	v_cvt_pk_bf16_f32 v81, v90, v91
; DI float siluf_(float x) { return x / (1.f + __expf(-x)); }
; #define EPI_ROWS(...) _Pragma("unroll") for (int ai = 0; ai < 2; ++ai) _Pragma("unroll") for (int m = 0; m < 4; ++m) { const int row = u.pm * 256 + ai * 128 + wr * 64 + m * 16 + fr; __VA_ARGS__ }
; DI u32x4 pack8(f32x4 a, f32x4 b) { u32x4 w; w.x = pk2(a[0], a[1]); w.y = pk2(a[2], a[3]); w.z = pk2(b[0], b[1]); w.w = pk2(b[2], b[3]); return w; }
; DI void st16_wt(void* p, u32x4 v) { asm volatile("global_store_dwordx4 %0, %1, off sc0 sc1\n\ts_nop 1" :: "v"(p), "v"(v) : "memory"); }
;     DI void operator()(const Acc& acc, const Unit& u, int wr, int wc, int fr, int fq) const {
;         const int c0 = u.pn * 128 + wc * 32 + 8 * fq;
;         EPI_ROWS( f32x4 a, b;
;             _Pragma("unroll") for (int e = 0; e < 4; ++e) { a[e] = siluf_(acc[ai][0][m][0][e]) * acc[ai][1][m][0][e]; b[e] = siluf_(acc[ai][0][m][1][e]) * acc[ai][1][m][1][e]; }
;             st16_wt(H + (size_t)row * DFF + c0, pack8(a, b)); )
;     }
	v_pk_add_f32 v[84:85], v[88:89], 1.0 op_sel_hi:[1,0]
	global_store_dwordx4 v[92:93], v[80:83], off sc0 sc1
	s_nop 1
	v_rcp_f32_e32 v81, v85
	v_mul_f32_e32 v80, 0xbfb8aa3b, v68
	v_exp_f32_e32 v80, v80
	v_mul_f32_e32 v77, v77, v81
	v_rcp_f32_e32 v82, v84
	v_mul_f32_e32 v81, 0xbfb8aa3b, v69
	v_exp_f32_e32 v81, v81
	s_nop 0
	v_pk_add_f32 v[80:81], v[80:81], 1.0 op_sel_hi:[1,0]
	v_mul_f32_e32 v76, v76, v82
	v_pk_mul_f32 v[72:73], v[76:77], v[72:73]
	v_rcp_f32_e32 v76, v81
	s_nop 0
	v_mul_f32_e32 v69, v69, v76
	v_mul_f32_e32 v76, 0xbfb8aa3b, v78
	v_rcp_f32_e32 v81, v80
	v_mul_f32_e32 v77, 0xbfb8aa3b, v79
	v_exp_f32_e32 v76, v76
	v_exp_f32_e32 v77, v77
	v_mul_f32_e32 v68, v68, v81
	v_pk_mul_f32 v[68:69], v[68:69], v[64:65]
	v_pk_add_f32 v[76:77], v[76:77], 1.0 op_sel_hi:[1,0]
	s_nop 0
	v_rcp_f32_e32 v65, v77
	v_mul_f32_e32 v64, 0xbfb8aa3b, v70
	v_exp_f32_e32 v64, v64
	v_mul_f32_e32 v77, v79, v65
	v_rcp_f32_e32 v79, v76
	v_mul_f32_e32 v65, 0xbfb8aa3b, v71
	v_exp_f32_e32 v65, v65
	s_nop 0
	v_pk_add_f32 v[64:65], v[64:65], 1.0 op_sel_hi:[1,0]
	v_mul_f32_e32 v76, v78, v79
	v_pk_mul_f32 v[74:75], v[76:77], v[74:75]
	v_rcp_f32_e32 v76, v65
	s_nop 0
	v_mul_f32_e32 v65, v71, v76
	v_rcp_f32_e32 v71, v64
	s_nop 0
	v_mul_f32_e32 v64, v70, v71
	v_pk_mul_f32 v[70:71], v[64:65], v[66:67]
	v_add_u32_e32 v64, 48, v150
	v_mad_i64_i32 v[64:65], s[24:25], v64, s47, v[112:113]
	v_mul_f32_e32 v66, 0xbfb8aa3b, v60
	v_lshl_add_u64 v[76:77], v[64:65], 0, v[114:115]
	v_cvt_pk_bf16_f32 v64, v72, v73
	v_exp_f32_e32 v72, v66
	v_mul_f32_e32 v66, 0xbfb8aa3b, v61
	v_exp_f32_e32 v73, v66
	v_cvt_pk_bf16_f32 v65, v74, v75
	v_cvt_pk_bf16_f32 v66, v68, v69
	v_cvt_pk_bf16_f32 v67, v70, v71
	global_store_dwordx4 v[76:77], v[64:67], off sc0 sc1
	s_nop 1
	v_pk_add_f32 v[64:65], v[72:73], 1.0 op_sel_hi:[1,0]
	s_nop 0
	v_rcp_f32_e32 v67, v65
	v_mul_f32_e32 v66, 0xbfb8aa3b, v52
	v_exp_f32_e32 v66, v66
	v_add_u32_e32 v69, 0x80, v150
	v_mul_f32_e32 v61, v61, v67
	v_rcp_f32_e32 v65, v64
	v_mul_f32_e32 v67, 0xbfb8aa3b, v53
	v_exp_f32_e32 v67, v67
	s_nop 0
	v_pk_add_f32 v[66:67], v[66:67], 1.0 op_sel_hi:[1,0]
	v_mul_f32_e32 v60, v60, v65
	v_pk_mul_f32 v[56:57], v[60:61], v[56:57]
	v_rcp_f32_e32 v60, v67
	s_nop 0
	v_mul_f32_e32 v53, v53, v60
	v_mul_f32_e32 v60, 0xbfb8aa3b, v62
	v_rcp_f32_e32 v64, v66
	v_mul_f32_e32 v61, 0xbfb8aa3b, v63
	v_exp_f32_e32 v60, v60
	v_exp_f32_e32 v61, v61
	v_mul_f32_e32 v52, v52, v64
	v_pk_mul_f32 v[52:53], v[52:53], v[48:49]
	v_pk_add_f32 v[60:61], v[60:61], 1.0 op_sel_hi:[1,0]
	s_nop 0
	v_rcp_f32_e32 v49, v61
	v_mul_f32_e32 v48, 0xbfb8aa3b, v54
	v_exp_f32_e32 v48, v48
	v_mul_f32_e32 v61, v63, v49
	v_rcp_f32_e32 v63, v60
	v_mul_f32_e32 v49, 0xbfb8aa3b, v55
	v_exp_f32_e32 v49, v49
	s_nop 0
	v_pk_add_f32 v[48:49], v[48:49], 1.0 op_sel_hi:[1,0]
	v_mul_f32_e32 v60, v62, v63
	v_pk_mul_f32 v[58:59], v[60:61], v[58:59]
	v_rcp_f32_e32 v60, v49
	s_nop 0
	v_mul_f32_e32 v49, v55, v60
	v_rcp_f32_e32 v55, v48
	s_nop 0
	v_mul_f32_e32 v48, v54, v55
	v_pk_mul_f32 v[54:55], v[48:49], v[50:51]
	v_mad_i64_i32 v[48:49], s[24:25], v69, s47, v[112:113]
	v_lshl_add_u64 v[60:61], v[48:49], 0, v[114:115]
	v_mul_f32_e32 v49, 0xbfb8aa3b, v44
	v_cvt_pk_bf16_f32 v48, v56, v57
	v_exp_f32_e32 v56, v49
	v_mul_f32_e32 v49, 0xbfb8aa3b, v45
	v_exp_f32_e32 v57, v49
	v_cvt_pk_bf16_f32 v50, v52, v53
	v_cvt_pk_bf16_f32 v51, v54, v55
	v_cvt_pk_bf16_f32 v49, v58, v59
	v_pk_add_f32 v[52:53], v[56:57], 1.0 op_sel_hi:[1,0]
	global_store_dwordx4 v[60:61], v[48:51], off sc0 sc1
	s_nop 1
	v_rcp_f32_e32 v49, v53
	v_mul_f32_e32 v48, 0xbfb8aa3b, v36
	v_exp_f32_e32 v48, v48
	v_mul_f32_e32 v45, v45, v49
	v_rcp_f32_e32 v50, v52
	v_mul_f32_e32 v49, 0xbfb8aa3b, v37
	v_exp_f32_e32 v49, v49
	s_nop 0
	v_pk_add_f32 v[48:49], v[48:49], 1.0 op_sel_hi:[1,0]
	v_mul_f32_e32 v44, v44, v50
	v_pk_mul_f32 v[40:41], v[44:45], v[40:41]
	v_rcp_f32_e32 v44, v49
	s_nop 0
	v_mul_f32_e32 v37, v37, v44
	v_mul_f32_e32 v44, 0xbfb8aa3b, v46
	v_rcp_f32_e32 v49, v48
	v_mul_f32_e32 v45, 0xbfb8aa3b, v47
	v_exp_f32_e32 v44, v44
	v_exp_f32_e32 v45, v45
	v_mul_f32_e32 v36, v36, v49
	v_pk_mul_f32 v[36:37], v[36:37], v[32:33]
	v_pk_add_f32 v[44:45], v[44:45], 1.0 op_sel_hi:[1,0]
	s_nop 0
	v_rcp_f32_e32 v33, v45
	v_mul_f32_e32 v32, 0xbfb8aa3b, v38
; DI float siluf_(float x) { return x / (1.f + __expf(-x)); }
; #define PG8_BAR __builtin_amdgcn_s_barrier()
; #define EPI_ROWS(...) _Pragma("unroll") for (int ai = 0; ai < 2; ++ai) _Pragma("unroll") for (int m = 0; m < 4; ++m) { const int row = u.pm * 256 + ai * 128 + wr * 64 + m * 16 + fr; __VA_ARGS__ }
; DI void st16_wt(void* p, u32x4 v) { asm volatile("global_store_dwordx4 %0, %1, off sc0 sc1\n\ts_nop 1" :: "v"(p), "v"(v) : "memory"); }
; DI u32x4 pack8(f32x4 a, f32x4 b) { u32x4 w; w.x = pk2(a[0], a[1]); w.y = pk2(a[2], a[3]); w.z = pk2(b[0], b[1]); w.w = pk2(b[2], b[3]); return w; }
; template <class Epi>
; DI void gemm_phase(int wv, LAS unsigned char* lds, const Gemm g, const StaticOrder& S, const Epi& E) {
;     ...
;         if (wr == 0) PG8_BAR;
;         { int fr2 = fr, fq2 = fq; asm volatile("" : "+v"(fr2), "+v"(fq2)); E(acc, cur, wr, wc, fr2, fq2); }
;         if (!has_next) break;
; #pragma unroll
;         for (int a = 0; a < 2; ++a)
; #pragma unroll
;             for (int b = 0; b < 2; ++b)
; #pragma unroll
;                 for (int m = 0; m < 4; ++m)
; #pragma unroll
;                     for (int n = 0; n < 2; ++n) acc[a][b][m][n] = (f32x4){0.f, 0.f, 0.f, 0.f};
;         cur = nxt; cA = nA; cB = nB; ++ui;
;         if (wr == 1) PG8_BAR;
;     DI void operator()(const Acc& acc, const Unit& u, int wr, int wc, int fr, int fq) const {
;         const int c0 = u.pn * 128 + wc * 32 + 8 * fq;
;         EPI_ROWS( f32x4 a, b;
;             _Pragma("unroll") for (int e = 0; e < 4; ++e) { a[e] = siluf_(acc[ai][0][m][0][e]) * acc[ai][1][m][0][e]; b[e] = siluf_(acc[ai][0][m][1][e]) * acc[ai][1][m][1][e]; }
;             st16_wt(H + (size_t)row * DFF + c0, pack8(a, b)); )
;     }
	v_exp_f32_e32 v32, v32
	v_mul_f32_e32 v45, v47, v33
	v_rcp_f32_e32 v47, v44
	v_mul_f32_e32 v33, 0xbfb8aa3b, v39
	v_exp_f32_e32 v33, v33
	s_nop 0
	v_pk_add_f32 v[32:33], v[32:33], 1.0 op_sel_hi:[1,0]
	v_mul_f32_e32 v44, v46, v47
	v_pk_mul_f32 v[42:43], v[44:45], v[42:43]
	v_rcp_f32_e32 v44, v33
	s_nop 0
	v_mul_f32_e32 v33, v39, v44
	v_rcp_f32_e32 v39, v32
	s_nop 0
	v_mul_f32_e32 v32, v38, v39
	v_pk_mul_f32 v[38:39], v[32:33], v[34:35]
	v_add_u32_e32 v32, 0x90, v150
	v_mad_i64_i32 v[32:33], s[24:25], v32, s47, v[112:113]
	v_lshl_add_u64 v[44:45], v[32:33], 0, v[114:115]
	v_mul_f32_e32 v33, 0xbfb8aa3b, v28
	v_cvt_pk_bf16_f32 v32, v40, v41
	v_exp_f32_e32 v40, v33
	v_mul_f32_e32 v33, 0xbfb8aa3b, v29
	v_exp_f32_e32 v41, v33
	v_cvt_pk_bf16_f32 v34, v36, v37
	v_cvt_pk_bf16_f32 v35, v38, v39
	v_cvt_pk_bf16_f32 v33, v42, v43
	v_pk_add_f32 v[36:37], v[40:41], 1.0 op_sel_hi:[1,0]
	global_store_dwordx4 v[44:45], v[32:35], off sc0 sc1
	s_nop 1
	v_rcp_f32_e32 v33, v37
	v_mul_f32_e32 v32, 0xbfb8aa3b, v20
	v_exp_f32_e32 v32, v32
	v_mul_f32_e32 v29, v29, v33
	v_rcp_f32_e32 v34, v36
	v_mul_f32_e32 v33, 0xbfb8aa3b, v21
	v_exp_f32_e32 v33, v33
	s_nop 0
	v_pk_add_f32 v[32:33], v[32:33], 1.0 op_sel_hi:[1,0]
	v_mul_f32_e32 v28, v28, v34
	v_pk_mul_f32 v[24:25], v[28:29], v[24:25]
	v_rcp_f32_e32 v28, v33
	s_nop 0
	v_mul_f32_e32 v21, v21, v28
	v_mul_f32_e32 v28, 0xbfb8aa3b, v30
	v_rcp_f32_e32 v33, v32
	v_mul_f32_e32 v29, 0xbfb8aa3b, v31
	v_exp_f32_e32 v28, v28
	v_exp_f32_e32 v29, v29
	v_mul_f32_e32 v20, v20, v33
	v_pk_mul_f32 v[20:21], v[20:21], v[16:17]
	v_pk_add_f32 v[28:29], v[28:29], 1.0 op_sel_hi:[1,0]
	s_nop 0
	v_rcp_f32_e32 v17, v29
	v_mul_f32_e32 v16, 0xbfb8aa3b, v22
	v_exp_f32_e32 v16, v16
	v_mul_f32_e32 v29, v31, v17
	v_rcp_f32_e32 v31, v28
	v_mul_f32_e32 v17, 0xbfb8aa3b, v23
	v_exp_f32_e32 v17, v17
	s_nop 0
	v_pk_add_f32 v[16:17], v[16:17], 1.0 op_sel_hi:[1,0]
	v_mul_f32_e32 v28, v30, v31
	v_pk_mul_f32 v[26:27], v[28:29], v[26:27]
	v_rcp_f32_e32 v28, v17
	s_nop 0
	v_mul_f32_e32 v17, v23, v28
	v_rcp_f32_e32 v23, v16
	s_nop 0
	v_mul_f32_e32 v16, v22, v23
	v_pk_mul_f32 v[22:23], v[16:17], v[18:19]
	v_add_u32_e32 v16, 0xa0, v150
	v_mad_i64_i32 v[16:17], s[24:25], v16, s47, v[112:113]
	v_lshl_add_u64 v[28:29], v[16:17], 0, v[114:115]
	v_mul_f32_e32 v17, 0xbfb8aa3b, v12
	v_cvt_pk_bf16_f32 v16, v24, v25
	v_exp_f32_e32 v24, v17
	v_mul_f32_e32 v17, 0xbfb8aa3b, v13
	v_exp_f32_e32 v25, v17
	v_cvt_pk_bf16_f32 v18, v20, v21
	v_cvt_pk_bf16_f32 v19, v22, v23
	v_cvt_pk_bf16_f32 v17, v26, v27
	v_pk_add_f32 v[20:21], v[24:25], 1.0 op_sel_hi:[1,0]
	global_store_dwordx4 v[28:29], v[16:19], off sc0 sc1
	s_nop 1
	v_rcp_f32_e32 v17, v21
	v_mul_f32_e32 v16, 0xbfb8aa3b, v4
	v_exp_f32_e32 v16, v16
	v_mul_f32_e32 v13, v13, v17
	v_rcp_f32_e32 v18, v20
	v_mul_f32_e32 v17, 0xbfb8aa3b, v5
	v_exp_f32_e32 v17, v17
	s_nop 0
	v_pk_add_f32 v[16:17], v[16:17], 1.0 op_sel_hi:[1,0]
	v_mul_f32_e32 v12, v12, v18
	v_pk_mul_f32 v[8:9], v[12:13], v[8:9]
	v_rcp_f32_e32 v12, v17
	s_nop 0
	v_mul_f32_e32 v5, v5, v12
	v_mul_f32_e32 v12, 0xbfb8aa3b, v14
	v_rcp_f32_e32 v17, v16
	v_mul_f32_e32 v13, 0xbfb8aa3b, v15
	v_exp_f32_e32 v12, v12
	v_exp_f32_e32 v13, v13
	v_mul_f32_e32 v4, v4, v17
	v_pk_mul_f32 v[4:5], v[4:5], v[0:1]
	v_pk_add_f32 v[12:13], v[12:13], 1.0 op_sel_hi:[1,0]
	s_nop 0
	v_rcp_f32_e32 v1, v13
	v_mul_f32_e32 v0, 0xbfb8aa3b, v6
	v_exp_f32_e32 v0, v0
	v_mul_f32_e32 v13, v15, v1
	v_rcp_f32_e32 v15, v12
	v_mul_f32_e32 v1, 0xbfb8aa3b, v7
	v_exp_f32_e32 v1, v1
	s_nop 0
	v_pk_add_f32 v[0:1], v[0:1], 1.0 op_sel_hi:[1,0]
	v_mul_f32_e32 v12, v14, v15
	v_pk_mul_f32 v[10:11], v[12:13], v[10:11]
	v_rcp_f32_e32 v12, v1
	s_nop 0
	v_mul_f32_e32 v1, v7, v12
	v_rcp_f32_e32 v7, v0
	s_nop 0
	v_mul_f32_e32 v0, v6, v7
	v_pk_mul_f32 v[6:7], v[0:1], v[2:3]
	v_add_u32_e32 v0, 0xb0, v150
	v_mad_i64_i32 v[0:1], s[24:25], v0, s47, v[112:113]
	v_lshl_add_u64 v[12:13], v[0:1], 0, v[114:115]
	v_cvt_pk_bf16_f32 v0, v8, v9
	v_cvt_pk_bf16_f32 v1, v10, v11
	v_cvt_pk_bf16_f32 v2, v4, v5
	v_cvt_pk_bf16_f32 v3, v6, v7
	global_store_dwordx4 v[12:13], v[0:3], off sc0 sc1
	s_nop 1
	s_andn2_b64 vcc, exec, s[2:3]
	s_mov_b64 s[2:3], -1
	s_cbranch_vccnz .LBB0_1884
	s_andn2_b64 vcc, exec, s[6:7]
	s_cbranch_vccnz .LBB0_1883
	s_barrier
	s_branch .LBB0_1883

; DI float siluf_(float x) { return x / (1.f + __expf(-x)); }
; #define EPI_ROWS(...) _Pragma("unroll") for (int ai = 0; ai < 2; ++ai) _Pragma("unroll") for (int m = 0; m < 4; ++m) { const int row = u.pm * 256 + ai * 128 + wr * 64 + m * 16 + fr; __VA_ARGS__ }
; DI u32x4 pack8(f32x4 a, f32x4 b) { u32x4 w; w.x = pk2(a[0], a[1]); w.y = pk2(a[2], a[3]); w.z = pk2(b[0], b[1]); w.w = pk2(b[2], b[3]); return w; }
; DI void st16_wt(void* p, u32x4 v) { asm volatile("global_store_dwordx4 %0, %1, off sc0 sc1\n\ts_nop 1" :: "v"(p), "v"(v) : "memory"); }
;     DI void operator()(const Acc& acc, const Unit& u, int wr, int wc, int fr, int fq) const {
;         const int c0 = u.pn * 128 + wc * 32 + 8 * fq;
;         EPI_ROWS( f32x4 a, b;
;             _Pragma("unroll") for (int e = 0; e < 4; ++e) { a[e] = siluf_(acc[ai][0][m][0][e]) * acc[ai][1][m][0][e]; b[e] = siluf_(acc[ai][0][m][1][e]) * acc[ai][1][m][1][e]; }
;             st16_wt(H + (size_t)row * DFF + c0, pack8(a, b)); )
;     }
.LBB0_2384:
	v_mov_b32_e32 v150, v145
	v_mov_b32_e32 v151, v144
	s_lshl_b32 s15, s50, 7
	s_or_b32 s15, s15, s42
	v_lshl_add_u32 v152, v150, 3, s15
	v_mul_f32_e32 v150, 0xbfb8aa3b, v124
	v_exp_f32_e32 v154, v150
	v_mul_f32_e32 v150, 0xbfb8aa3b, v125
	v_exp_f32_e32 v155, v150
	s_lshl_b32 s15, s22, 8
	s_add_i32 s15, s15, s41
	v_add_u32_e32 v150, s15, v151
	v_pk_add_f32 v[154:155], v[154:155], 1.0 op_sel_hi:[1,0]
	v_mul_f32_e32 v156, 0xbfb8aa3b, v116
	v_rcp_f32_e32 v151, v155
	v_exp_f32_e32 v156, v156
	v_ashrrev_i32_e32 v153, 31, v152
	v_mul_f32_e32 v157, 0xbfb8aa3b, v117
	v_mul_f32_e32 v125, v125, v151
	v_rcp_f32_e32 v151, v154
	v_exp_f32_e32 v157, v157
	s_nop 0
	v_pk_add_f32 v[156:157], v[156:157], 1.0 op_sel_hi:[1,0]
	v_mul_f32_e32 v124, v124, v151
	v_pk_mul_f32 v[120:121], v[124:125], v[120:121]
	v_rcp_f32_e32 v124, v157
	s_nop 0
	v_mul_f32_e32 v117, v117, v124
	v_mul_f32_e32 v124, 0xbfb8aa3b, v126
	v_rcp_f32_e32 v151, v156
	v_mul_f32_e32 v125, 0xbfb8aa3b, v127
	v_exp_f32_e32 v124, v124
	v_exp_f32_e32 v125, v125
	v_mul_f32_e32 v116, v116, v151
	v_pk_mul_f32 v[154:155], v[116:117], v[112:113]
	v_pk_add_f32 v[124:125], v[124:125], 1.0 op_sel_hi:[1,0]
	s_nop 0
	v_rcp_f32_e32 v113, v125
	v_mul_f32_e32 v112, 0xbfb8aa3b, v118
	v_exp_f32_e32 v112, v112
	v_mul_f32_e32 v117, v127, v113
	v_rcp_f32_e32 v116, v124
	v_mul_f32_e32 v113, 0xbfb8aa3b, v119
	v_exp_f32_e32 v113, v113
	s_nop 0
	v_pk_add_f32 v[112:113], v[112:113], 1.0 op_sel_hi:[1,0]
	v_mul_f32_e32 v116, v126, v116
	v_pk_mul_f32 v[122:123], v[116:117], v[122:123]
	v_rcp_f32_e32 v116, v113
	s_nop 0
	v_mul_f32_e32 v113, v119, v116
	v_rcp_f32_e32 v116, v112
	s_nop 0
	v_mul_f32_e32 v112, v118, v116
	v_pk_mul_f32 v[124:125], v[112:113], v[114:115]
	v_mov_b64_e32 v[112:113], s[8:9]
	v_mad_i64_i32 v[116:117], s[24:25], v150, s47, v[112:113]
	v_lshlrev_b64 v[114:115], 1, v[152:153]
	v_lshl_add_u64 v[126:127], v[116:117], 0, v[114:115]
	v_mul_f32_e32 v117, 0xbfb8aa3b, v108
	v_cvt_pk_bf16_f32 v116, v120, v121
	v_exp_f32_e32 v120, v117
	v_mul_f32_e32 v117, 0xbfb8aa3b, v109
	v_exp_f32_e32 v121, v117
	v_cvt_pk_bf16_f32 v117, v122, v123
	v_cvt_pk_bf16_f32 v118, v154, v155
	v_cvt_pk_bf16_f32 v119, v124, v125
	v_pk_add_f32 v[120:121], v[120:121], 1.0 op_sel_hi:[1,0]
	global_store_dwordx4 v[126:127], v[116:119], off sc0 sc1
	s_nop 1
	v_rcp_f32_e32 v117, v121
	v_mul_f32_e32 v116, 0xbfb8aa3b, v100
	v_exp_f32_e32 v116, v116
	v_mul_f32_e32 v109, v109, v117
	v_rcp_f32_e32 v118, v120
	v_mul_f32_e32 v117, 0xbfb8aa3b, v101
	v_exp_f32_e32 v117, v117
	s_nop 0
	v_pk_add_f32 v[116:117], v[116:117], 1.0 op_sel_hi:[1,0]
	v_mul_f32_e32 v108, v108, v118
	v_pk_mul_f32 v[104:105], v[108:109], v[104:105]
	v_rcp_f32_e32 v108, v117
	s_nop 0
	v_mul_f32_e32 v101, v101, v108
	v_mul_f32_e32 v108, 0xbfb8aa3b, v110
	v_rcp_f32_e32 v117, v116
	v_mul_f32_e32 v109, 0xbfb8aa3b, v111
	v_exp_f32_e32 v108, v108
	v_exp_f32_e32 v109, v109
	v_mul_f32_e32 v100, v100, v117
	v_pk_mul_f32 v[100:101], v[100:101], v[96:97]
	v_pk_add_f32 v[108:109], v[108:109], 1.0 op_sel_hi:[1,0]
	s_nop 0
	v_rcp_f32_e32 v97, v109
	v_mul_f32_e32 v96, 0xbfb8aa3b, v102
	v_exp_f32_e32 v96, v96
	v_mul_f32_e32 v109, v111, v97
	v_rcp_f32_e32 v111, v108
	v_mul_f32_e32 v97, 0xbfb8aa3b, v103
	v_exp_f32_e32 v97, v97
	s_nop 0
	v_pk_add_f32 v[96:97], v[96:97], 1.0 op_sel_hi:[1,0]
	v_mul_f32_e32 v108, v110, v111
	v_pk_mul_f32 v[106:107], v[108:109], v[106:107]
	v_rcp_f32_e32 v108, v97
	s_nop 0
	v_mul_f32_e32 v97, v103, v108
	v_rcp_f32_e32 v103, v96
	s_nop 0
	v_mul_f32_e32 v96, v102, v103
	v_pk_mul_f32 v[102:103], v[96:97], v[98:99]
	v_add_u32_e32 v96, 16, v150
	v_mad_i64_i32 v[96:97], s[24:25], v96, s47, v[112:113]
	v_lshl_add_u64 v[108:109], v[96:97], 0, v[114:115]
	v_mul_f32_e32 v97, 0xbfb8aa3b, v92
	v_cvt_pk_bf16_f32 v96, v104, v105
	v_exp_f32_e32 v104, v97
	v_mul_f32_e32 v97, 0xbfb8aa3b, v93
	v_exp_f32_e32 v105, v97
	v_cvt_pk_bf16_f32 v98, v100, v101
	v_cvt_pk_bf16_f32 v99, v102, v103
	v_cvt_pk_bf16_f32 v97, v106, v107
	v_pk_add_f32 v[100:101], v[104:105], 1.0 op_sel_hi:[1,0]
	global_store_dwordx4 v[108:109], v[96:99], off sc0 sc1
	s_nop 1
	v_rcp_f32_e32 v97, v101
	v_mul_f32_e32 v96, 0xbfb8aa3b, v84
	v_exp_f32_e32 v96, v96
	v_mul_f32_e32 v93, v93, v97
	v_rcp_f32_e32 v98, v100
	v_mul_f32_e32 v97, 0xbfb8aa3b, v85
	v_exp_f32_e32 v97, v97
	s_nop 0
	v_pk_add_f32 v[96:97], v[96:97], 1.0 op_sel_hi:[1,0]
	v_mul_f32_e32 v92, v92, v98
	v_pk_mul_f32 v[88:89], v[92:93], v[88:89]
	v_rcp_f32_e32 v92, v97
	s_nop 0
	v_mul_f32_e32 v85, v85, v92
	v_mul_f32_e32 v92, 0xbfb8aa3b, v94
	v_rcp_f32_e32 v97, v96
	v_mul_f32_e32 v93, 0xbfb8aa3b, v95
	v_exp_f32_e32 v92, v92
	v_exp_f32_e32 v93, v93
	v_mul_f32_e32 v84, v84, v97
	v_pk_mul_f32 v[84:85], v[84:85], v[80:81]
	v_pk_add_f32 v[92:93], v[92:93], 1.0 op_sel_hi:[1,0]
	s_nop 0
	v_rcp_f32_e32 v81, v93
	v_mul_f32_e32 v80, 0xbfb8aa3b, v86
	v_exp_f32_e32 v80, v80
	v_mul_f32_e32 v93, v95, v81
	v_rcp_f32_e32 v95, v92
	v_mul_f32_e32 v81, 0xbfb8aa3b, v87
	v_exp_f32_e32 v81, v81
	s_nop 0
	v_pk_add_f32 v[80:81], v[80:81], 1.0 op_sel_hi:[1,0]
	v_mul_f32_e32 v92, v94, v95
	v_pk_mul_f32 v[90:91], v[92:93], v[90:91]
	v_rcp_f32_e32 v92, v81
	s_nop 0
	v_mul_f32_e32 v81, v87, v92
	v_rcp_f32_e32 v87, v80
	s_nop 0
	v_mul_f32_e32 v80, v86, v87
	v_pk_mul_f32 v[86:87], v[80:81], v[82:83]
	v_add_u32_e32 v80, 32, v150
	v_mad_i64_i32 v[80:81], s[24:25], v80, s47, v[112:113]
	v_lshl_add_u64 v[92:93], v[80:81], 0, v[114:115]
	v_mul_f32_e32 v81, 0xbfb8aa3b, v76
	v_cvt_pk_bf16_f32 v80, v88, v89
	v_exp_f32_e32 v88, v81
	v_mul_f32_e32 v81, 0xbfb8aa3b, v77
	v_exp_f32_e32 v89, v81
	v_cvt_pk_bf16_f32 v82, v84, v85
	v_cvt_pk_bf16_f32 v83, v86, v87
	v_cvt_pk_bf16_f32 v81, v90, v91
; DI float siluf_(float x) { return x / (1.f + __expf(-x)); }
; #define EPI_ROWS(...) _Pragma("unroll") for (int ai = 0; ai < 2; ++ai) _Pragma("unroll") for (int m = 0; m < 4; ++m) { const int row = u.pm * 256 + ai * 128 + wr * 64 + m * 16 + fr; __VA_ARGS__ }
; DI u32x4 pack8(f32x4 a, f32x4 b) { u32x4 w; w.x = pk2(a[0], a[1]); w.y = pk2(a[2], a[3]); w.z = pk2(b[0], b[1]); w.w = pk2(b[2], b[3]); return w; }
; DI void st16_wt(void* p, u32x4 v) { asm volatile("global_store_dwordx4 %0, %1, off sc0 sc1\n\ts_nop 1" :: "v"(p), "v"(v) : "memory"); }
;     DI void operator()(const Acc& acc, const Unit& u, int wr, int wc, int fr, int fq) const {
;         const int c0 = u.pn * 128 + wc * 32 + 8 * fq;
;         EPI_ROWS( f32x4 a, b;
;             _Pragma("unroll") for (int e = 0; e < 4; ++e) { a[e] = siluf_(acc[ai][0][m][0][e]) * acc[ai][1][m][0][e]; b[e] = siluf_(acc[ai][0][m][1][e]) * acc[ai][1][m][1][e]; }
;             st16_wt(H + (size_t)row * DFF + c0, pack8(a, b)); )
;     }
	v_pk_add_f32 v[84:85], v[88:89], 1.0 op_sel_hi:[1,0]
	global_store_dwordx4 v[92:93], v[80:83], off sc0 sc1
	s_nop 1
	v_rcp_f32_e32 v81, v85
	v_mul_f32_e32 v80, 0xbfb8aa3b, v68
	v_exp_f32_e32 v80, v80
	v_mul_f32_e32 v77, v77, v81
	v_rcp_f32_e32 v82, v84
	v_mul_f32_e32 v81, 0xbfb8aa3b, v69
	v_exp_f32_e32 v81, v81
	s_nop 0
	v_pk_add_f32 v[80:81], v[80:81], 1.0 op_sel_hi:[1,0]
	v_mul_f32_e32 v76, v76, v82
	v_pk_mul_f32 v[72:73], v[76:77], v[72:73]
	v_rcp_f32_e32 v76, v81
	s_nop 0
	v_mul_f32_e32 v69, v69, v76
	v_mul_f32_e32 v76, 0xbfb8aa3b, v78
	v_rcp_f32_e32 v81, v80
	v_mul_f32_e32 v77, 0xbfb8aa3b, v79
	v_exp_f32_e32 v76, v76
	v_exp_f32_e32 v77, v77
	v_mul_f32_e32 v68, v68, v81
	v_pk_mul_f32 v[68:69], v[68:69], v[64:65]
	v_pk_add_f32 v[76:77], v[76:77], 1.0 op_sel_hi:[1,0]
	s_nop 0
	v_rcp_f32_e32 v65, v77
	v_mul_f32_e32 v64, 0xbfb8aa3b, v70
	v_exp_f32_e32 v64, v64
	v_mul_f32_e32 v77, v79, v65
	v_rcp_f32_e32 v79, v76
	v_mul_f32_e32 v65, 0xbfb8aa3b, v71
	v_exp_f32_e32 v65, v65
	s_nop 0
	v_pk_add_f32 v[64:65], v[64:65], 1.0 op_sel_hi:[1,0]
	v_mul_f32_e32 v76, v78, v79
	v_pk_mul_f32 v[74:75], v[76:77], v[74:75]
	v_rcp_f32_e32 v76, v65
	s_nop 0
	v_mul_f32_e32 v65, v71, v76
	v_rcp_f32_e32 v71, v64
	s_nop 0
	v_mul_f32_e32 v64, v70, v71
	v_pk_mul_f32 v[70:71], v[64:65], v[66:67]
	v_add_u32_e32 v64, 48, v150
	v_mad_i64_i32 v[64:65], s[24:25], v64, s47, v[112:113]
	v_mul_f32_e32 v66, 0xbfb8aa3b, v60
	v_lshl_add_u64 v[76:77], v[64:65], 0, v[114:115]
	v_cvt_pk_bf16_f32 v64, v72, v73
	v_exp_f32_e32 v72, v66
	v_mul_f32_e32 v66, 0xbfb8aa3b, v61
	v_exp_f32_e32 v73, v66
	v_cvt_pk_bf16_f32 v65, v74, v75
	v_cvt_pk_bf16_f32 v66, v68, v69
	v_cvt_pk_bf16_f32 v67, v70, v71
	global_store_dwordx4 v[76:77], v[64:67], off sc0 sc1
	s_nop 1
	v_pk_add_f32 v[64:65], v[72:73], 1.0 op_sel_hi:[1,0]
	s_nop 0
	v_rcp_f32_e32 v67, v65
	v_mul_f32_e32 v66, 0xbfb8aa3b, v52
	v_exp_f32_e32 v66, v66
	v_add_u32_e32 v69, 0x80, v150
	v_mul_f32_e32 v61, v61, v67
	v_rcp_f32_e32 v65, v64
	v_mul_f32_e32 v67, 0xbfb8aa3b, v53
	v_exp_f32_e32 v67, v67
	s_nop 0
	v_pk_add_f32 v[66:67], v[66:67], 1.0 op_sel_hi:[1,0]
	v_mul_f32_e32 v60, v60, v65
	v_pk_mul_f32 v[56:57], v[60:61], v[56:57]
	v_rcp_f32_e32 v60, v67
	s_nop 0
	v_mul_f32_e32 v53, v53, v60
	v_mul_f32_e32 v60, 0xbfb8aa3b, v62
	v_rcp_f32_e32 v64, v66
	v_mul_f32_e32 v61, 0xbfb8aa3b, v63
	v_exp_f32_e32 v60, v60
	v_exp_f32_e32 v61, v61
	v_mul_f32_e32 v52, v52, v64
	v_pk_mul_f32 v[52:53], v[52:53], v[48:49]
	v_pk_add_f32 v[60:61], v[60:61], 1.0 op_sel_hi:[1,0]
	s_nop 0
	v_rcp_f32_e32 v49, v61
	v_mul_f32_e32 v48, 0xbfb8aa3b, v54
	v_exp_f32_e32 v48, v48
	v_mul_f32_e32 v61, v63, v49
	v_rcp_f32_e32 v63, v60
	v_mul_f32_e32 v49, 0xbfb8aa3b, v55
	v_exp_f32_e32 v49, v49
	s_nop 0
	v_pk_add_f32 v[48:49], v[48:49], 1.0 op_sel_hi:[1,0]
	v_mul_f32_e32 v60, v62, v63
	v_pk_mul_f32 v[58:59], v[60:61], v[58:59]
	v_rcp_f32_e32 v60, v49
	s_nop 0
	v_mul_f32_e32 v49, v55, v60
	v_rcp_f32_e32 v55, v48
	s_nop 0
	v_mul_f32_e32 v48, v54, v55
	v_pk_mul_f32 v[54:55], v[48:49], v[50:51]
	v_mad_i64_i32 v[48:49], s[24:25], v69, s47, v[112:113]
	v_lshl_add_u64 v[60:61], v[48:49], 0, v[114:115]
	v_mul_f32_e32 v49, 0xbfb8aa3b, v44
	v_cvt_pk_bf16_f32 v48, v56, v57
	v_exp_f32_e32 v56, v49
	v_mul_f32_e32 v49, 0xbfb8aa3b, v45
	v_exp_f32_e32 v57, v49
	v_cvt_pk_bf16_f32 v50, v52, v53
	v_cvt_pk_bf16_f32 v51, v54, v55
	v_cvt_pk_bf16_f32 v49, v58, v59
	v_pk_add_f32 v[52:53], v[56:57], 1.0 op_sel_hi:[1,0]
	global_store_dwordx4 v[60:61], v[48:51], off sc0 sc1
	s_nop 1
	v_rcp_f32_e32 v49, v53
	v_mul_f32_e32 v48, 0xbfb8aa3b, v36
	v_exp_f32_e32 v48, v48
	v_mul_f32_e32 v45, v45, v49
	v_rcp_f32_e32 v50, v52
	v_mul_f32_e32 v49, 0xbfb8aa3b, v37
	v_exp_f32_e32 v49, v49
	s_nop 0
	v_pk_add_f32 v[48:49], v[48:49], 1.0 op_sel_hi:[1,0]
	v_mul_f32_e32 v44, v44, v50
	v_pk_mul_f32 v[40:41], v[44:45], v[40:41]
	v_rcp_f32_e32 v44, v49
	s_nop 0
	v_mul_f32_e32 v37, v37, v44
	v_mul_f32_e32 v44, 0xbfb8aa3b, v46
	v_rcp_f32_e32 v49, v48
	v_mul_f32_e32 v45, 0xbfb8aa3b, v47
	v_exp_f32_e32 v44, v44
	v_exp_f32_e32 v45, v45
	v_mul_f32_e32 v36, v36, v49
	v_pk_mul_f32 v[36:37], v[36:37], v[32:33]
	v_pk_add_f32 v[44:45], v[44:45], 1.0 op_sel_hi:[1,0]
	s_nop 0
	v_rcp_f32_e32 v33, v45
	v_mul_f32_e32 v32, 0xbfb8aa3b, v38
; DI float siluf_(float x) { return x / (1.f + __expf(-x)); }
; #define PG8_BAR __builtin_amdgcn_s_barrier()
; #define EPI_ROWS(...) _Pragma("unroll") for (int ai = 0; ai < 2; ++ai) _Pragma("unroll") for (int m = 0; m < 4; ++m) { const int row = u.pm * 256 + ai * 128 + wr * 64 + m * 16 + fr; __VA_ARGS__ }
; DI void st16_wt(void* p, u32x4 v) { asm volatile("global_store_dwordx4 %0, %1, off sc0 sc1\n\ts_nop 1" :: "v"(p), "v"(v) : "memory"); }
; DI u32x4 pack8(f32x4 a, f32x4 b) { u32x4 w; w.x = pk2(a[0], a[1]); w.y = pk2(a[2], a[3]); w.z = pk2(b[0], b[1]); w.w = pk2(b[2], b[3]); return w; }
; template <class Epi>
; DI void gemm_phase(int wv, LAS unsigned char* lds, const Gemm g, const StaticOrder& S, const Epi& E) {
;     ...
;         if (wr == 0) PG8_BAR;
;         { int fr2 = fr, fq2 = fq; asm volatile("" : "+v"(fr2), "+v"(fq2)); E(acc, cur, wr, wc, fr2, fq2); }
;         if (!has_next) break;
; #pragma unroll
;         for (int a = 0; a < 2; ++a)
; #pragma unroll
;             for (int b = 0; b < 2; ++b)
; #pragma unroll
;                 for (int m = 0; m < 4; ++m)
; #pragma unroll
;                     for (int n = 0; n < 2; ++n) acc[a][b][m][n] = (f32x4){0.f, 0.f, 0.f, 0.f};
;         cur = nxt; cA = nA; cB = nB; ++ui;
;         if (wr == 1) PG8_BAR;
;     DI void operator()(const Acc& acc, const Unit& u, int wr, int wc, int fr, int fq) const {
;         const int c0 = u.pn * 128 + wc * 32 + 8 * fq;
;         EPI_ROWS( f32x4 a, b;
;             _Pragma("unroll") for (int e = 0; e < 4; ++e) { a[e] = siluf_(acc[ai][0][m][0][e]) * acc[ai][1][m][0][e]; b[e] = siluf_(acc[ai][0][m][1][e]) * acc[ai][1][m][1][e]; }
;             st16_wt(H + (size_t)row * DFF + c0, pack8(a, b)); )
;     }
	v_exp_f32_e32 v32, v32
	v_mul_f32_e32 v45, v47, v33
	v_rcp_f32_e32 v47, v44
	v_mul_f32_e32 v33, 0xbfb8aa3b, v39
	v_exp_f32_e32 v33, v33
	s_nop 0
	v_pk_add_f32 v[32:33], v[32:33], 1.0 op_sel_hi:[1,0]
	v_mul_f32_e32 v44, v46, v47
	v_pk_mul_f32 v[42:43], v[44:45], v[42:43]
	v_rcp_f32_e32 v44, v33
	s_nop 0
	v_mul_f32_e32 v33, v39, v44
	v_rcp_f32_e32 v39, v32
	s_nop 0
	v_mul_f32_e32 v32, v38, v39
	v_pk_mul_f32 v[38:39], v[32:33], v[34:35]
	v_add_u32_e32 v32, 0x90, v150
	v_mad_i64_i32 v[32:33], s[24:25], v32, s47, v[112:113]
	v_lshl_add_u64 v[44:45], v[32:33], 0, v[114:115]
	v_mul_f32_e32 v33, 0xbfb8aa3b, v28
	v_cvt_pk_bf16_f32 v32, v40, v41
	v_exp_f32_e32 v40, v33
	v_mul_f32_e32 v33, 0xbfb8aa3b, v29
	v_exp_f32_e32 v41, v33
	v_cvt_pk_bf16_f32 v34, v36, v37
	v_cvt_pk_bf16_f32 v35, v38, v39
	v_cvt_pk_bf16_f32 v33, v42, v43
	v_pk_add_f32 v[36:37], v[40:41], 1.0 op_sel_hi:[1,0]
	global_store_dwordx4 v[44:45], v[32:35], off sc0 sc1
	s_nop 1
	v_rcp_f32_e32 v33, v37
	v_mul_f32_e32 v32, 0xbfb8aa3b, v20
	v_exp_f32_e32 v32, v32
	v_mul_f32_e32 v29, v29, v33
	v_rcp_f32_e32 v34, v36
	v_mul_f32_e32 v33, 0xbfb8aa3b, v21
	v_exp_f32_e32 v33, v33
	s_nop 0
	v_pk_add_f32 v[32:33], v[32:33], 1.0 op_sel_hi:[1,0]
	v_mul_f32_e32 v28, v28, v34
	v_pk_mul_f32 v[24:25], v[28:29], v[24:25]
	v_rcp_f32_e32 v28, v33
	s_nop 0
	v_mul_f32_e32 v21, v21, v28
	v_mul_f32_e32 v28, 0xbfb8aa3b, v30
	v_rcp_f32_e32 v33, v32
	v_mul_f32_e32 v29, 0xbfb8aa3b, v31
	v_exp_f32_e32 v28, v28
	v_exp_f32_e32 v29, v29
	v_mul_f32_e32 v20, v20, v33
	v_pk_mul_f32 v[20:21], v[20:21], v[16:17]
	v_pk_add_f32 v[28:29], v[28:29], 1.0 op_sel_hi:[1,0]
	s_nop 0
	v_rcp_f32_e32 v17, v29
	v_mul_f32_e32 v16, 0xbfb8aa3b, v22
	v_exp_f32_e32 v16, v16
	v_mul_f32_e32 v29, v31, v17
	v_rcp_f32_e32 v31, v28
	v_mul_f32_e32 v17, 0xbfb8aa3b, v23
	v_exp_f32_e32 v17, v17
	s_nop 0
	v_pk_add_f32 v[16:17], v[16:17], 1.0 op_sel_hi:[1,0]
	v_mul_f32_e32 v28, v30, v31
	v_pk_mul_f32 v[26:27], v[28:29], v[26:27]
	v_rcp_f32_e32 v28, v17
	s_nop 0
	v_mul_f32_e32 v17, v23, v28
	v_rcp_f32_e32 v23, v16
	s_nop 0
	v_mul_f32_e32 v16, v22, v23
	v_pk_mul_f32 v[22:23], v[16:17], v[18:19]
	v_add_u32_e32 v16, 0xa0, v150
	v_mad_i64_i32 v[16:17], s[24:25], v16, s47, v[112:113]
	v_lshl_add_u64 v[28:29], v[16:17], 0, v[114:115]
	v_mul_f32_e32 v17, 0xbfb8aa3b, v12
	v_cvt_pk_bf16_f32 v16, v24, v25
	v_exp_f32_e32 v24, v17
	v_mul_f32_e32 v17, 0xbfb8aa3b, v13
	v_exp_f32_e32 v25, v17
	v_cvt_pk_bf16_f32 v18, v20, v21
	v_cvt_pk_bf16_f32 v19, v22, v23
	v_cvt_pk_bf16_f32 v17, v26, v27
	v_pk_add_f32 v[20:21], v[24:25], 1.0 op_sel_hi:[1,0]
	global_store_dwordx4 v[28:29], v[16:19], off sc0 sc1
	s_nop 1
	v_rcp_f32_e32 v17, v21
	v_mul_f32_e32 v16, 0xbfb8aa3b, v4
	v_exp_f32_e32 v16, v16
	v_mul_f32_e32 v13, v13, v17
	v_rcp_f32_e32 v18, v20
	v_mul_f32_e32 v17, 0xbfb8aa3b, v5
	v_exp_f32_e32 v17, v17
	s_nop 0
	v_pk_add_f32 v[16:17], v[16:17], 1.0 op_sel_hi:[1,0]
	v_mul_f32_e32 v12, v12, v18
	v_pk_mul_f32 v[8:9], v[12:13], v[8:9]
	v_rcp_f32_e32 v12, v17
	s_nop 0
	v_mul_f32_e32 v5, v5, v12
	v_mul_f32_e32 v12, 0xbfb8aa3b, v14
	v_rcp_f32_e32 v17, v16
	v_mul_f32_e32 v13, 0xbfb8aa3b, v15
	v_exp_f32_e32 v12, v12
	v_exp_f32_e32 v13, v13
	v_mul_f32_e32 v4, v4, v17
	v_pk_mul_f32 v[4:5], v[4:5], v[0:1]
	v_pk_add_f32 v[12:13], v[12:13], 1.0 op_sel_hi:[1,0]
	s_nop 0
	v_rcp_f32_e32 v1, v13
	v_mul_f32_e32 v0, 0xbfb8aa3b, v6
	v_exp_f32_e32 v0, v0
	v_mul_f32_e32 v13, v15, v1
	v_rcp_f32_e32 v15, v12
	v_mul_f32_e32 v1, 0xbfb8aa3b, v7
	v_exp_f32_e32 v1, v1
	s_nop 0
	v_pk_add_f32 v[0:1], v[0:1], 1.0 op_sel_hi:[1,0]
	v_mul_f32_e32 v12, v14, v15
	v_pk_mul_f32 v[10:11], v[12:13], v[10:11]
	v_rcp_f32_e32 v12, v1
	s_nop 0
	v_mul_f32_e32 v1, v7, v12
	v_rcp_f32_e32 v7, v0
	s_nop 0
	v_mul_f32_e32 v0, v6, v7
	v_pk_mul_f32 v[6:7], v[0:1], v[2:3]
	v_add_u32_e32 v0, 0xb0, v150
	v_mad_i64_i32 v[0:1], s[24:25], v0, s47, v[112:113]
	v_lshl_add_u64 v[12:13], v[0:1], 0, v[114:115]
	v_cvt_pk_bf16_f32 v0, v8, v9
	v_cvt_pk_bf16_f32 v1, v10, v11
	v_cvt_pk_bf16_f32 v2, v4, v5
	v_cvt_pk_bf16_f32 v3, v6, v7
	global_store_dwordx4 v[12:13], v[0:3], off sc0 sc1
	s_nop 1
	s_andn2_b64 vcc, exec, s[2:3]
	s_mov_b64 s[2:3], -1
	s_cbranch_vccnz .LBB0_2377
	s_andn2_b64 vcc, exec, s[6:7]
	s_cbranch_vccnz .LBB0_2376
	s_barrier
	s_branch .LBB0_2376

; DI float sigmoidf_(float x) { return 1.f / (1.f + __expf(-x)); }
; #define EPI_ROWS(...) _Pragma("unroll") for (int ai = 0; ai < 2; ++ai) _Pragma("unroll") for (int m = 0; m < 4; ++m) { const int row = u.pm * 256 + ai * 128 + wr * 64 + m * 16 + fr; __VA_ARGS__ }
; DI u32x4 pack8(f32x4 a, f32x4 b) { u32x4 w; w.x = pk2(a[0], a[1]); w.y = pk2(a[2], a[3]); w.z = pk2(b[0], b[1]); w.w = pk2(b[2], b[3]); return w; }
; DI float tanh_fast(float x) { const float e = __expf(2.f * x); return 1.f - 2.f / (e + 1.f); }
;     DI void operator()(const Acc& acc, const Unit& u, int wr, int wc, int fr, int fq) const {
;     ...
;             EPI_ROWS( _Pragma("unroll") for (int bj = 0; bj < 2; ++bj) { const int c0 = (pn - 12) * 256 + bj * 128 + wc * 32 + 8 * fq; f32x4 a = acc[ai][bj][m][0], b = acc[ai][bj][m][1];
;                     if (c0 < 64) { _Pragma("unroll") for (int e = 0; e < 4; ++e) { a[e] = tanh_fast(a[e]); b[e] = tanh_fast(b[e]); } }
;                     else if (c0 >= 128) { _Pragma("unroll") for (int e = 0; e < 4; ++e) { a[e] = sigmoidf_(a[e]); b[e] = sigmoidf_(b[e]); } }
;                     *(u32x4*)(LH + (size_t)row * 512 + c0) = pack8(a, b); } )
.LBB0_2879:
	s_andn2_saveexec_b64 s[6:7], s[6:7]
	s_cbranch_execz .LBB0_2881
	v_add_f32_e32 v129, v120, v120
	v_mul_f32_e32 v129, 0x3fb8aa3b, v129
	v_add_f32_e32 v128, v124, v124
	v_exp_f32_e32 v132, v129
	v_add_f32_e32 v129, v125, v125
	v_mul_f32_e32 v128, 0x3fb8aa3b, v128
	v_mul_f32_e32 v129, 0x3fb8aa3b, v129
	v_exp_f32_e32 v128, v128
	v_exp_f32_e32 v129, v129
	v_add_f32_e32 v130, v121, v121
	v_mul_f32_e32 v130, 0x3fb8aa3b, v130
	v_exp_f32_e32 v133, v130
	v_pk_add_f32 v[128:129], v[128:129], 1.0 op_sel_hi:[1,0]
	v_add_f32_e32 v130, v126, v126
	v_add_f32_e32 v131, v127, v127
	v_mul_f32_e32 v130, 0x3fb8aa3b, v130
	v_rcp_f32_e32 v135, v128
	v_mul_f32_e32 v131, 0x3fb8aa3b, v131
	v_exp_f32_e32 v130, v130
	v_exp_f32_e32 v131, v131
	v_mul_f32_e32 v128, 2.0, v135
	v_rcp_f32_e32 v135, v129
	v_pk_add_f32 v[130:131], v[130:131], 1.0 op_sel_hi:[1,0]
	v_mul_f32_e32 v129, 2.0, v135
	v_rcp_f32_e32 v135, v130
	v_pk_add_f32 v[132:133], v[132:133], 1.0 op_sel_hi:[1,0]
	v_mul_f32_e32 v130, 2.0, v135
	v_rcp_f32_e32 v135, v131
	v_add_f32_e32 v134, v122, v122
	v_mul_f32_e32 v131, 2.0, v135
	v_add_f32_e32 v135, v123, v123
	v_mul_f32_e32 v134, 0x3fb8aa3b, v134
	v_rcp_f32_e32 v153, v132
	v_mul_f32_e32 v135, 0x3fb8aa3b, v135
	v_exp_f32_e32 v134, v134
	v_exp_f32_e32 v135, v135
	v_mul_f32_e32 v132, 2.0, v153
	v_rcp_f32_e32 v153, v133
	v_pk_add_f32 v[134:135], v[134:135], 1.0 op_sel_hi:[1,0]
	v_mul_f32_e32 v133, 2.0, v153
	v_rcp_f32_e32 v153, v134
	v_sub_f32_e32 v131, 1.0, v131
	v_mul_f32_e32 v134, 2.0, v153
	v_rcp_f32_e32 v153, v135
	v_sub_f32_e32 v130, 1.0, v130
	v_mul_f32_e32 v135, 2.0, v153
	v_sub_f32_e32 v129, 1.0, v129
	v_sub_f32_e32 v128, 1.0, v128
	v_sub_f32_e32 v135, 1.0, v135
	v_sub_f32_e32 v134, 1.0, v134
	v_sub_f32_e32 v133, 1.0, v133
	v_sub_f32_e32 v132, 1.0, v132

; DI float sigmoidf_(float x) { return 1.f / (1.f + __expf(-x)); }
; #define EPI_ROWS(...) _Pragma("unroll") for (int ai = 0; ai < 2; ++ai) _Pragma("unroll") for (int m = 0; m < 4; ++m) { const int row = u.pm * 256 + ai * 128 + wr * 64 + m * 16 + fr; __VA_ARGS__ }
; DI u32x4 pack8(f32x4 a, f32x4 b) { u32x4 w; w.x = pk2(a[0], a[1]); w.y = pk2(a[2], a[3]); w.z = pk2(b[0], b[1]); w.w = pk2(b[2], b[3]); return w; }
; DI float tanh_fast(float x) { const float e = __expf(2.f * x); return 1.f - 2.f / (e + 1.f); }
;     DI void operator()(const Acc& acc, const Unit& u, int wr, int wc, int fr, int fq) const {
;     ...
;             EPI_ROWS( _Pragma("unroll") for (int bj = 0; bj < 2; ++bj) { const int c0 = (pn - 12) * 256 + bj * 128 + wc * 32 + 8 * fq; f32x4 a = acc[ai][bj][m][0], b = acc[ai][bj][m][1];
;                     if (c0 < 64) { _Pragma("unroll") for (int e = 0; e < 4; ++e) { a[e] = tanh_fast(a[e]); b[e] = tanh_fast(b[e]); } }
;                     else if (c0 >= 128) { _Pragma("unroll") for (int e = 0; e < 4; ++e) { a[e] = sigmoidf_(a[e]); b[e] = sigmoidf_(b[e]); } }
;                     *(u32x4*)(LH + (size_t)row * 512 + c0) = pack8(a, b); } )
.LBB0_2885:
	s_andn2_saveexec_b64 s[34:35], s[34:35]
	s_cbranch_execz .LBB0_2887
	v_add_f32_e32 v129, v104, v104
	v_mul_f32_e32 v129, 0x3fb8aa3b, v129
	v_add_f32_e32 v128, v108, v108
	v_exp_f32_e32 v132, v129
	v_add_f32_e32 v129, v109, v109
	v_mul_f32_e32 v128, 0x3fb8aa3b, v128
	v_mul_f32_e32 v129, 0x3fb8aa3b, v129
	v_exp_f32_e32 v128, v128
	v_exp_f32_e32 v129, v129
	v_add_f32_e32 v130, v105, v105
	v_mul_f32_e32 v130, 0x3fb8aa3b, v130
	v_exp_f32_e32 v133, v130
	v_pk_add_f32 v[128:129], v[128:129], 1.0 op_sel_hi:[1,0]
	v_add_f32_e32 v130, v110, v110
	v_add_f32_e32 v131, v111, v111
	v_mul_f32_e32 v130, 0x3fb8aa3b, v130
	v_rcp_f32_e32 v135, v128
	v_mul_f32_e32 v131, 0x3fb8aa3b, v131
	v_exp_f32_e32 v130, v130
	v_exp_f32_e32 v131, v131
	v_mul_f32_e32 v128, 2.0, v135
	v_rcp_f32_e32 v135, v129
	v_pk_add_f32 v[130:131], v[130:131], 1.0 op_sel_hi:[1,0]
	v_mul_f32_e32 v129, 2.0, v135
	v_rcp_f32_e32 v135, v130
	v_pk_add_f32 v[132:133], v[132:133], 1.0 op_sel_hi:[1,0]
	v_mul_f32_e32 v130, 2.0, v135
	v_rcp_f32_e32 v135, v131
	v_add_f32_e32 v134, v106, v106
	v_mul_f32_e32 v131, 2.0, v135
	v_add_f32_e32 v135, v107, v107
	v_mul_f32_e32 v134, 0x3fb8aa3b, v134
	v_rcp_f32_e32 v155, v132
	v_mul_f32_e32 v135, 0x3fb8aa3b, v135
	v_exp_f32_e32 v134, v134
	v_exp_f32_e32 v135, v135
	v_mul_f32_e32 v132, 2.0, v155
	v_rcp_f32_e32 v155, v133
	v_pk_add_f32 v[134:135], v[134:135], 1.0 op_sel_hi:[1,0]
	v_mul_f32_e32 v133, 2.0, v155
	v_rcp_f32_e32 v155, v134
	v_sub_f32_e32 v131, 1.0, v131
	v_mul_f32_e32 v134, 2.0, v155
	v_rcp_f32_e32 v155, v135
	v_sub_f32_e32 v130, 1.0, v130
	v_mul_f32_e32 v135, 2.0, v155
	v_sub_f32_e32 v129, 1.0, v129
	v_sub_f32_e32 v128, 1.0, v128
	v_sub_f32_e32 v135, 1.0, v135
	v_sub_f32_e32 v134, 1.0, v134
	v_sub_f32_e32 v133, 1.0, v133
	v_sub_f32_e32 v132, 1.0, v132

; DI float sigmoidf_(float x) { return 1.f / (1.f + __expf(-x)); }
; #define EPI_ROWS(...) _Pragma("unroll") for (int ai = 0; ai < 2; ++ai) _Pragma("unroll") for (int m = 0; m < 4; ++m) { const int row = u.pm * 256 + ai * 128 + wr * 64 + m * 16 + fr; __VA_ARGS__ }
; DI u32x4 pack8(f32x4 a, f32x4 b) { u32x4 w; w.x = pk2(a[0], a[1]); w.y = pk2(a[2], a[3]); w.z = pk2(b[0], b[1]); w.w = pk2(b[2], b[3]); return w; }
; DI float tanh_fast(float x) { const float e = __expf(2.f * x); return 1.f - 2.f / (e + 1.f); }
;     DI void operator()(const Acc& acc, const Unit& u, int wr, int wc, int fr, int fq) const {
;     ...
;             EPI_ROWS( _Pragma("unroll") for (int bj = 0; bj < 2; ++bj) { const int c0 = (pn - 12) * 256 + bj * 128 + wc * 32 + 8 * fq; f32x4 a = acc[ai][bj][m][0], b = acc[ai][bj][m][1];
;                     if (c0 < 64) { _Pragma("unroll") for (int e = 0; e < 4; ++e) { a[e] = tanh_fast(a[e]); b[e] = tanh_fast(b[e]); } }
;                     else if (c0 >= 128) { _Pragma("unroll") for (int e = 0; e < 4; ++e) { a[e] = sigmoidf_(a[e]); b[e] = sigmoidf_(b[e]); } }
;                     *(u32x4*)(LH + (size_t)row * 512 + c0) = pack8(a, b); } )
.LBB0_2891:
	s_andn2_saveexec_b64 s[34:35], s[34:35]
	s_cbranch_execz .LBB0_2893
	v_add_f32_e32 v129, v112, v112
	v_mul_f32_e32 v129, 0x3fb8aa3b, v129
	v_add_f32_e32 v128, v116, v116
	v_exp_f32_e32 v132, v129
	v_add_f32_e32 v129, v117, v117
	v_mul_f32_e32 v128, 0x3fb8aa3b, v128
	v_mul_f32_e32 v129, 0x3fb8aa3b, v129
	v_exp_f32_e32 v128, v128
	v_exp_f32_e32 v129, v129
	v_add_f32_e32 v130, v113, v113
	v_mul_f32_e32 v130, 0x3fb8aa3b, v130
	v_exp_f32_e32 v133, v130
	v_pk_add_f32 v[128:129], v[128:129], 1.0 op_sel_hi:[1,0]
	v_add_f32_e32 v130, v118, v118
	v_add_f32_e32 v131, v119, v119
	v_mul_f32_e32 v130, 0x3fb8aa3b, v130
	v_rcp_f32_e32 v135, v128
	v_mul_f32_e32 v131, 0x3fb8aa3b, v131
	v_exp_f32_e32 v130, v130
	v_exp_f32_e32 v131, v131
	v_mul_f32_e32 v128, 2.0, v135
	v_rcp_f32_e32 v135, v129
	v_pk_add_f32 v[130:131], v[130:131], 1.0 op_sel_hi:[1,0]
	v_mul_f32_e32 v129, 2.0, v135
	v_rcp_f32_e32 v135, v130
	v_pk_add_f32 v[132:133], v[132:133], 1.0 op_sel_hi:[1,0]
	v_mul_f32_e32 v130, 2.0, v135
	v_rcp_f32_e32 v135, v131
	v_add_f32_e32 v134, v114, v114
	v_mul_f32_e32 v131, 2.0, v135
	v_add_f32_e32 v135, v115, v115
	v_mul_f32_e32 v134, 0x3fb8aa3b, v134
	v_rcp_f32_e32 v155, v132
	v_mul_f32_e32 v135, 0x3fb8aa3b, v135
	v_exp_f32_e32 v134, v134
	v_exp_f32_e32 v135, v135
	v_mul_f32_e32 v132, 2.0, v155
	v_rcp_f32_e32 v155, v133
	v_pk_add_f32 v[134:135], v[134:135], 1.0 op_sel_hi:[1,0]
	v_mul_f32_e32 v133, 2.0, v155
	v_rcp_f32_e32 v155, v134
	v_sub_f32_e32 v131, 1.0, v131
	v_mul_f32_e32 v134, 2.0, v155
	v_rcp_f32_e32 v155, v135
	v_sub_f32_e32 v130, 1.0, v130
	v_mul_f32_e32 v135, 2.0, v155
	v_sub_f32_e32 v129, 1.0, v129
	v_sub_f32_e32 v128, 1.0, v128
	v_sub_f32_e32 v135, 1.0, v135
	v_sub_f32_e32 v134, 1.0, v134
	v_sub_f32_e32 v133, 1.0, v133
	v_sub_f32_e32 v132, 1.0, v132

; DI float sigmoidf_(float x) { return 1.f / (1.f + __expf(-x)); }
; #define EPI_ROWS(...) _Pragma("unroll") for (int ai = 0; ai < 2; ++ai) _Pragma("unroll") for (int m = 0; m < 4; ++m) { const int row = u.pm * 256 + ai * 128 + wr * 64 + m * 16 + fr; __VA_ARGS__ }
; DI u32x4 pack8(f32x4 a, f32x4 b) { u32x4 w; w.x = pk2(a[0], a[1]); w.y = pk2(a[2], a[3]); w.z = pk2(b[0], b[1]); w.w = pk2(b[2], b[3]); return w; }
; DI float tanh_fast(float x) { const float e = __expf(2.f * x); return 1.f - 2.f / (e + 1.f); }
;     DI void operator()(const Acc& acc, const Unit& u, int wr, int wc, int fr, int fq) const {
;     ...
;             EPI_ROWS( _Pragma("unroll") for (int bj = 0; bj < 2; ++bj) { const int c0 = (pn - 12) * 256 + bj * 128 + wc * 32 + 8 * fq; f32x4 a = acc[ai][bj][m][0], b = acc[ai][bj][m][1];
;                     if (c0 < 64) { _Pragma("unroll") for (int e = 0; e < 4; ++e) { a[e] = tanh_fast(a[e]); b[e] = tanh_fast(b[e]); } }
;                     else if (c0 >= 128) { _Pragma("unroll") for (int e = 0; e < 4; ++e) { a[e] = sigmoidf_(a[e]); b[e] = sigmoidf_(b[e]); } }
;                     *(u32x4*)(LH + (size_t)row * 512 + c0) = pack8(a, b); } )
.LBB0_2897:
	s_andn2_saveexec_b64 s[34:35], s[34:35]
	s_cbranch_execz .LBB0_2899
	v_add_f32_e32 v129, v88, v88
	v_mul_f32_e32 v129, 0x3fb8aa3b, v129
	v_add_f32_e32 v128, v92, v92
	v_exp_f32_e32 v132, v129
	v_add_f32_e32 v129, v93, v93
	v_mul_f32_e32 v128, 0x3fb8aa3b, v128
	v_mul_f32_e32 v129, 0x3fb8aa3b, v129
	v_exp_f32_e32 v128, v128
	v_exp_f32_e32 v129, v129
	v_add_f32_e32 v130, v89, v89
	v_mul_f32_e32 v130, 0x3fb8aa3b, v130
	v_exp_f32_e32 v133, v130
	v_pk_add_f32 v[128:129], v[128:129], 1.0 op_sel_hi:[1,0]
	v_add_f32_e32 v130, v94, v94
	v_add_f32_e32 v131, v95, v95
	v_mul_f32_e32 v130, 0x3fb8aa3b, v130
	v_rcp_f32_e32 v135, v128
	v_mul_f32_e32 v131, 0x3fb8aa3b, v131
	v_exp_f32_e32 v130, v130
	v_exp_f32_e32 v131, v131
	v_mul_f32_e32 v128, 2.0, v135
	v_rcp_f32_e32 v135, v129
	v_pk_add_f32 v[130:131], v[130:131], 1.0 op_sel_hi:[1,0]
	v_mul_f32_e32 v129, 2.0, v135
	v_rcp_f32_e32 v135, v130
	v_pk_add_f32 v[132:133], v[132:133], 1.0 op_sel_hi:[1,0]
	v_mul_f32_e32 v130, 2.0, v135
	v_rcp_f32_e32 v135, v131
	v_add_f32_e32 v134, v90, v90
	v_mul_f32_e32 v131, 2.0, v135
	v_add_f32_e32 v135, v91, v91
	v_mul_f32_e32 v134, 0x3fb8aa3b, v134
	v_rcp_f32_e32 v155, v132
	v_mul_f32_e32 v135, 0x3fb8aa3b, v135
	v_exp_f32_e32 v134, v134
	v_exp_f32_e32 v135, v135
	v_mul_f32_e32 v132, 2.0, v155
	v_rcp_f32_e32 v155, v133
	v_pk_add_f32 v[134:135], v[134:135], 1.0 op_sel_hi:[1,0]
	v_mul_f32_e32 v133, 2.0, v155
	v_rcp_f32_e32 v155, v134
	v_sub_f32_e32 v131, 1.0, v131
	v_mul_f32_e32 v134, 2.0, v155
	v_rcp_f32_e32 v155, v135
	v_sub_f32_e32 v130, 1.0, v130
	v_mul_f32_e32 v135, 2.0, v155
	v_sub_f32_e32 v129, 1.0, v129
	v_sub_f32_e32 v128, 1.0, v128
	v_sub_f32_e32 v135, 1.0, v135
	v_sub_f32_e32 v134, 1.0, v134
	v_sub_f32_e32 v133, 1.0, v133
	v_sub_f32_e32 v132, 1.0, v132

; DI float sigmoidf_(float x) { return 1.f / (1.f + __expf(-x)); }
; #define EPI_ROWS(...) _Pragma("unroll") for (int ai = 0; ai < 2; ++ai) _Pragma("unroll") for (int m = 0; m < 4; ++m) { const int row = u.pm * 256 + ai * 128 + wr * 64 + m * 16 + fr; __VA_ARGS__ }
; DI u32x4 pack8(f32x4 a, f32x4 b) { u32x4 w; w.x = pk2(a[0], a[1]); w.y = pk2(a[2], a[3]); w.z = pk2(b[0], b[1]); w.w = pk2(b[2], b[3]); return w; }
; DI float tanh_fast(float x) { const float e = __expf(2.f * x); return 1.f - 2.f / (e + 1.f); }
;     DI void operator()(const Acc& acc, const Unit& u, int wr, int wc, int fr, int fq) const {
;     ...
;             EPI_ROWS( _Pragma("unroll") for (int bj = 0; bj < 2; ++bj) { const int c0 = (pn - 12) * 256 + bj * 128 + wc * 32 + 8 * fq; f32x4 a = acc[ai][bj][m][0], b = acc[ai][bj][m][1];
;                     if (c0 < 64) { _Pragma("unroll") for (int e = 0; e < 4; ++e) { a[e] = tanh_fast(a[e]); b[e] = tanh_fast(b[e]); } }
;                     else if (c0 >= 128) { _Pragma("unroll") for (int e = 0; e < 4; ++e) { a[e] = sigmoidf_(a[e]); b[e] = sigmoidf_(b[e]); } }
;                     *(u32x4*)(LH + (size_t)row * 512 + c0) = pack8(a, b); } )
.LBB0_2903:
	s_andn2_saveexec_b64 s[34:35], s[34:35]
	s_cbranch_execz .LBB0_2905
	v_add_f32_e32 v129, v96, v96
	v_mul_f32_e32 v129, 0x3fb8aa3b, v129
	v_add_f32_e32 v128, v100, v100
	v_exp_f32_e32 v132, v129
	v_add_f32_e32 v129, v101, v101
	v_mul_f32_e32 v128, 0x3fb8aa3b, v128
	v_mul_f32_e32 v129, 0x3fb8aa3b, v129
	v_exp_f32_e32 v128, v128
	v_exp_f32_e32 v129, v129
	v_add_f32_e32 v130, v97, v97
	v_mul_f32_e32 v130, 0x3fb8aa3b, v130
	v_exp_f32_e32 v133, v130
	v_pk_add_f32 v[128:129], v[128:129], 1.0 op_sel_hi:[1,0]
	v_add_f32_e32 v130, v102, v102
	v_add_f32_e32 v131, v103, v103
	v_mul_f32_e32 v130, 0x3fb8aa3b, v130
	v_rcp_f32_e32 v135, v128
	v_mul_f32_e32 v131, 0x3fb8aa3b, v131
	v_exp_f32_e32 v130, v130
	v_exp_f32_e32 v131, v131
	v_mul_f32_e32 v128, 2.0, v135
	v_rcp_f32_e32 v135, v129
	v_pk_add_f32 v[130:131], v[130:131], 1.0 op_sel_hi:[1,0]
	v_mul_f32_e32 v129, 2.0, v135
	v_rcp_f32_e32 v135, v130
	v_pk_add_f32 v[132:133], v[132:133], 1.0 op_sel_hi:[1,0]
	v_mul_f32_e32 v130, 2.0, v135
	v_rcp_f32_e32 v135, v131
	v_add_f32_e32 v134, v98, v98
	v_mul_f32_e32 v131, 2.0, v135
	v_add_f32_e32 v135, v99, v99
	v_mul_f32_e32 v134, 0x3fb8aa3b, v134
	v_rcp_f32_e32 v155, v132
	v_mul_f32_e32 v135, 0x3fb8aa3b, v135
	v_exp_f32_e32 v134, v134
	v_exp_f32_e32 v135, v135
	v_mul_f32_e32 v132, 2.0, v155
	v_rcp_f32_e32 v155, v133
	v_pk_add_f32 v[134:135], v[134:135], 1.0 op_sel_hi:[1,0]
	v_mul_f32_e32 v133, 2.0, v155
	v_rcp_f32_e32 v155, v134
	v_sub_f32_e32 v131, 1.0, v131
	v_mul_f32_e32 v134, 2.0, v155
	v_rcp_f32_e32 v155, v135
	v_sub_f32_e32 v130, 1.0, v130
	v_mul_f32_e32 v135, 2.0, v155
	v_sub_f32_e32 v129, 1.0, v129
	v_sub_f32_e32 v128, 1.0, v128
	v_sub_f32_e32 v135, 1.0, v135
	v_sub_f32_e32 v134, 1.0, v134
	v_sub_f32_e32 v133, 1.0, v133
	v_sub_f32_e32 v132, 1.0, v132

; DI float sigmoidf_(float x) { return 1.f / (1.f + __expf(-x)); }
; #define EPI_ROWS(...) _Pragma("unroll") for (int ai = 0; ai < 2; ++ai) _Pragma("unroll") for (int m = 0; m < 4; ++m) { const int row = u.pm * 256 + ai * 128 + wr * 64 + m * 16 + fr; __VA_ARGS__ }
; DI u32x4 pack8(f32x4 a, f32x4 b) { u32x4 w; w.x = pk2(a[0], a[1]); w.y = pk2(a[2], a[3]); w.z = pk2(b[0], b[1]); w.w = pk2(b[2], b[3]); return w; }
; DI float tanh_fast(float x) { const float e = __expf(2.f * x); return 1.f - 2.f / (e + 1.f); }
;     DI void operator()(const Acc& acc, const Unit& u, int wr, int wc, int fr, int fq) const {
;     ...
;             EPI_ROWS( _Pragma("unroll") for (int bj = 0; bj < 2; ++bj) { const int c0 = (pn - 12) * 256 + bj * 128 + wc * 32 + 8 * fq; f32x4 a = acc[ai][bj][m][0], b = acc[ai][bj][m][1];
;                     if (c0 < 64) { _Pragma("unroll") for (int e = 0; e < 4; ++e) { a[e] = tanh_fast(a[e]); b[e] = tanh_fast(b[e]); } }
;                     else if (c0 >= 128) { _Pragma("unroll") for (int e = 0; e < 4; ++e) { a[e] = sigmoidf_(a[e]); b[e] = sigmoidf_(b[e]); } }
;                     *(u32x4*)(LH + (size_t)row * 512 + c0) = pack8(a, b); } )
.LBB0_2909:
	s_andn2_saveexec_b64 s[34:35], s[34:35]
	s_cbranch_execz .LBB0_2911
	v_add_f32_e32 v129, v72, v72
	v_mul_f32_e32 v129, 0x3fb8aa3b, v129
	v_add_f32_e32 v128, v76, v76
	v_exp_f32_e32 v132, v129
	v_add_f32_e32 v129, v77, v77
	v_mul_f32_e32 v128, 0x3fb8aa3b, v128
	v_mul_f32_e32 v129, 0x3fb8aa3b, v129
	v_exp_f32_e32 v128, v128
	v_exp_f32_e32 v129, v129
	v_add_f32_e32 v130, v73, v73
	v_mul_f32_e32 v130, 0x3fb8aa3b, v130
	v_exp_f32_e32 v133, v130
	v_pk_add_f32 v[128:129], v[128:129], 1.0 op_sel_hi:[1,0]
	v_add_f32_e32 v130, v78, v78
	v_add_f32_e32 v131, v79, v79
	v_mul_f32_e32 v130, 0x3fb8aa3b, v130
	v_rcp_f32_e32 v135, v128
	v_mul_f32_e32 v131, 0x3fb8aa3b, v131
	v_exp_f32_e32 v130, v130
	v_exp_f32_e32 v131, v131
	v_mul_f32_e32 v128, 2.0, v135
	v_rcp_f32_e32 v135, v129
	v_pk_add_f32 v[130:131], v[130:131], 1.0 op_sel_hi:[1,0]
	v_mul_f32_e32 v129, 2.0, v135
	v_rcp_f32_e32 v135, v130
	v_pk_add_f32 v[132:133], v[132:133], 1.0 op_sel_hi:[1,0]
	v_mul_f32_e32 v130, 2.0, v135
	v_rcp_f32_e32 v135, v131
	v_add_f32_e32 v134, v74, v74
	v_mul_f32_e32 v131, 2.0, v135
	v_add_f32_e32 v135, v75, v75
	v_mul_f32_e32 v134, 0x3fb8aa3b, v134
	v_rcp_f32_e32 v155, v132
	v_mul_f32_e32 v135, 0x3fb8aa3b, v135
	v_exp_f32_e32 v134, v134
	v_exp_f32_e32 v135, v135
	v_mul_f32_e32 v132, 2.0, v155
	v_rcp_f32_e32 v155, v133
	v_pk_add_f32 v[134:135], v[134:135], 1.0 op_sel_hi:[1,0]
	v_mul_f32_e32 v133, 2.0, v155
	v_rcp_f32_e32 v155, v134
	v_sub_f32_e32 v131, 1.0, v131
	v_mul_f32_e32 v134, 2.0, v155
	v_rcp_f32_e32 v155, v135
	v_sub_f32_e32 v130, 1.0, v130
	v_mul_f32_e32 v135, 2.0, v155
	v_sub_f32_e32 v129, 1.0, v129
	v_sub_f32_e32 v128, 1.0, v128
	v_sub_f32_e32 v135, 1.0, v135
	v_sub_f32_e32 v134, 1.0, v134
	v_sub_f32_e32 v133, 1.0, v133
	v_sub_f32_e32 v132, 1.0, v132

; DI float sigmoidf_(float x) { return 1.f / (1.f + __expf(-x)); }
; #define EPI_ROWS(...) _Pragma("unroll") for (int ai = 0; ai < 2; ++ai) _Pragma("unroll") for (int m = 0; m < 4; ++m) { const int row = u.pm * 256 + ai * 128 + wr * 64 + m * 16 + fr; __VA_ARGS__ }
; DI u32x4 pack8(f32x4 a, f32x4 b) { u32x4 w; w.x = pk2(a[0], a[1]); w.y = pk2(a[2], a[3]); w.z = pk2(b[0], b[1]); w.w = pk2(b[2], b[3]); return w; }
; DI float tanh_fast(float x) { const float e = __expf(2.f * x); return 1.f - 2.f / (e + 1.f); }
;     DI void operator()(const Acc& acc, const Unit& u, int wr, int wc, int fr, int fq) const {
;     ...
;             EPI_ROWS( _Pragma("unroll") for (int bj = 0; bj < 2; ++bj) { const int c0 = (pn - 12) * 256 + bj * 128 + wc * 32 + 8 * fq; f32x4 a = acc[ai][bj][m][0], b = acc[ai][bj][m][1];
;                     if (c0 < 64) { _Pragma("unroll") for (int e = 0; e < 4; ++e) { a[e] = tanh_fast(a[e]); b[e] = tanh_fast(b[e]); } }
;                     else if (c0 >= 128) { _Pragma("unroll") for (int e = 0; e < 4; ++e) { a[e] = sigmoidf_(a[e]); b[e] = sigmoidf_(b[e]); } }
;                     *(u32x4*)(LH + (size_t)row * 512 + c0) = pack8(a, b); } )
.LBB0_2915:
	s_andn2_saveexec_b64 s[34:35], s[34:35]
	s_cbranch_execz .LBB0_2917
	v_add_f32_e32 v129, v80, v80
	v_mul_f32_e32 v129, 0x3fb8aa3b, v129
	v_add_f32_e32 v128, v84, v84
	v_exp_f32_e32 v132, v129
	v_add_f32_e32 v129, v85, v85
	v_mul_f32_e32 v128, 0x3fb8aa3b, v128
	v_mul_f32_e32 v129, 0x3fb8aa3b, v129
	v_exp_f32_e32 v128, v128
	v_exp_f32_e32 v129, v129
	v_add_f32_e32 v130, v81, v81
	v_mul_f32_e32 v130, 0x3fb8aa3b, v130
	v_exp_f32_e32 v133, v130
	v_pk_add_f32 v[128:129], v[128:129], 1.0 op_sel_hi:[1,0]
	v_add_f32_e32 v130, v86, v86
	v_add_f32_e32 v131, v87, v87
	v_mul_f32_e32 v130, 0x3fb8aa3b, v130
	v_rcp_f32_e32 v135, v128
	v_mul_f32_e32 v131, 0x3fb8aa3b, v131
	v_exp_f32_e32 v130, v130
	v_exp_f32_e32 v131, v131
	v_mul_f32_e32 v128, 2.0, v135
	v_rcp_f32_e32 v135, v129
	v_pk_add_f32 v[130:131], v[130:131], 1.0 op_sel_hi:[1,0]
	v_mul_f32_e32 v129, 2.0, v135
	v_rcp_f32_e32 v135, v130
	v_pk_add_f32 v[132:133], v[132:133], 1.0 op_sel_hi:[1,0]
	v_mul_f32_e32 v130, 2.0, v135
	v_rcp_f32_e32 v135, v131
	v_add_f32_e32 v134, v82, v82
	v_mul_f32_e32 v131, 2.0, v135
	v_add_f32_e32 v135, v83, v83
	v_mul_f32_e32 v134, 0x3fb8aa3b, v134
	v_rcp_f32_e32 v155, v132
	v_mul_f32_e32 v135, 0x3fb8aa3b, v135
	v_exp_f32_e32 v134, v134
	v_exp_f32_e32 v135, v135
	v_mul_f32_e32 v132, 2.0, v155
	v_rcp_f32_e32 v155, v133
	v_pk_add_f32 v[134:135], v[134:135], 1.0 op_sel_hi:[1,0]
	v_mul_f32_e32 v133, 2.0, v155
	v_rcp_f32_e32 v155, v134
	v_sub_f32_e32 v131, 1.0, v131
	v_mul_f32_e32 v134, 2.0, v155
	v_rcp_f32_e32 v155, v135
	v_sub_f32_e32 v130, 1.0, v130
	v_mul_f32_e32 v135, 2.0, v155
	v_sub_f32_e32 v129, 1.0, v129
	v_sub_f32_e32 v128, 1.0, v128
	v_sub_f32_e32 v135, 1.0, v135
	v_sub_f32_e32 v134, 1.0, v134
	v_sub_f32_e32 v133, 1.0, v133
	v_sub_f32_e32 v132, 1.0, v132

; DI float sigmoidf_(float x) { return 1.f / (1.f + __expf(-x)); }
; #define EPI_ROWS(...) _Pragma("unroll") for (int ai = 0; ai < 2; ++ai) _Pragma("unroll") for (int m = 0; m < 4; ++m) { const int row = u.pm * 256 + ai * 128 + wr * 64 + m * 16 + fr; __VA_ARGS__ }
; DI u32x4 pack8(f32x4 a, f32x4 b) { u32x4 w; w.x = pk2(a[0], a[1]); w.y = pk2(a[2], a[3]); w.z = pk2(b[0], b[1]); w.w = pk2(b[2], b[3]); return w; }
; DI float tanh_fast(float x) { const float e = __expf(2.f * x); return 1.f - 2.f / (e + 1.f); }
;     DI void operator()(const Acc& acc, const Unit& u, int wr, int wc, int fr, int fq) const {
;     ...
;             EPI_ROWS( _Pragma("unroll") for (int bj = 0; bj < 2; ++bj) { const int c0 = (pn - 12) * 256 + bj * 128 + wc * 32 + 8 * fq; f32x4 a = acc[ai][bj][m][0], b = acc[ai][bj][m][1];
;                     if (c0 < 64) { _Pragma("unroll") for (int e = 0; e < 4; ++e) { a[e] = tanh_fast(a[e]); b[e] = tanh_fast(b[e]); } }
;                     else if (c0 >= 128) { _Pragma("unroll") for (int e = 0; e < 4; ++e) { a[e] = sigmoidf_(a[e]); b[e] = sigmoidf_(b[e]); } }
;                     *(u32x4*)(LH + (size_t)row * 512 + c0) = pack8(a, b); } )
.LBB0_2921:
	s_andn2_saveexec_b64 s[34:35], s[34:35]
	s_cbranch_execz .LBB0_2923
	v_add_f32_e32 v129, v64, v64
	v_mul_f32_e32 v129, 0x3fb8aa3b, v129
	v_add_f32_e32 v128, v68, v68
	v_exp_f32_e32 v132, v129
	v_add_f32_e32 v129, v69, v69
	v_mul_f32_e32 v128, 0x3fb8aa3b, v128
	v_mul_f32_e32 v129, 0x3fb8aa3b, v129
	v_exp_f32_e32 v128, v128
	v_exp_f32_e32 v129, v129
	v_add_f32_e32 v130, v65, v65
	v_mul_f32_e32 v130, 0x3fb8aa3b, v130
	v_exp_f32_e32 v133, v130
	v_pk_add_f32 v[128:129], v[128:129], 1.0 op_sel_hi:[1,0]
	v_add_f32_e32 v130, v70, v70
	v_add_f32_e32 v131, v71, v71
	v_mul_f32_e32 v130, 0x3fb8aa3b, v130
	v_rcp_f32_e32 v135, v128
	v_mul_f32_e32 v131, 0x3fb8aa3b, v131
	v_exp_f32_e32 v130, v130
	v_exp_f32_e32 v131, v131
	v_mul_f32_e32 v128, 2.0, v135
	v_rcp_f32_e32 v135, v129
	v_pk_add_f32 v[130:131], v[130:131], 1.0 op_sel_hi:[1,0]
	v_mul_f32_e32 v129, 2.0, v135
	v_rcp_f32_e32 v135, v130
	v_pk_add_f32 v[132:133], v[132:133], 1.0 op_sel_hi:[1,0]
	v_mul_f32_e32 v130, 2.0, v135
	v_rcp_f32_e32 v135, v131
	v_add_f32_e32 v134, v66, v66
	v_mul_f32_e32 v131, 2.0, v135
	v_add_f32_e32 v135, v67, v67
	v_mul_f32_e32 v134, 0x3fb8aa3b, v134
	v_rcp_f32_e32 v155, v132
	v_mul_f32_e32 v135, 0x3fb8aa3b, v135
	v_exp_f32_e32 v134, v134
	v_exp_f32_e32 v135, v135
	v_mul_f32_e32 v132, 2.0, v155
	v_rcp_f32_e32 v155, v133
	v_pk_add_f32 v[134:135], v[134:135], 1.0 op_sel_hi:[1,0]
	v_mul_f32_e32 v133, 2.0, v155
	v_rcp_f32_e32 v155, v134
	v_sub_f32_e32 v131, 1.0, v131
	v_mul_f32_e32 v134, 2.0, v155
	v_rcp_f32_e32 v155, v135
	v_sub_f32_e32 v130, 1.0, v130
	v_mul_f32_e32 v135, 2.0, v155
	v_sub_f32_e32 v129, 1.0, v129
	v_sub_f32_e32 v128, 1.0, v128
	v_sub_f32_e32 v135, 1.0, v135
	v_sub_f32_e32 v134, 1.0, v134
	v_sub_f32_e32 v133, 1.0, v133
	v_sub_f32_e32 v132, 1.0, v132

; DI float sigmoidf_(float x) { return 1.f / (1.f + __expf(-x)); }
; #define EPI_ROWS(...) _Pragma("unroll") for (int ai = 0; ai < 2; ++ai) _Pragma("unroll") for (int m = 0; m < 4; ++m) { const int row = u.pm * 256 + ai * 128 + wr * 64 + m * 16 + fr; __VA_ARGS__ }
; DI u32x4 pack8(f32x4 a, f32x4 b) { u32x4 w; w.x = pk2(a[0], a[1]); w.y = pk2(a[2], a[3]); w.z = pk2(b[0], b[1]); w.w = pk2(b[2], b[3]); return w; }
; DI float tanh_fast(float x) { const float e = __expf(2.f * x); return 1.f - 2.f / (e + 1.f); }
;     DI void operator()(const Acc& acc, const Unit& u, int wr, int wc, int fr, int fq) const {
;     ...
;             EPI_ROWS( _Pragma("unroll") for (int bj = 0; bj < 2; ++bj) { const int c0 = (pn - 12) * 256 + bj * 128 + wc * 32 + 8 * fq; f32x4 a = acc[ai][bj][m][0], b = acc[ai][bj][m][1];
;                     if (c0 < 64) { _Pragma("unroll") for (int e = 0; e < 4; ++e) { a[e] = tanh_fast(a[e]); b[e] = tanh_fast(b[e]); } }
;                     else if (c0 >= 128) { _Pragma("unroll") for (int e = 0; e < 4; ++e) { a[e] = sigmoidf_(a[e]); b[e] = sigmoidf_(b[e]); } }
;                     *(u32x4*)(LH + (size_t)row * 512 + c0) = pack8(a, b); } )
.LBB0_2927:
	s_andn2_saveexec_b64 s[34:35], s[34:35]
	s_cbranch_execz .LBB0_2929
	v_add_f32_e32 v129, v56, v56
	v_mul_f32_e32 v129, 0x3fb8aa3b, v129
	v_add_f32_e32 v128, v60, v60
	v_exp_f32_e32 v132, v129
	v_add_f32_e32 v129, v61, v61
	v_mul_f32_e32 v128, 0x3fb8aa3b, v128
	v_mul_f32_e32 v129, 0x3fb8aa3b, v129
	v_exp_f32_e32 v128, v128
	v_exp_f32_e32 v129, v129
	v_add_f32_e32 v130, v57, v57
	v_mul_f32_e32 v130, 0x3fb8aa3b, v130
	v_exp_f32_e32 v133, v130
	v_pk_add_f32 v[128:129], v[128:129], 1.0 op_sel_hi:[1,0]
	v_add_f32_e32 v130, v62, v62
	v_add_f32_e32 v131, v63, v63
	v_mul_f32_e32 v130, 0x3fb8aa3b, v130
	v_rcp_f32_e32 v135, v128
	v_mul_f32_e32 v131, 0x3fb8aa3b, v131
	v_exp_f32_e32 v130, v130
	v_exp_f32_e32 v131, v131
	v_mul_f32_e32 v128, 2.0, v135
	v_rcp_f32_e32 v135, v129
	v_pk_add_f32 v[130:131], v[130:131], 1.0 op_sel_hi:[1,0]
	v_mul_f32_e32 v129, 2.0, v135
	v_rcp_f32_e32 v135, v130
	v_pk_add_f32 v[132:133], v[132:133], 1.0 op_sel_hi:[1,0]
	v_mul_f32_e32 v130, 2.0, v135
	v_rcp_f32_e32 v135, v131
	v_add_f32_e32 v134, v58, v58
	v_mul_f32_e32 v131, 2.0, v135
	v_add_f32_e32 v135, v59, v59
	v_mul_f32_e32 v134, 0x3fb8aa3b, v134
	v_rcp_f32_e32 v155, v132
	v_mul_f32_e32 v135, 0x3fb8aa3b, v135
	v_exp_f32_e32 v134, v134
	v_exp_f32_e32 v135, v135
	v_mul_f32_e32 v132, 2.0, v155
	v_rcp_f32_e32 v155, v133
	v_pk_add_f32 v[134:135], v[134:135], 1.0 op_sel_hi:[1,0]
	v_mul_f32_e32 v133, 2.0, v155
	v_rcp_f32_e32 v155, v134
	v_sub_f32_e32 v131, 1.0, v131
	v_mul_f32_e32 v134, 2.0, v155
	v_rcp_f32_e32 v155, v135
	v_sub_f32_e32 v130, 1.0, v130
	v_mul_f32_e32 v135, 2.0, v155
	v_sub_f32_e32 v129, 1.0, v129
	v_sub_f32_e32 v128, 1.0, v128
	v_sub_f32_e32 v135, 1.0, v135
	v_sub_f32_e32 v134, 1.0, v134
	v_sub_f32_e32 v133, 1.0, v133
	v_sub_f32_e32 v132, 1.0, v132

; DI float sigmoidf_(float x) { return 1.f / (1.f + __expf(-x)); }
; #define EPI_ROWS(...) _Pragma("unroll") for (int ai = 0; ai < 2; ++ai) _Pragma("unroll") for (int m = 0; m < 4; ++m) { const int row = u.pm * 256 + ai * 128 + wr * 64 + m * 16 + fr; __VA_ARGS__ }
; DI u32x4 pack8(f32x4 a, f32x4 b) { u32x4 w; w.x = pk2(a[0], a[1]); w.y = pk2(a[2], a[3]); w.z = pk2(b[0], b[1]); w.w = pk2(b[2], b[3]); return w; }
; DI float tanh_fast(float x) { const float e = __expf(2.f * x); return 1.f - 2.f / (e + 1.f); }
;     DI void operator()(const Acc& acc, const Unit& u, int wr, int wc, int fr, int fq) const {
;     ...
;             EPI_ROWS( _Pragma("unroll") for (int bj = 0; bj < 2; ++bj) { const int c0 = (pn - 12) * 256 + bj * 128 + wc * 32 + 8 * fq; f32x4 a = acc[ai][bj][m][0], b = acc[ai][bj][m][1];
;                     if (c0 < 64) { _Pragma("unroll") for (int e = 0; e < 4; ++e) { a[e] = tanh_fast(a[e]); b[e] = tanh_fast(b[e]); } }
;                     else if (c0 >= 128) { _Pragma("unroll") for (int e = 0; e < 4; ++e) { a[e] = sigmoidf_(a[e]); b[e] = sigmoidf_(b[e]); } }
;                     *(u32x4*)(LH + (size_t)row * 512 + c0) = pack8(a, b); } )
.LBB0_2933:
	s_andn2_saveexec_b64 s[34:35], s[34:35]
	s_cbranch_execz .LBB0_2935
	v_add_f32_e32 v129, v40, v40
	v_mul_f32_e32 v129, 0x3fb8aa3b, v129
	v_add_f32_e32 v128, v44, v44
	v_exp_f32_e32 v132, v129
	v_add_f32_e32 v129, v45, v45
	v_mul_f32_e32 v128, 0x3fb8aa3b, v128
	v_mul_f32_e32 v129, 0x3fb8aa3b, v129
	v_exp_f32_e32 v128, v128
	v_exp_f32_e32 v129, v129
	v_add_f32_e32 v130, v41, v41
	v_mul_f32_e32 v130, 0x3fb8aa3b, v130
	v_exp_f32_e32 v133, v130
	v_pk_add_f32 v[128:129], v[128:129], 1.0 op_sel_hi:[1,0]
	v_add_f32_e32 v130, v46, v46
	v_add_f32_e32 v131, v47, v47
	v_mul_f32_e32 v130, 0x3fb8aa3b, v130
	v_rcp_f32_e32 v135, v128
	v_mul_f32_e32 v131, 0x3fb8aa3b, v131
	v_exp_f32_e32 v130, v130
	v_exp_f32_e32 v131, v131
	v_mul_f32_e32 v128, 2.0, v135
	v_rcp_f32_e32 v135, v129
	v_pk_add_f32 v[130:131], v[130:131], 1.0 op_sel_hi:[1,0]
	v_mul_f32_e32 v129, 2.0, v135
	v_rcp_f32_e32 v135, v130
	v_pk_add_f32 v[132:133], v[132:133], 1.0 op_sel_hi:[1,0]
	v_mul_f32_e32 v130, 2.0, v135
	v_rcp_f32_e32 v135, v131
	v_add_f32_e32 v134, v42, v42
	v_mul_f32_e32 v131, 2.0, v135
	v_add_f32_e32 v135, v43, v43
	v_mul_f32_e32 v134, 0x3fb8aa3b, v134
	v_rcp_f32_e32 v155, v132
	v_mul_f32_e32 v135, 0x3fb8aa3b, v135
	v_exp_f32_e32 v134, v134
	v_exp_f32_e32 v135, v135
	v_mul_f32_e32 v132, 2.0, v155
	v_rcp_f32_e32 v155, v133
	v_pk_add_f32 v[134:135], v[134:135], 1.0 op_sel_hi:[1,0]
	v_mul_f32_e32 v133, 2.0, v155
	v_rcp_f32_e32 v155, v134
	v_sub_f32_e32 v131, 1.0, v131
	v_mul_f32_e32 v134, 2.0, v155
	v_rcp_f32_e32 v155, v135
	v_sub_f32_e32 v130, 1.0, v130
	v_mul_f32_e32 v135, 2.0, v155
	v_sub_f32_e32 v129, 1.0, v129
	v_sub_f32_e32 v128, 1.0, v128
	v_sub_f32_e32 v135, 1.0, v135
	v_sub_f32_e32 v134, 1.0, v134
	v_sub_f32_e32 v133, 1.0, v133
	v_sub_f32_e32 v132, 1.0, v132

; DI float sigmoidf_(float x) { return 1.f / (1.f + __expf(-x)); }
; #define EPI_ROWS(...) _Pragma("unroll") for (int ai = 0; ai < 2; ++ai) _Pragma("unroll") for (int m = 0; m < 4; ++m) { const int row = u.pm * 256 + ai * 128 + wr * 64 + m * 16 + fr; __VA_ARGS__ }
; DI u32x4 pack8(f32x4 a, f32x4 b) { u32x4 w; w.x = pk2(a[0], a[1]); w.y = pk2(a[2], a[3]); w.z = pk2(b[0], b[1]); w.w = pk2(b[2], b[3]); return w; }
; DI float tanh_fast(float x) { const float e = __expf(2.f * x); return 1.f - 2.f / (e + 1.f); }
;     DI void operator()(const Acc& acc, const Unit& u, int wr, int wc, int fr, int fq) const {
;     ...
;             EPI_ROWS( _Pragma("unroll") for (int bj = 0; bj < 2; ++bj) { const int c0 = (pn - 12) * 256 + bj * 128 + wc * 32 + 8 * fq; f32x4 a = acc[ai][bj][m][0], b = acc[ai][bj][m][1];
;                     if (c0 < 64) { _Pragma("unroll") for (int e = 0; e < 4; ++e) { a[e] = tanh_fast(a[e]); b[e] = tanh_fast(b[e]); } }
;                     else if (c0 >= 128) { _Pragma("unroll") for (int e = 0; e < 4; ++e) { a[e] = sigmoidf_(a[e]); b[e] = sigmoidf_(b[e]); } }
;                     *(u32x4*)(LH + (size_t)row * 512 + c0) = pack8(a, b); } )
.LBB0_2939:
	s_andn2_saveexec_b64 s[34:35], s[34:35]
	s_cbranch_execz .LBB0_2941
	v_add_f32_e32 v129, v48, v48
	v_mul_f32_e32 v129, 0x3fb8aa3b, v129
	v_add_f32_e32 v128, v52, v52
	v_exp_f32_e32 v132, v129
	v_add_f32_e32 v129, v53, v53
	v_mul_f32_e32 v128, 0x3fb8aa3b, v128
	v_mul_f32_e32 v129, 0x3fb8aa3b, v129
	v_exp_f32_e32 v128, v128
	v_exp_f32_e32 v129, v129
	v_add_f32_e32 v130, v49, v49
	v_mul_f32_e32 v130, 0x3fb8aa3b, v130
	v_exp_f32_e32 v133, v130
	v_pk_add_f32 v[128:129], v[128:129], 1.0 op_sel_hi:[1,0]
	v_add_f32_e32 v130, v54, v54
	v_add_f32_e32 v131, v55, v55
	v_mul_f32_e32 v130, 0x3fb8aa3b, v130
	v_rcp_f32_e32 v135, v128
	v_mul_f32_e32 v131, 0x3fb8aa3b, v131
	v_exp_f32_e32 v130, v130
	v_exp_f32_e32 v131, v131
	v_mul_f32_e32 v128, 2.0, v135
	v_rcp_f32_e32 v135, v129
	v_pk_add_f32 v[130:131], v[130:131], 1.0 op_sel_hi:[1,0]
	v_mul_f32_e32 v129, 2.0, v135
	v_rcp_f32_e32 v135, v130
	v_pk_add_f32 v[132:133], v[132:133], 1.0 op_sel_hi:[1,0]
	v_mul_f32_e32 v130, 2.0, v135
	v_rcp_f32_e32 v135, v131
	v_add_f32_e32 v134, v50, v50
	v_mul_f32_e32 v131, 2.0, v135
	v_add_f32_e32 v135, v51, v51
	v_mul_f32_e32 v134, 0x3fb8aa3b, v134
	v_rcp_f32_e32 v155, v132
	v_mul_f32_e32 v135, 0x3fb8aa3b, v135
	v_exp_f32_e32 v134, v134
	v_exp_f32_e32 v135, v135
	v_mul_f32_e32 v132, 2.0, v155
	v_rcp_f32_e32 v155, v133
	v_pk_add_f32 v[134:135], v[134:135], 1.0 op_sel_hi:[1,0]
	v_mul_f32_e32 v133, 2.0, v155
	v_rcp_f32_e32 v155, v134
	v_sub_f32_e32 v131, 1.0, v131
	v_mul_f32_e32 v134, 2.0, v155
	v_rcp_f32_e32 v155, v135
	v_sub_f32_e32 v130, 1.0, v130
	v_mul_f32_e32 v135, 2.0, v155
	v_sub_f32_e32 v129, 1.0, v129
	v_sub_f32_e32 v128, 1.0, v128
	v_sub_f32_e32 v135, 1.0, v135
	v_sub_f32_e32 v134, 1.0, v134
	v_sub_f32_e32 v133, 1.0, v133
	v_sub_f32_e32 v132, 1.0, v132

; DI float sigmoidf_(float x) { return 1.f / (1.f + __expf(-x)); }
; #define EPI_ROWS(...) _Pragma("unroll") for (int ai = 0; ai < 2; ++ai) _Pragma("unroll") for (int m = 0; m < 4; ++m) { const int row = u.pm * 256 + ai * 128 + wr * 64 + m * 16 + fr; __VA_ARGS__ }
; DI u32x4 pack8(f32x4 a, f32x4 b) { u32x4 w; w.x = pk2(a[0], a[1]); w.y = pk2(a[2], a[3]); w.z = pk2(b[0], b[1]); w.w = pk2(b[2], b[3]); return w; }
; DI float tanh_fast(float x) { const float e = __expf(2.f * x); return 1.f - 2.f / (e + 1.f); }
;     DI void operator()(const Acc& acc, const Unit& u, int wr, int wc, int fr, int fq) const {
;     ...
;             EPI_ROWS( _Pragma("unroll") for (int bj = 0; bj < 2; ++bj) { const int c0 = (pn - 12) * 256 + bj * 128 + wc * 32 + 8 * fq; f32x4 a = acc[ai][bj][m][0], b = acc[ai][bj][m][1];
;                     if (c0 < 64) { _Pragma("unroll") for (int e = 0; e < 4; ++e) { a[e] = tanh_fast(a[e]); b[e] = tanh_fast(b[e]); } }
;                     else if (c0 >= 128) { _Pragma("unroll") for (int e = 0; e < 4; ++e) { a[e] = sigmoidf_(a[e]); b[e] = sigmoidf_(b[e]); } }
;                     *(u32x4*)(LH + (size_t)row * 512 + c0) = pack8(a, b); } )
.LBB0_2945:
	s_andn2_saveexec_b64 s[34:35], s[34:35]
	s_cbranch_execz .LBB0_2947
	v_add_f32_e32 v129, v24, v24
	v_mul_f32_e32 v129, 0x3fb8aa3b, v129
	v_add_f32_e32 v128, v28, v28
	v_exp_f32_e32 v132, v129
	v_add_f32_e32 v129, v29, v29
	v_mul_f32_e32 v128, 0x3fb8aa3b, v128
	v_mul_f32_e32 v129, 0x3fb8aa3b, v129
	v_exp_f32_e32 v128, v128
	v_exp_f32_e32 v129, v129
	v_add_f32_e32 v130, v25, v25
	v_mul_f32_e32 v130, 0x3fb8aa3b, v130
	v_exp_f32_e32 v133, v130
	v_pk_add_f32 v[128:129], v[128:129], 1.0 op_sel_hi:[1,0]
	v_add_f32_e32 v130, v30, v30
	v_add_f32_e32 v131, v31, v31
	v_mul_f32_e32 v130, 0x3fb8aa3b, v130
	v_rcp_f32_e32 v135, v128
	v_mul_f32_e32 v131, 0x3fb8aa3b, v131
	v_exp_f32_e32 v130, v130
	v_exp_f32_e32 v131, v131
	v_mul_f32_e32 v128, 2.0, v135
	v_rcp_f32_e32 v135, v129
	v_pk_add_f32 v[130:131], v[130:131], 1.0 op_sel_hi:[1,0]
	v_mul_f32_e32 v129, 2.0, v135
	v_rcp_f32_e32 v135, v130
	v_pk_add_f32 v[132:133], v[132:133], 1.0 op_sel_hi:[1,0]
	v_mul_f32_e32 v130, 2.0, v135
	v_rcp_f32_e32 v135, v131
	v_add_f32_e32 v134, v26, v26
	v_mul_f32_e32 v131, 2.0, v135
	v_add_f32_e32 v135, v27, v27
	v_mul_f32_e32 v134, 0x3fb8aa3b, v134
	v_rcp_f32_e32 v155, v132
	v_mul_f32_e32 v135, 0x3fb8aa3b, v135
	v_exp_f32_e32 v134, v134
	v_exp_f32_e32 v135, v135
	v_mul_f32_e32 v132, 2.0, v155
	v_rcp_f32_e32 v155, v133
	v_pk_add_f32 v[134:135], v[134:135], 1.0 op_sel_hi:[1,0]
	v_mul_f32_e32 v133, 2.0, v155
	v_rcp_f32_e32 v155, v134
	v_sub_f32_e32 v131, 1.0, v131
	v_mul_f32_e32 v134, 2.0, v155
	v_rcp_f32_e32 v155, v135
	v_sub_f32_e32 v130, 1.0, v130
	v_mul_f32_e32 v135, 2.0, v155
	v_sub_f32_e32 v129, 1.0, v129
	v_sub_f32_e32 v128, 1.0, v128
	v_sub_f32_e32 v135, 1.0, v135
	v_sub_f32_e32 v134, 1.0, v134
	v_sub_f32_e32 v133, 1.0, v133
	v_sub_f32_e32 v132, 1.0, v132

; DI float sigmoidf_(float x) { return 1.f / (1.f + __expf(-x)); }
; #define EPI_ROWS(...) _Pragma("unroll") for (int ai = 0; ai < 2; ++ai) _Pragma("unroll") for (int m = 0; m < 4; ++m) { const int row = u.pm * 256 + ai * 128 + wr * 64 + m * 16 + fr; __VA_ARGS__ }
; DI u32x4 pack8(f32x4 a, f32x4 b) { u32x4 w; w.x = pk2(a[0], a[1]); w.y = pk2(a[2], a[3]); w.z = pk2(b[0], b[1]); w.w = pk2(b[2], b[3]); return w; }
; DI float tanh_fast(float x) { const float e = __expf(2.f * x); return 1.f - 2.f / (e + 1.f); }
;     DI void operator()(const Acc& acc, const Unit& u, int wr, int wc, int fr, int fq) const {
;     ...
;             EPI_ROWS( _Pragma("unroll") for (int bj = 0; bj < 2; ++bj) { const int c0 = (pn - 12) * 256 + bj * 128 + wc * 32 + 8 * fq; f32x4 a = acc[ai][bj][m][0], b = acc[ai][bj][m][1];
;                     if (c0 < 64) { _Pragma("unroll") for (int e = 0; e < 4; ++e) { a[e] = tanh_fast(a[e]); b[e] = tanh_fast(b[e]); } }
;                     else if (c0 >= 128) { _Pragma("unroll") for (int e = 0; e < 4; ++e) { a[e] = sigmoidf_(a[e]); b[e] = sigmoidf_(b[e]); } }
;                     *(u32x4*)(LH + (size_t)row * 512 + c0) = pack8(a, b); } )
.LBB0_2951:
	s_andn2_saveexec_b64 s[34:35], s[34:35]
	s_cbranch_execz .LBB0_2953
	v_add_f32_e32 v129, v32, v32
	v_mul_f32_e32 v129, 0x3fb8aa3b, v129
	v_add_f32_e32 v128, v36, v36
	v_exp_f32_e32 v132, v129
	v_add_f32_e32 v129, v37, v37
	v_mul_f32_e32 v128, 0x3fb8aa3b, v128
	v_mul_f32_e32 v129, 0x3fb8aa3b, v129
	v_exp_f32_e32 v128, v128
	v_exp_f32_e32 v129, v129
	v_add_f32_e32 v130, v33, v33
	v_mul_f32_e32 v130, 0x3fb8aa3b, v130
	v_exp_f32_e32 v133, v130
	v_pk_add_f32 v[128:129], v[128:129], 1.0 op_sel_hi:[1,0]
	v_add_f32_e32 v130, v38, v38
	v_add_f32_e32 v131, v39, v39
	v_mul_f32_e32 v130, 0x3fb8aa3b, v130
	v_rcp_f32_e32 v135, v128
	v_mul_f32_e32 v131, 0x3fb8aa3b, v131
	v_exp_f32_e32 v130, v130
	v_exp_f32_e32 v131, v131
	v_mul_f32_e32 v128, 2.0, v135
	v_rcp_f32_e32 v135, v129
	v_pk_add_f32 v[130:131], v[130:131], 1.0 op_sel_hi:[1,0]
	v_mul_f32_e32 v129, 2.0, v135
	v_rcp_f32_e32 v135, v130
	v_pk_add_f32 v[132:133], v[132:133], 1.0 op_sel_hi:[1,0]
	v_mul_f32_e32 v130, 2.0, v135
	v_rcp_f32_e32 v135, v131
	v_add_f32_e32 v134, v34, v34
	v_mul_f32_e32 v131, 2.0, v135
	v_add_f32_e32 v135, v35, v35
	v_mul_f32_e32 v134, 0x3fb8aa3b, v134
	v_rcp_f32_e32 v155, v132
	v_mul_f32_e32 v135, 0x3fb8aa3b, v135
	v_exp_f32_e32 v134, v134
	v_exp_f32_e32 v135, v135
	v_mul_f32_e32 v132, 2.0, v155
	v_rcp_f32_e32 v155, v133
	v_pk_add_f32 v[134:135], v[134:135], 1.0 op_sel_hi:[1,0]
	v_mul_f32_e32 v133, 2.0, v155
	v_rcp_f32_e32 v155, v134
	v_sub_f32_e32 v131, 1.0, v131
	v_mul_f32_e32 v134, 2.0, v155
	v_rcp_f32_e32 v155, v135
	v_sub_f32_e32 v130, 1.0, v130
	v_mul_f32_e32 v135, 2.0, v155
	v_sub_f32_e32 v129, 1.0, v129
	v_sub_f32_e32 v128, 1.0, v128
	v_sub_f32_e32 v135, 1.0, v135
	v_sub_f32_e32 v134, 1.0, v134
	v_sub_f32_e32 v133, 1.0, v133
	v_sub_f32_e32 v132, 1.0, v132

; DI float sigmoidf_(float x) { return 1.f / (1.f + __expf(-x)); }
; #define EPI_ROWS(...) _Pragma("unroll") for (int ai = 0; ai < 2; ++ai) _Pragma("unroll") for (int m = 0; m < 4; ++m) { const int row = u.pm * 256 + ai * 128 + wr * 64 + m * 16 + fr; __VA_ARGS__ }
; DI u32x4 pack8(f32x4 a, f32x4 b) { u32x4 w; w.x = pk2(a[0], a[1]); w.y = pk2(a[2], a[3]); w.z = pk2(b[0], b[1]); w.w = pk2(b[2], b[3]); return w; }
; DI float tanh_fast(float x) { const float e = __expf(2.f * x); return 1.f - 2.f / (e + 1.f); }
;     DI void operator()(const Acc& acc, const Unit& u, int wr, int wc, int fr, int fq) const {
;     ...
;             EPI_ROWS( _Pragma("unroll") for (int bj = 0; bj < 2; ++bj) { const int c0 = (pn - 12) * 256 + bj * 128 + wc * 32 + 8 * fq; f32x4 a = acc[ai][bj][m][0], b = acc[ai][bj][m][1];
;                     if (c0 < 64) { _Pragma("unroll") for (int e = 0; e < 4; ++e) { a[e] = tanh_fast(a[e]); b[e] = tanh_fast(b[e]); } }
;                     else if (c0 >= 128) { _Pragma("unroll") for (int e = 0; e < 4; ++e) { a[e] = sigmoidf_(a[e]); b[e] = sigmoidf_(b[e]); } }
;                     *(u32x4*)(LH + (size_t)row * 512 + c0) = pack8(a, b); } )
.LBB0_2957:
	s_andn2_saveexec_b64 s[34:35], s[34:35]
	s_cbranch_execz .LBB0_2959
	v_add_f32_e32 v129, v8, v8
	v_mul_f32_e32 v129, 0x3fb8aa3b, v129
	v_add_f32_e32 v128, v12, v12
	v_exp_f32_e32 v132, v129
	v_add_f32_e32 v129, v13, v13
	v_mul_f32_e32 v128, 0x3fb8aa3b, v128
	v_mul_f32_e32 v129, 0x3fb8aa3b, v129
	v_exp_f32_e32 v128, v128
	v_exp_f32_e32 v129, v129
	v_add_f32_e32 v130, v9, v9
	v_mul_f32_e32 v130, 0x3fb8aa3b, v130
	v_exp_f32_e32 v133, v130
	v_pk_add_f32 v[128:129], v[128:129], 1.0 op_sel_hi:[1,0]
	v_add_f32_e32 v130, v14, v14
	v_add_f32_e32 v131, v15, v15
	v_mul_f32_e32 v130, 0x3fb8aa3b, v130
	v_rcp_f32_e32 v135, v128
	v_mul_f32_e32 v131, 0x3fb8aa3b, v131
	v_exp_f32_e32 v130, v130
	v_exp_f32_e32 v131, v131
	v_mul_f32_e32 v128, 2.0, v135
	v_rcp_f32_e32 v135, v129
	v_pk_add_f32 v[130:131], v[130:131], 1.0 op_sel_hi:[1,0]
	v_mul_f32_e32 v129, 2.0, v135
	v_rcp_f32_e32 v135, v130
	v_pk_add_f32 v[132:133], v[132:133], 1.0 op_sel_hi:[1,0]
	v_mul_f32_e32 v130, 2.0, v135
	v_rcp_f32_e32 v135, v131
	v_add_f32_e32 v134, v10, v10
	v_mul_f32_e32 v131, 2.0, v135
	v_add_f32_e32 v135, v11, v11
	v_mul_f32_e32 v134, 0x3fb8aa3b, v134
	v_rcp_f32_e32 v155, v132
	v_mul_f32_e32 v135, 0x3fb8aa3b, v135
	v_exp_f32_e32 v134, v134
	v_exp_f32_e32 v135, v135
	v_mul_f32_e32 v132, 2.0, v155
	v_rcp_f32_e32 v155, v133
	v_pk_add_f32 v[134:135], v[134:135], 1.0 op_sel_hi:[1,0]
	v_mul_f32_e32 v133, 2.0, v155
	v_rcp_f32_e32 v155, v134
	v_sub_f32_e32 v131, 1.0, v131
	v_mul_f32_e32 v134, 2.0, v155
	v_rcp_f32_e32 v155, v135
	v_sub_f32_e32 v130, 1.0, v130
	v_mul_f32_e32 v135, 2.0, v155
	v_sub_f32_e32 v129, 1.0, v129
	v_sub_f32_e32 v128, 1.0, v128
	v_sub_f32_e32 v135, 1.0, v135
	v_sub_f32_e32 v134, 1.0, v134
	v_sub_f32_e32 v133, 1.0, v133
	v_sub_f32_e32 v132, 1.0, v132

; DI float sigmoidf_(float x) { return 1.f / (1.f + __expf(-x)); }
; #define EPI_ROWS(...) _Pragma("unroll") for (int ai = 0; ai < 2; ++ai) _Pragma("unroll") for (int m = 0; m < 4; ++m) { const int row = u.pm * 256 + ai * 128 + wr * 64 + m * 16 + fr; __VA_ARGS__ }
; DI u32x4 pack8(f32x4 a, f32x4 b) { u32x4 w; w.x = pk2(a[0], a[1]); w.y = pk2(a[2], a[3]); w.z = pk2(b[0], b[1]); w.w = pk2(b[2], b[3]); return w; }
; DI float tanh_fast(float x) { const float e = __expf(2.f * x); return 1.f - 2.f / (e + 1.f); }
;     DI void operator()(const Acc& acc, const Unit& u, int wr, int wc, int fr, int fq) const {
;     ...
;             EPI_ROWS( _Pragma("unroll") for (int bj = 0; bj < 2; ++bj) { const int c0 = (pn - 12) * 256 + bj * 128 + wc * 32 + 8 * fq; f32x4 a = acc[ai][bj][m][0], b = acc[ai][bj][m][1];
;                     if (c0 < 64) { _Pragma("unroll") for (int e = 0; e < 4; ++e) { a[e] = tanh_fast(a[e]); b[e] = tanh_fast(b[e]); } }
;                     else if (c0 >= 128) { _Pragma("unroll") for (int e = 0; e < 4; ++e) { a[e] = sigmoidf_(a[e]); b[e] = sigmoidf_(b[e]); } }
;                     *(u32x4*)(LH + (size_t)row * 512 + c0) = pack8(a, b); } )
.LBB0_2963:
	s_andn2_saveexec_b64 s[4:5], s[4:5]
	s_cbranch_execz .LBB0_2965
	v_add_f32_e32 v129, v16, v16
	v_mul_f32_e32 v129, 0x3fb8aa3b, v129
	v_add_f32_e32 v128, v20, v20
	v_exp_f32_e32 v132, v129
	v_add_f32_e32 v129, v21, v21
	v_mul_f32_e32 v128, 0x3fb8aa3b, v128
	v_mul_f32_e32 v129, 0x3fb8aa3b, v129
	v_exp_f32_e32 v128, v128
	v_exp_f32_e32 v129, v129
	v_add_f32_e32 v130, v17, v17
	v_mul_f32_e32 v130, 0x3fb8aa3b, v130
	v_exp_f32_e32 v133, v130
	v_pk_add_f32 v[128:129], v[128:129], 1.0 op_sel_hi:[1,0]
	v_add_f32_e32 v130, v22, v22
	v_add_f32_e32 v131, v23, v23
	v_mul_f32_e32 v130, 0x3fb8aa3b, v130
	v_rcp_f32_e32 v135, v128
	v_mul_f32_e32 v131, 0x3fb8aa3b, v131
	v_exp_f32_e32 v130, v130
	v_exp_f32_e32 v131, v131
	v_mul_f32_e32 v128, 2.0, v135
	v_rcp_f32_e32 v135, v129
	v_pk_add_f32 v[130:131], v[130:131], 1.0 op_sel_hi:[1,0]
	v_mul_f32_e32 v129, 2.0, v135
	v_rcp_f32_e32 v135, v130
	v_pk_add_f32 v[132:133], v[132:133], 1.0 op_sel_hi:[1,0]
	v_mul_f32_e32 v130, 2.0, v135
	v_rcp_f32_e32 v135, v131
	v_add_f32_e32 v134, v18, v18
	v_mul_f32_e32 v131, 2.0, v135
	v_add_f32_e32 v135, v19, v19
	v_mul_f32_e32 v134, 0x3fb8aa3b, v134
	v_rcp_f32_e32 v155, v132
	v_mul_f32_e32 v135, 0x3fb8aa3b, v135
	v_exp_f32_e32 v134, v134
	v_exp_f32_e32 v135, v135
	v_mul_f32_e32 v132, 2.0, v155
	v_rcp_f32_e32 v155, v133
	v_pk_add_f32 v[134:135], v[134:135], 1.0 op_sel_hi:[1,0]
	v_mul_f32_e32 v133, 2.0, v155
	v_rcp_f32_e32 v155, v134
	v_sub_f32_e32 v131, 1.0, v131
	v_mul_f32_e32 v134, 2.0, v155
	v_rcp_f32_e32 v155, v135
	v_sub_f32_e32 v130, 1.0, v130
	v_mul_f32_e32 v135, 2.0, v155
	v_sub_f32_e32 v129, 1.0, v129
	v_sub_f32_e32 v128, 1.0, v128
	v_sub_f32_e32 v135, 1.0, v135
	v_sub_f32_e32 v134, 1.0, v134
	v_sub_f32_e32 v133, 1.0, v133
	v_sub_f32_e32 v132, 1.0, v132

; DI float sigmoidf_(float x) { return 1.f / (1.f + __expf(-x)); }
; #define EPI_ROWS(...) _Pragma("unroll") for (int ai = 0; ai < 2; ++ai) _Pragma("unroll") for (int m = 0; m < 4; ++m) { const int row = u.pm * 256 + ai * 128 + wr * 64 + m * 16 + fr; __VA_ARGS__ }
; DI u32x4 pack8(f32x4 a, f32x4 b) { u32x4 w; w.x = pk2(a[0], a[1]); w.y = pk2(a[2], a[3]); w.z = pk2(b[0], b[1]); w.w = pk2(b[2], b[3]); return w; }
; DI float tanh_fast(float x) { const float e = __expf(2.f * x); return 1.f - 2.f / (e + 1.f); }
;     DI void operator()(const Acc& acc, const Unit& u, int wr, int wc, int fr, int fq) const {
;     ...
;             EPI_ROWS( _Pragma("unroll") for (int bj = 0; bj < 2; ++bj) { const int c0 = (pn - 12) * 256 + bj * 128 + wc * 32 + 8 * fq; f32x4 a = acc[ai][bj][m][0], b = acc[ai][bj][m][1];
;                     if (c0 < 64) { _Pragma("unroll") for (int e = 0; e < 4; ++e) { a[e] = tanh_fast(a[e]); b[e] = tanh_fast(b[e]); } }
;                     else if (c0 >= 128) { _Pragma("unroll") for (int e = 0; e < 4; ++e) { a[e] = sigmoidf_(a[e]); b[e] = sigmoidf_(b[e]); } }
;                     *(u32x4*)(LH + (size_t)row * 512 + c0) = pack8(a, b); } )
.LBB0_2969:
	s_andn2_saveexec_b64 s[4:5], s[4:5]
	s_cbranch_execz .LBB0_2971
	v_add_f32_e32 v129, v0, v0
	v_mul_f32_e32 v129, 0x3fb8aa3b, v129
	v_add_f32_e32 v128, v4, v4
	v_exp_f32_e32 v132, v129
	v_add_f32_e32 v129, v5, v5
	v_mul_f32_e32 v128, 0x3fb8aa3b, v128
	v_mul_f32_e32 v129, 0x3fb8aa3b, v129
	v_exp_f32_e32 v128, v128
	v_exp_f32_e32 v129, v129
	v_add_f32_e32 v130, v1, v1
	v_mul_f32_e32 v130, 0x3fb8aa3b, v130
	v_exp_f32_e32 v133, v130
	v_pk_add_f32 v[128:129], v[128:129], 1.0 op_sel_hi:[1,0]
	v_add_f32_e32 v130, v6, v6
	v_add_f32_e32 v131, v7, v7
	v_mul_f32_e32 v130, 0x3fb8aa3b, v130
	v_rcp_f32_e32 v135, v128
	v_mul_f32_e32 v131, 0x3fb8aa3b, v131
	v_exp_f32_e32 v130, v130
	v_exp_f32_e32 v131, v131
	v_mul_f32_e32 v128, 2.0, v135
	v_rcp_f32_e32 v135, v129
	v_pk_add_f32 v[130:131], v[130:131], 1.0 op_sel_hi:[1,0]
	v_mul_f32_e32 v129, 2.0, v135
	v_rcp_f32_e32 v135, v130
	v_pk_add_f32 v[132:133], v[132:133], 1.0 op_sel_hi:[1,0]
	v_mul_f32_e32 v130, 2.0, v135
	v_rcp_f32_e32 v135, v131
	v_add_f32_e32 v134, v2, v2
	v_mul_f32_e32 v131, 2.0, v135
	v_add_f32_e32 v135, v3, v3
	v_mul_f32_e32 v134, 0x3fb8aa3b, v134
	v_rcp_f32_e32 v152, v132
	v_mul_f32_e32 v135, 0x3fb8aa3b, v135
	v_exp_f32_e32 v134, v134
	v_exp_f32_e32 v135, v135
	v_mul_f32_e32 v132, 2.0, v152
	v_rcp_f32_e32 v152, v133
	v_pk_add_f32 v[134:135], v[134:135], 1.0 op_sel_hi:[1,0]
	v_mul_f32_e32 v133, 2.0, v152
	v_rcp_f32_e32 v152, v134
	v_sub_f32_e32 v131, 1.0, v131
	v_mul_f32_e32 v134, 2.0, v152
	v_rcp_f32_e32 v152, v135
	v_sub_f32_e32 v130, 1.0, v130
	v_mul_f32_e32 v135, 2.0, v152
	v_sub_f32_e32 v129, 1.0, v129
	v_sub_f32_e32 v128, 1.0, v128
	v_sub_f32_e32 v135, 1.0, v135
	v_sub_f32_e32 v134, 1.0, v134
	v_sub_f32_e32 v133, 1.0, v133
	v_sub_f32_e32 v132, 1.0, v132

; #define EPI_ROWS(...) _Pragma("unroll") for (int ai = 0; ai < 2; ++ai) _Pragma("unroll") for (int m = 0; m < 4; ++m) { const int row = u.pm * 256 + ai * 128 + wr * 64 + m * 16 + fr; __VA_ARGS__ }
; DI void st16_wt(void* p, u32x4 v) { asm volatile("global_store_dwordx4 %0, %1, off sc0 sc1\n\ts_nop 1" :: "v"(p), "v"(v) : "memory"); }
; DI u32x4 pack8(f32x4 a, f32x4 b) { u32x4 w; w.x = pk2(a[0], a[1]); w.y = pk2(a[2], a[3]); w.z = pk2(b[0], b[1]); w.w = pk2(b[2], b[3]); return w; }
; DI float siluf_(float x) { return x / (1.f + __expf(-x)); }
;     DI void operator()(const Acc& acc, const Unit& u, int wr, int wc, int fr, int fq) const {
;     ...
;         EPI_ROWS( f32x4 a, b;
;             _Pragma("unroll") for (int e = 0; e < 4; ++e) { a[e] = siluf_(acc[ai][0][m][0][e]) * acc[ai][1][m][0][e]; b[e] = siluf_(acc[ai][0][m][1][e]) * acc[ai][1][m][1][e]; }
;             st16_wt(H + (size_t)row * DFF + c0, pack8(a, b)); )
.LBB0_3535:
	v_mov_b32_e32 v150, v145
	v_mov_b32_e32 v151, v144
	s_lshl_b32 s13, s45, 7
	s_or_b32 s13, s13, s39
	v_lshl_add_u32 v152, v150, 3, s13
	v_mul_f32_e32 v150, 0xbfb8aa3b, v124
	v_exp_f32_e32 v154, v150
	v_mul_f32_e32 v150, 0xbfb8aa3b, v125
	v_exp_f32_e32 v155, v150
	s_lshl_b32 s13, s20, 8
	s_add_i32 s13, s13, s38
	v_add_u32_e32 v150, s13, v151
	v_pk_add_f32 v[154:155], v[154:155], 1.0 op_sel_hi:[1,0]
	v_mul_f32_e32 v156, 0xbfb8aa3b, v116
	v_rcp_f32_e32 v151, v155
	v_exp_f32_e32 v156, v156
	v_ashrrev_i32_e32 v153, 31, v152
	v_mul_f32_e32 v157, 0xbfb8aa3b, v117
	v_mul_f32_e32 v125, v125, v151
	v_rcp_f32_e32 v151, v154
	v_exp_f32_e32 v157, v157
	s_nop 0
	v_pk_add_f32 v[156:157], v[156:157], 1.0 op_sel_hi:[1,0]
	v_mul_f32_e32 v124, v124, v151
	v_pk_mul_f32 v[120:121], v[124:125], v[120:121]
	v_rcp_f32_e32 v124, v157
	s_nop 0
	v_mul_f32_e32 v117, v117, v124
	v_mul_f32_e32 v124, 0xbfb8aa3b, v126
	v_rcp_f32_e32 v151, v156
	v_mul_f32_e32 v125, 0xbfb8aa3b, v127
	v_exp_f32_e32 v124, v124
	v_exp_f32_e32 v125, v125
	v_mul_f32_e32 v116, v116, v151
	v_pk_mul_f32 v[154:155], v[116:117], v[112:113]
	v_pk_add_f32 v[124:125], v[124:125], 1.0 op_sel_hi:[1,0]
	s_nop 0
	v_rcp_f32_e32 v113, v125
	v_mul_f32_e32 v112, 0xbfb8aa3b, v118
	v_exp_f32_e32 v112, v112
	v_mul_f32_e32 v117, v127, v113
	v_rcp_f32_e32 v116, v124
	v_mul_f32_e32 v113, 0xbfb8aa3b, v119
	v_exp_f32_e32 v113, v113
	s_nop 0
	v_pk_add_f32 v[112:113], v[112:113], 1.0 op_sel_hi:[1,0]
	v_mul_f32_e32 v116, v126, v116
	v_pk_mul_f32 v[122:123], v[116:117], v[122:123]
	v_rcp_f32_e32 v116, v113
	s_nop 0
	v_mul_f32_e32 v113, v119, v116
	v_rcp_f32_e32 v116, v112
	s_nop 0
	v_mul_f32_e32 v112, v118, v116
	v_pk_mul_f32 v[124:125], v[112:113], v[114:115]
	v_mov_b64_e32 v[112:113], s[6:7]
	v_mad_i64_i32 v[116:117], s[22:23], v150, s44, v[112:113]
	v_lshlrev_b64 v[114:115], 1, v[152:153]
	v_lshl_add_u64 v[126:127], v[116:117], 0, v[114:115]
	v_mul_f32_e32 v117, 0xbfb8aa3b, v108
	v_cvt_pk_bf16_f32 v116, v120, v121
	v_exp_f32_e32 v120, v117
	v_mul_f32_e32 v117, 0xbfb8aa3b, v109
	v_exp_f32_e32 v121, v117
	v_cvt_pk_bf16_f32 v117, v122, v123
	v_cvt_pk_bf16_f32 v118, v154, v155
	v_cvt_pk_bf16_f32 v119, v124, v125
	v_pk_add_f32 v[120:121], v[120:121], 1.0 op_sel_hi:[1,0]
	global_store_dwordx4 v[126:127], v[116:119], off sc0 sc1
	s_nop 1
	v_rcp_f32_e32 v117, v121
	v_mul_f32_e32 v116, 0xbfb8aa3b, v100
	v_exp_f32_e32 v116, v116
	v_mul_f32_e32 v109, v109, v117
	v_rcp_f32_e32 v118, v120
	v_mul_f32_e32 v117, 0xbfb8aa3b, v101
	v_exp_f32_e32 v117, v117
	s_nop 0
	v_pk_add_f32 v[116:117], v[116:117], 1.0 op_sel_hi:[1,0]
	v_mul_f32_e32 v108, v108, v118
	v_pk_mul_f32 v[104:105], v[108:109], v[104:105]
	v_rcp_f32_e32 v108, v117
	s_nop 0
	v_mul_f32_e32 v101, v101, v108
	v_mul_f32_e32 v108, 0xbfb8aa3b, v110
	v_rcp_f32_e32 v117, v116
	v_mul_f32_e32 v109, 0xbfb8aa3b, v111
	v_exp_f32_e32 v108, v108
	v_exp_f32_e32 v109, v109
	v_mul_f32_e32 v100, v100, v117
	v_pk_mul_f32 v[100:101], v[100:101], v[96:97]
	v_pk_add_f32 v[108:109], v[108:109], 1.0 op_sel_hi:[1,0]
	s_nop 0
	v_rcp_f32_e32 v97, v109
	v_mul_f32_e32 v96, 0xbfb8aa3b, v102
	v_exp_f32_e32 v96, v96
	v_mul_f32_e32 v109, v111, v97
	v_rcp_f32_e32 v111, v108
	v_mul_f32_e32 v97, 0xbfb8aa3b, v103
	v_exp_f32_e32 v97, v97
	s_nop 0
	v_pk_add_f32 v[96:97], v[96:97], 1.0 op_sel_hi:[1,0]
	v_mul_f32_e32 v108, v110, v111
	v_pk_mul_f32 v[106:107], v[108:109], v[106:107]
	v_rcp_f32_e32 v108, v97
	s_nop 0
	v_mul_f32_e32 v97, v103, v108
	v_rcp_f32_e32 v103, v96
	s_nop 0
	v_mul_f32_e32 v96, v102, v103
	v_pk_mul_f32 v[102:103], v[96:97], v[98:99]
	v_add_u32_e32 v96, 16, v150
	v_mad_i64_i32 v[96:97], s[22:23], v96, s44, v[112:113]
	v_lshl_add_u64 v[108:109], v[96:97], 0, v[114:115]
	v_mul_f32_e32 v97, 0xbfb8aa3b, v92
	v_cvt_pk_bf16_f32 v96, v104, v105
	v_exp_f32_e32 v104, v97
	v_mul_f32_e32 v97, 0xbfb8aa3b, v93
	v_exp_f32_e32 v105, v97
	v_cvt_pk_bf16_f32 v98, v100, v101
	v_cvt_pk_bf16_f32 v99, v102, v103
	v_cvt_pk_bf16_f32 v97, v106, v107
	v_pk_add_f32 v[100:101], v[104:105], 1.0 op_sel_hi:[1,0]
	global_store_dwordx4 v[108:109], v[96:99], off sc0 sc1
	s_nop 1
	v_rcp_f32_e32 v97, v101
	v_mul_f32_e32 v96, 0xbfb8aa3b, v84
	v_exp_f32_e32 v96, v96
	v_mul_f32_e32 v93, v93, v97
	v_rcp_f32_e32 v98, v100
	v_mul_f32_e32 v97, 0xbfb8aa3b, v85
	v_exp_f32_e32 v97, v97
	s_nop 0
	v_pk_add_f32 v[96:97], v[96:97], 1.0 op_sel_hi:[1,0]
	v_mul_f32_e32 v92, v92, v98
	v_pk_mul_f32 v[88:89], v[92:93], v[88:89]
	v_rcp_f32_e32 v92, v97
	s_nop 0
	v_mul_f32_e32 v85, v85, v92
	v_mul_f32_e32 v92, 0xbfb8aa3b, v94
	v_rcp_f32_e32 v97, v96
	v_mul_f32_e32 v93, 0xbfb8aa3b, v95
	v_exp_f32_e32 v92, v92
	v_exp_f32_e32 v93, v93
	v_mul_f32_e32 v84, v84, v97
	v_pk_mul_f32 v[84:85], v[84:85], v[80:81]
	v_pk_add_f32 v[92:93], v[92:93], 1.0 op_sel_hi:[1,0]
	s_nop 0
	v_rcp_f32_e32 v81, v93
	v_mul_f32_e32 v80, 0xbfb8aa3b, v86
	v_exp_f32_e32 v80, v80
	v_mul_f32_e32 v93, v95, v81
	v_rcp_f32_e32 v95, v92
	v_mul_f32_e32 v81, 0xbfb8aa3b, v87
	v_exp_f32_e32 v81, v81
	s_nop 0
	v_pk_add_f32 v[80:81], v[80:81], 1.0 op_sel_hi:[1,0]
	v_mul_f32_e32 v92, v94, v95
	v_pk_mul_f32 v[90:91], v[92:93], v[90:91]
	v_rcp_f32_e32 v92, v81
	s_nop 0
	v_mul_f32_e32 v81, v87, v92
	v_rcp_f32_e32 v87, v80
	s_nop 0
	v_mul_f32_e32 v80, v86, v87
	v_pk_mul_f32 v[86:87], v[80:81], v[82:83]
	v_add_u32_e32 v80, 32, v150
	v_mad_i64_i32 v[80:81], s[22:23], v80, s44, v[112:113]
	v_lshl_add_u64 v[92:93], v[80:81], 0, v[114:115]
	v_mul_f32_e32 v81, 0xbfb8aa3b, v76
	v_cvt_pk_bf16_f32 v80, v88, v89
	v_exp_f32_e32 v88, v81
	v_mul_f32_e32 v81, 0xbfb8aa3b, v77
	v_exp_f32_e32 v89, v81
	v_cvt_pk_bf16_f32 v82, v84, v85
	v_cvt_pk_bf16_f32 v83, v86, v87
	v_cvt_pk_bf16_f32 v81, v90, v91
; #define EPI_ROWS(...) _Pragma("unroll") for (int ai = 0; ai < 2; ++ai) _Pragma("unroll") for (int m = 0; m < 4; ++m) { const int row = u.pm * 256 + ai * 128 + wr * 64 + m * 16 + fr; __VA_ARGS__ }
; DI void st16_wt(void* p, u32x4 v) { asm volatile("global_store_dwordx4 %0, %1, off sc0 sc1\n\ts_nop 1" :: "v"(p), "v"(v) : "memory"); }
; DI u32x4 pack8(f32x4 a, f32x4 b) { u32x4 w; w.x = pk2(a[0], a[1]); w.y = pk2(a[2], a[3]); w.z = pk2(b[0], b[1]); w.w = pk2(b[2], b[3]); return w; }
; DI float siluf_(float x) { return x / (1.f + __expf(-x)); }
;     DI void operator()(const Acc& acc, const Unit& u, int wr, int wc, int fr, int fq) const {
;     ...
;         EPI_ROWS( f32x4 a, b;
;             _Pragma("unroll") for (int e = 0; e < 4; ++e) { a[e] = siluf_(acc[ai][0][m][0][e]) * acc[ai][1][m][0][e]; b[e] = siluf_(acc[ai][0][m][1][e]) * acc[ai][1][m][1][e]; }
;             st16_wt(H + (size_t)row * DFF + c0, pack8(a, b)); )
	v_pk_add_f32 v[84:85], v[88:89], 1.0 op_sel_hi:[1,0]
	global_store_dwordx4 v[92:93], v[80:83], off sc0 sc1
	s_nop 1
	v_rcp_f32_e32 v81, v85
	v_mul_f32_e32 v80, 0xbfb8aa3b, v68
	v_exp_f32_e32 v80, v80
	v_mul_f32_e32 v77, v77, v81
	v_rcp_f32_e32 v82, v84
	v_mul_f32_e32 v81, 0xbfb8aa3b, v69
	v_exp_f32_e32 v81, v81
	s_nop 0
	v_pk_add_f32 v[80:81], v[80:81], 1.0 op_sel_hi:[1,0]
	v_mul_f32_e32 v76, v76, v82
	v_pk_mul_f32 v[72:73], v[76:77], v[72:73]
	v_rcp_f32_e32 v76, v81
	s_nop 0
	v_mul_f32_e32 v69, v69, v76
	v_mul_f32_e32 v76, 0xbfb8aa3b, v78
	v_rcp_f32_e32 v81, v80
	v_mul_f32_e32 v77, 0xbfb8aa3b, v79
	v_exp_f32_e32 v76, v76
	v_exp_f32_e32 v77, v77
	v_mul_f32_e32 v68, v68, v81
	v_pk_mul_f32 v[68:69], v[68:69], v[64:65]
	v_pk_add_f32 v[76:77], v[76:77], 1.0 op_sel_hi:[1,0]
	s_nop 0
	v_rcp_f32_e32 v65, v77
	v_mul_f32_e32 v64, 0xbfb8aa3b, v70
	v_exp_f32_e32 v64, v64
	v_mul_f32_e32 v77, v79, v65
	v_rcp_f32_e32 v79, v76
	v_mul_f32_e32 v65, 0xbfb8aa3b, v71
	v_exp_f32_e32 v65, v65
	s_nop 0
	v_pk_add_f32 v[64:65], v[64:65], 1.0 op_sel_hi:[1,0]
	v_mul_f32_e32 v76, v78, v79
	v_pk_mul_f32 v[74:75], v[76:77], v[74:75]
	v_rcp_f32_e32 v76, v65
	s_nop 0
	v_mul_f32_e32 v65, v71, v76
	v_rcp_f32_e32 v71, v64
	s_nop 0
	v_mul_f32_e32 v64, v70, v71
	v_pk_mul_f32 v[70:71], v[64:65], v[66:67]
	v_add_u32_e32 v64, 48, v150
	v_mad_i64_i32 v[64:65], s[22:23], v64, s44, v[112:113]
	v_mul_f32_e32 v66, 0xbfb8aa3b, v60
	v_lshl_add_u64 v[76:77], v[64:65], 0, v[114:115]
	v_cvt_pk_bf16_f32 v64, v72, v73
	v_exp_f32_e32 v72, v66
	v_mul_f32_e32 v66, 0xbfb8aa3b, v61
	v_exp_f32_e32 v73, v66
	v_cvt_pk_bf16_f32 v65, v74, v75
	v_cvt_pk_bf16_f32 v66, v68, v69
	v_cvt_pk_bf16_f32 v67, v70, v71
	global_store_dwordx4 v[76:77], v[64:67], off sc0 sc1
	s_nop 1
	v_pk_add_f32 v[64:65], v[72:73], 1.0 op_sel_hi:[1,0]
	s_nop 0
	v_rcp_f32_e32 v67, v65
	v_mul_f32_e32 v66, 0xbfb8aa3b, v52
	v_exp_f32_e32 v66, v66
	v_add_u32_e32 v69, 0x80, v150
	v_mul_f32_e32 v61, v61, v67
	v_rcp_f32_e32 v65, v64
	v_mul_f32_e32 v67, 0xbfb8aa3b, v53
	v_exp_f32_e32 v67, v67
	s_nop 0
	v_pk_add_f32 v[66:67], v[66:67], 1.0 op_sel_hi:[1,0]
	v_mul_f32_e32 v60, v60, v65
	v_pk_mul_f32 v[56:57], v[60:61], v[56:57]
	v_rcp_f32_e32 v60, v67
	s_nop 0
	v_mul_f32_e32 v53, v53, v60
	v_mul_f32_e32 v60, 0xbfb8aa3b, v62
	v_rcp_f32_e32 v64, v66
	v_mul_f32_e32 v61, 0xbfb8aa3b, v63
	v_exp_f32_e32 v60, v60
	v_exp_f32_e32 v61, v61
	v_mul_f32_e32 v52, v52, v64
	v_pk_mul_f32 v[52:53], v[52:53], v[48:49]
	v_pk_add_f32 v[60:61], v[60:61], 1.0 op_sel_hi:[1,0]
	s_nop 0
	v_rcp_f32_e32 v49, v61
	v_mul_f32_e32 v48, 0xbfb8aa3b, v54
	v_exp_f32_e32 v48, v48
	v_mul_f32_e32 v61, v63, v49
	v_rcp_f32_e32 v63, v60
	v_mul_f32_e32 v49, 0xbfb8aa3b, v55
	v_exp_f32_e32 v49, v49
	s_nop 0
	v_pk_add_f32 v[48:49], v[48:49], 1.0 op_sel_hi:[1,0]
	v_mul_f32_e32 v60, v62, v63
	v_pk_mul_f32 v[58:59], v[60:61], v[58:59]
	v_rcp_f32_e32 v60, v49
	s_nop 0
	v_mul_f32_e32 v49, v55, v60
	v_rcp_f32_e32 v55, v48
	s_nop 0
	v_mul_f32_e32 v48, v54, v55
	v_pk_mul_f32 v[54:55], v[48:49], v[50:51]
	v_mad_i64_i32 v[48:49], s[22:23], v69, s44, v[112:113]
	v_lshl_add_u64 v[60:61], v[48:49], 0, v[114:115]
	v_mul_f32_e32 v49, 0xbfb8aa3b, v44
	v_cvt_pk_bf16_f32 v48, v56, v57
	v_exp_f32_e32 v56, v49
	v_mul_f32_e32 v49, 0xbfb8aa3b, v45
	v_exp_f32_e32 v57, v49
	v_cvt_pk_bf16_f32 v50, v52, v53
	v_cvt_pk_bf16_f32 v51, v54, v55
	v_cvt_pk_bf16_f32 v49, v58, v59
	v_pk_add_f32 v[52:53], v[56:57], 1.0 op_sel_hi:[1,0]
	global_store_dwordx4 v[60:61], v[48:51], off sc0 sc1
	s_nop 1
	v_rcp_f32_e32 v49, v53
	v_mul_f32_e32 v48, 0xbfb8aa3b, v36
	v_exp_f32_e32 v48, v48
	v_mul_f32_e32 v45, v45, v49
	v_rcp_f32_e32 v50, v52
	v_mul_f32_e32 v49, 0xbfb8aa3b, v37
	v_exp_f32_e32 v49, v49
	s_nop 0
	v_pk_add_f32 v[48:49], v[48:49], 1.0 op_sel_hi:[1,0]
	v_mul_f32_e32 v44, v44, v50
	v_pk_mul_f32 v[40:41], v[44:45], v[40:41]
	v_rcp_f32_e32 v44, v49
	s_nop 0
	v_mul_f32_e32 v37, v37, v44
	v_mul_f32_e32 v44, 0xbfb8aa3b, v46
	v_rcp_f32_e32 v49, v48
	v_mul_f32_e32 v45, 0xbfb8aa3b, v47
	v_exp_f32_e32 v44, v44
	v_exp_f32_e32 v45, v45
	v_mul_f32_e32 v36, v36, v49
	v_pk_mul_f32 v[36:37], v[36:37], v[32:33]
	v_pk_add_f32 v[44:45], v[44:45], 1.0 op_sel_hi:[1,0]
	s_nop 0
	v_rcp_f32_e32 v33, v45
	v_mul_f32_e32 v32, 0xbfb8aa3b, v38
; #define EPI_ROWS(...) _Pragma("unroll") for (int ai = 0; ai < 2; ++ai) _Pragma("unroll") for (int m = 0; m < 4; ++m) { const int row = u.pm * 256 + ai * 128 + wr * 64 + m * 16 + fr; __VA_ARGS__ }
; DI void st16_wt(void* p, u32x4 v) { asm volatile("global_store_dwordx4 %0, %1, off sc0 sc1\n\ts_nop 1" :: "v"(p), "v"(v) : "memory"); }
; DI u32x4 pack8(f32x4 a, f32x4 b) { u32x4 w; w.x = pk2(a[0], a[1]); w.y = pk2(a[2], a[3]); w.z = pk2(b[0], b[1]); w.w = pk2(b[2], b[3]); return w; }
; DI float siluf_(float x) { return x / (1.f + __expf(-x)); }
;     DI void operator()(const Acc& acc, const Unit& u, int wr, int wc, int fr, int fq) const {
;     ...
;         EPI_ROWS( f32x4 a, b;
;             _Pragma("unroll") for (int e = 0; e < 4; ++e) { a[e] = siluf_(acc[ai][0][m][0][e]) * acc[ai][1][m][0][e]; b[e] = siluf_(acc[ai][0][m][1][e]) * acc[ai][1][m][1][e]; }
;             st16_wt(H + (size_t)row * DFF + c0, pack8(a, b)); )
	v_exp_f32_e32 v32, v32
	v_mul_f32_e32 v45, v47, v33
	v_rcp_f32_e32 v47, v44
	v_mul_f32_e32 v33, 0xbfb8aa3b, v39
	v_exp_f32_e32 v33, v33
	s_nop 0
	v_pk_add_f32 v[32:33], v[32:33], 1.0 op_sel_hi:[1,0]
	v_mul_f32_e32 v44, v46, v47
	v_pk_mul_f32 v[42:43], v[44:45], v[42:43]
	v_rcp_f32_e32 v44, v33
	s_nop 0
	v_mul_f32_e32 v33, v39, v44
	v_rcp_f32_e32 v39, v32
	s_nop 0
	v_mul_f32_e32 v32, v38, v39
	v_pk_mul_f32 v[38:39], v[32:33], v[34:35]
	v_add_u32_e32 v32, 0x90, v150
	v_mad_i64_i32 v[32:33], s[22:23], v32, s44, v[112:113]
	v_lshl_add_u64 v[44:45], v[32:33], 0, v[114:115]
	v_mul_f32_e32 v33, 0xbfb8aa3b, v28
	v_cvt_pk_bf16_f32 v32, v40, v41
	v_exp_f32_e32 v40, v33
	v_mul_f32_e32 v33, 0xbfb8aa3b, v29
	v_exp_f32_e32 v41, v33
	v_cvt_pk_bf16_f32 v34, v36, v37
	v_cvt_pk_bf16_f32 v35, v38, v39
	v_cvt_pk_bf16_f32 v33, v42, v43
	v_pk_add_f32 v[36:37], v[40:41], 1.0 op_sel_hi:[1,0]
	global_store_dwordx4 v[44:45], v[32:35], off sc0 sc1
	s_nop 1
	v_rcp_f32_e32 v33, v37
	v_mul_f32_e32 v32, 0xbfb8aa3b, v20
	v_exp_f32_e32 v32, v32
	v_mul_f32_e32 v29, v29, v33
	v_rcp_f32_e32 v34, v36
	v_mul_f32_e32 v33, 0xbfb8aa3b, v21
	v_exp_f32_e32 v33, v33
	s_nop 0
	v_pk_add_f32 v[32:33], v[32:33], 1.0 op_sel_hi:[1,0]
	v_mul_f32_e32 v28, v28, v34
	v_pk_mul_f32 v[24:25], v[28:29], v[24:25]
	v_rcp_f32_e32 v28, v33
	s_nop 0
	v_mul_f32_e32 v21, v21, v28
	v_mul_f32_e32 v28, 0xbfb8aa3b, v30
	v_rcp_f32_e32 v33, v32
	v_mul_f32_e32 v29, 0xbfb8aa3b, v31
	v_exp_f32_e32 v28, v28
	v_exp_f32_e32 v29, v29
	v_mul_f32_e32 v20, v20, v33
	v_pk_mul_f32 v[20:21], v[20:21], v[16:17]
	v_pk_add_f32 v[28:29], v[28:29], 1.0 op_sel_hi:[1,0]
	s_nop 0
	v_rcp_f32_e32 v17, v29
	v_mul_f32_e32 v16, 0xbfb8aa3b, v22
	v_exp_f32_e32 v16, v16
	v_mul_f32_e32 v29, v31, v17
	v_rcp_f32_e32 v31, v28
	v_mul_f32_e32 v17, 0xbfb8aa3b, v23
	v_exp_f32_e32 v17, v17
	s_nop 0
	v_pk_add_f32 v[16:17], v[16:17], 1.0 op_sel_hi:[1,0]
	v_mul_f32_e32 v28, v30, v31
	v_pk_mul_f32 v[26:27], v[28:29], v[26:27]
	v_rcp_f32_e32 v28, v17
	s_nop 0
	v_mul_f32_e32 v17, v23, v28
	v_rcp_f32_e32 v23, v16
	s_nop 0
	v_mul_f32_e32 v16, v22, v23
	v_pk_mul_f32 v[22:23], v[16:17], v[18:19]
	v_add_u32_e32 v16, 0xa0, v150
	v_mad_i64_i32 v[16:17], s[22:23], v16, s44, v[112:113]
	v_lshl_add_u64 v[28:29], v[16:17], 0, v[114:115]
	v_mul_f32_e32 v17, 0xbfb8aa3b, v12
	v_cvt_pk_bf16_f32 v16, v24, v25
	v_exp_f32_e32 v24, v17
	v_mul_f32_e32 v17, 0xbfb8aa3b, v13
	v_exp_f32_e32 v25, v17
	v_cvt_pk_bf16_f32 v18, v20, v21
	v_cvt_pk_bf16_f32 v19, v22, v23
	v_cvt_pk_bf16_f32 v17, v26, v27
	v_pk_add_f32 v[20:21], v[24:25], 1.0 op_sel_hi:[1,0]
	global_store_dwordx4 v[28:29], v[16:19], off sc0 sc1
	s_nop 1
	v_rcp_f32_e32 v17, v21
	v_mul_f32_e32 v16, 0xbfb8aa3b, v4
	v_exp_f32_e32 v16, v16
	v_mul_f32_e32 v13, v13, v17
	v_rcp_f32_e32 v18, v20
	v_mul_f32_e32 v17, 0xbfb8aa3b, v5
	v_exp_f32_e32 v17, v17
	s_nop 0
	v_pk_add_f32 v[16:17], v[16:17], 1.0 op_sel_hi:[1,0]
	v_mul_f32_e32 v12, v12, v18
	v_pk_mul_f32 v[8:9], v[12:13], v[8:9]
	v_rcp_f32_e32 v12, v17
	s_nop 0
	v_mul_f32_e32 v5, v5, v12
	v_mul_f32_e32 v12, 0xbfb8aa3b, v14
	v_rcp_f32_e32 v17, v16
	v_mul_f32_e32 v13, 0xbfb8aa3b, v15
	v_exp_f32_e32 v12, v12
	v_exp_f32_e32 v13, v13
	v_mul_f32_e32 v4, v4, v17
	v_pk_mul_f32 v[4:5], v[4:5], v[0:1]
	v_pk_add_f32 v[12:13], v[12:13], 1.0 op_sel_hi:[1,0]
	s_nop 0
	v_rcp_f32_e32 v1, v13
	v_mul_f32_e32 v0, 0xbfb8aa3b, v6
	v_exp_f32_e32 v0, v0
	v_mul_f32_e32 v13, v15, v1
	v_rcp_f32_e32 v15, v12
	v_mul_f32_e32 v1, 0xbfb8aa3b, v7
	v_exp_f32_e32 v1, v1
	s_nop 0
	v_pk_add_f32 v[0:1], v[0:1], 1.0 op_sel_hi:[1,0]
	v_mul_f32_e32 v12, v14, v15
	v_pk_mul_f32 v[10:11], v[12:13], v[10:11]
	v_rcp_f32_e32 v12, v1
	s_nop 0
	v_mul_f32_e32 v1, v7, v12
	v_rcp_f32_e32 v7, v0
	s_nop 0
	v_mul_f32_e32 v0, v6, v7
	v_pk_mul_f32 v[6:7], v[0:1], v[2:3]
	v_add_u32_e32 v0, 0xb0, v150
	v_mad_i64_i32 v[0:1], s[22:23], v0, s44, v[112:113]
	v_lshl_add_u64 v[12:13], v[0:1], 0, v[114:115]
	v_cvt_pk_bf16_f32 v0, v8, v9
	v_cvt_pk_bf16_f32 v1, v10, v11
	v_cvt_pk_bf16_f32 v2, v4, v5
	v_cvt_pk_bf16_f32 v3, v6, v7
	global_store_dwordx4 v[12:13], v[0:3], off sc0 sc1
	s_nop 1
	s_andn2_b64 vcc, exec, s[0:1]
	s_mov_b64 s[0:1], -1
	s_cbranch_vccnz .LBB0_3528
	s_andn2_b64 vcc, exec, s[4:5]
	s_cbranch_vccnz .LBB0_3527
	s_barrier
	s_branch .LBB0_3527
